# hand-off tightened (setprio outside barriers, duplicate lgkmcnt removed) + first LDS-DMA of 8-read load segments issued before the ds_reads
# speedup vs baseline: 1.0045x; 1.0041x over previous
; #define PG8_STAGE(bufoff, gbase, voff) do { _Pragma("unroll") for (int _i = 0; _i < 2; ++_i) \
;         __builtin_amdgcn_global_load_lds((const unsigned*)((const char*)(gbase) + (voff)[_i]), (PG8_LAS unsigned*)(lds + (bufoff) + ldsw + _i * 8192), 16, 0, 0); } while (0)
; #define PG8_LDA(dst, b, h) do { _Pragma("unroll") for (int m = 0; m < 4; ++m) _Pragma("unroll") for (int k = 0; k < 2; ++k) dst[m][k] = *(const PG8_LAS bf16x8*)(lds + PG8_SA(b, h) + aoff + m * 2048 + k * 1024); } while (0)
; #define PG8_LDB(dst, b, h) do { _Pragma("unroll") for (int n = 0; n < 2; ++n) _Pragma("unroll") for (int k = 0; k < 2; ++k) dst[n][k] = *(const PG8_LAS bf16x8*)(lds + PG8_SB(b, h) + boff + n * 2048 + k * 1024); } while (0)
; #define PG8_MMA(ai, bj, At, Bt) do { __builtin_amdgcn_s_setprio(1); _Pragma("unroll") for (int m = 0; m < 4; ++m) _Pragma("unroll") for (int n = 0; n < 2; ++n) _Pragma("unroll") for (int k = 0; k < 2; ++k) \
;         acc[ai][bj][m][n] = __builtin_amdgcn_mfma_f32_16x16x32_bf16(Bt[n][k], At[m][k], acc[ai][bj][m][n], 0, 0, 0); __builtin_amdgcn_s_setprio(0); } while (0)
; #define PG8_WAIT_V(n) asm volatile("s_waitcnt vmcnt(" #n ")" ::: "memory")
; #define PG8_WAIT_L(n) asm volatile("s_waitcnt lgkmcnt(" #n ")" ::: "memory")
; #define PG8_BAR __builtin_amdgcn_s_barrier()
; #define PG8_SCHED __builtin_amdgcn_sched_barrier(0)
; template <class Epi, class Sched, bool ALIGN_EPI = false, bool SP2 = false>
; __device__ __forceinline__ void gemm_phase(PG8_LAS unsigned char* lds, const Gemm g, const Sched& S, const Epi& E) {
;     ...
;             PG8_LDB(B0, 0, 0); PG8_LDB(B1, 0, 1); PG8_SCHED; PG8_LDA(At, 0, 0); PG8_STAGE(PG8_SA(1, 1), a1 + hstep, voffA);
;             PG8_WAIT_V(8); PG8_WAIT_L(0); PG8_BAR; PG8_MMA(0, 0, At, B0); PG8_MMA(0, 1, At, B1); PG8_BAR; PG8_SCHED;
;             PG8_LDA(At, 0, 1); PG8_STAGE(PG8_SB(0, 0), b2, voffB); PG8_STAGE(PG8_SB(0, 1), b2 + hstep, voffB); PG8_STAGE(PG8_SA(0, 0), a2, voffA);
;             PG8_WAIT_V(8); PG8_WAIT_L(0); PG8_BAR; PG8_MMA(1, 0, At, B0); PG8_MMA(1, 1, At, B1); PG8_BAR; PG8_SCHED;
;             PG8_LDB(B0, 1, 0); PG8_LDB(B1, 1, 1); PG8_SCHED; PG8_LDA(At, 1, 0); PG8_STAGE(PG8_SA(0, 1), a2 + hstep, voffA);
;             PG8_WAIT_V(8); PG8_WAIT_L(0); PG8_BAR; PG8_MMA(0, 0, At, B0); PG8_MMA(0, 1, At, B1); PG8_BAR; PG8_SCHED;
.LBB0_129:
	s_or_b32 s29, s1, 1
	s_mul_i32 s31, s45, s29
	s_mul_hi_u32 s58, s44, s29
	s_add_i32 s58, s58, s31
	s_mul_i32 s29, s44, s29
	s_add_u32 s29, s42, s29
	s_addc_u32 s31, s43, s58
	s_add_u32 s58, s56, s54
	s_addc_u32 s59, s57, s55
	s_add_i32 s78, 0, 0x10000
	s_add_i32 s79, 0, 0x14000
	v_add_u32_e32 v140, s78, v189
	v_add_u32_e32 v172, s79, v189
	ds_read_b128 v[128:131], v140
	ds_read_b128 v[132:135], v140 offset:1024
	ds_read_b128 v[136:139], v140 offset:2048
	ds_read_b128 v[140:143], v140 offset:3072
	ds_read_b128 v[160:163], v172
	ds_read_b128 v[164:167], v172 offset:1024
	ds_read_b128 v[168:171], v172 offset:2048
	ds_read_b128 v[182:185], v172 offset:3072
	s_add_u32 vcc_lo, s29, 0x80000
	s_addc_u32 vcc_hi, s31, 0
	v_lshl_add_u64 v[178:179], vcc, 0, v[144:145]
	s_add_i32 m0, s88, 0xc000
	ds_read_b128 v[192:195], v190
	ds_read_b128 v[196:199], v190 offset:1024
	ds_read_b128 v[200:203], v190 offset:2048
	ds_read_b128 v[212:215], v190 offset:3072
	ds_read_b128 v[216:219], v190 offset:4096
	ds_read_b128 v[220:223], v190 offset:5120
	ds_read_b128 v[224:227], v190 offset:6144
	ds_read_b128 v[228:231], v190 offset:7168
	global_load_lds_dwordx4 v[178:179], off
	v_lshl_add_u64 v[178:179], vcc, 0, v[148:149]
	s_add_i32 m0, s88, 0xe000
	s_nop 0
	global_load_lds_dwordx4 v[178:179], off
	s_waitcnt vmcnt(8)
	s_waitcnt lgkmcnt(0)
	s_setprio 1
	s_barrier
	v_mfma_f32_16x16x32_bf16 v[124:127], v[128:131], v[192:195], v[124:127]
	v_mfma_f32_16x16x32_bf16 v[120:123], v[136:139], v[192:195], v[120:123]
	v_mfma_f32_16x16x32_bf16 v[108:111], v[128:131], v[200:203], v[108:111]
	v_mfma_f32_16x16x32_bf16 v[104:107], v[136:139], v[200:203], v[104:107]
	v_mfma_f32_16x16x32_bf16 v[92:95], v[128:131], v[216:219], v[92:95]
	v_mfma_f32_16x16x32_bf16 v[88:91], v[136:139], v[216:219], v[88:91]
	v_mfma_f32_16x16x32_bf16 v[76:79], v[128:131], v[224:227], v[76:79]
	v_mfma_f32_16x16x32_bf16 v[72:75], v[136:139], v[224:227], v[72:75]
	v_mfma_f32_16x16x32_bf16 v[124:127], v[132:135], v[196:199], v[124:127]
	v_mfma_f32_16x16x32_bf16 v[120:123], v[140:143], v[196:199], v[120:123]
	v_mfma_f32_16x16x32_bf16 v[108:111], v[132:135], v[212:215], v[108:111]
	v_mfma_f32_16x16x32_bf16 v[104:107], v[140:143], v[212:215], v[104:107]
	v_mfma_f32_16x16x32_bf16 v[92:95], v[132:135], v[220:223], v[92:95]
	v_mfma_f32_16x16x32_bf16 v[88:91], v[140:143], v[220:223], v[88:91]
	v_mfma_f32_16x16x32_bf16 v[76:79], v[132:135], v[228:231], v[76:79]
	v_mfma_f32_16x16x32_bf16 v[72:75], v[140:143], v[228:231], v[72:75]
	s_setprio 0
	s_setprio 1
	v_mfma_f32_16x16x32_bf16 v[116:119], v[160:163], v[192:195], v[116:119]
	v_mfma_f32_16x16x32_bf16 v[112:115], v[168:171], v[192:195], v[112:115]
	v_mfma_f32_16x16x32_bf16 v[100:103], v[160:163], v[200:203], v[100:103]
	v_mfma_f32_16x16x32_bf16 v[96:99], v[168:171], v[200:203], v[96:99]
	v_mfma_f32_16x16x32_bf16 v[84:87], v[160:163], v[216:219], v[84:87]
	v_mfma_f32_16x16x32_bf16 v[80:83], v[168:171], v[216:219], v[80:83]
	v_mfma_f32_16x16x32_bf16 v[68:71], v[160:163], v[224:227], v[68:71]
	v_mfma_f32_16x16x32_bf16 v[64:67], v[168:171], v[224:227], v[64:67]
	v_mfma_f32_16x16x32_bf16 v[116:119], v[164:167], v[196:199], v[116:119]
	v_mfma_f32_16x16x32_bf16 v[112:115], v[182:185], v[196:199], v[112:115]
	v_mfma_f32_16x16x32_bf16 v[100:103], v[164:167], v[212:215], v[100:103]
	v_mfma_f32_16x16x32_bf16 v[96:99], v[182:185], v[212:215], v[96:99]
	v_mfma_f32_16x16x32_bf16 v[84:87], v[164:167], v[220:223], v[84:87]
	v_mfma_f32_16x16x32_bf16 v[80:83], v[182:185], v[220:223], v[80:83]
	v_mfma_f32_16x16x32_bf16 v[68:71], v[164:167], v[228:231], v[68:71]
	v_mfma_f32_16x16x32_bf16 v[64:67], v[182:185], v[228:231], v[64:67]
	s_barrier
	s_setprio 0
	s_add_i32 s29, s78, s72
	v_lshl_add_u64 v[178:179], s[52:53], 0, v[146:147]
	s_mov_b32 m0, s29
	s_nop 0
	global_load_lds_dwordx4 v[178:179], off
	ds_read_b128 v[192:195], v190 offset:16384
	ds_read_b128 v[196:199], v190 offset:17408
	ds_read_b128 v[200:203], v190 offset:18432
	ds_read_b128 v[212:215], v190 offset:19456
	s_add_i32 m0, s29, 0x2000
	s_add_u32 vcc_lo, s52, 0x80000
	v_lshl_add_u64 v[178:179], s[52:53], 0, v[150:151]
	s_addc_u32 vcc_hi, s53, 0
	s_add_i32 s29, s79, s72
	global_load_lds_dwordx4 v[178:179], off
	ds_read_b128 v[216:219], v190 offset:20480
	ds_read_b128 v[220:223], v190 offset:21504
	ds_read_b128 v[224:227], v190 offset:22528
	ds_read_b128 v[228:231], v190 offset:23552
	v_lshl_add_u64 v[178:179], vcc, 0, v[146:147]
	s_mov_b32 m0, s29
	s_nop 0
	global_load_lds_dwordx4 v[178:179], off
	v_lshl_add_u64 v[178:179], vcc, 0, v[150:151]
	s_add_i32 m0, s29, 0x2000
	s_nop 0
	global_load_lds_dwordx4 v[178:179], off
	v_lshl_add_u64 v[178:179], s[56:57], 0, v[144:145]
	s_mov_b32 m0, s88
	s_nop 0
	global_load_lds_dwordx4 v[178:179], off
	v_lshl_add_u64 v[178:179], s[56:57], 0, v[148:149]
	s_mov_b32 m0, s89
	s_nop 0
	global_load_lds_dwordx4 v[178:179], off
	s_waitcnt vmcnt(8)
	s_waitcnt lgkmcnt(0)
	s_setprio 1
	s_barrier
; #define PG8_STAGE(bufoff, gbase, voff) do { _Pragma("unroll") for (int _i = 0; _i < 2; ++_i) \
;         __builtin_amdgcn_global_load_lds((const unsigned*)((const char*)(gbase) + (voff)[_i]), (PG8_LAS unsigned*)(lds + (bufoff) + ldsw + _i * 8192), 16, 0, 0); } while (0)
; #define PG8_LDA(dst, b, h) do { _Pragma("unroll") for (int m = 0; m < 4; ++m) _Pragma("unroll") for (int k = 0; k < 2; ++k) dst[m][k] = *(const PG8_LAS bf16x8*)(lds + PG8_SA(b, h) + aoff + m * 2048 + k * 1024); } while (0)
; #define PG8_LDB(dst, b, h) do { _Pragma("unroll") for (int n = 0; n < 2; ++n) _Pragma("unroll") for (int k = 0; k < 2; ++k) dst[n][k] = *(const PG8_LAS bf16x8*)(lds + PG8_SB(b, h) + boff + n * 2048 + k * 1024); } while (0)
; #define PG8_MMA(ai, bj, At, Bt) do { __builtin_amdgcn_s_setprio(1); _Pragma("unroll") for (int m = 0; m < 4; ++m) _Pragma("unroll") for (int n = 0; n < 2; ++n) _Pragma("unroll") for (int k = 0; k < 2; ++k) \
;         acc[ai][bj][m][n] = __builtin_amdgcn_mfma_f32_16x16x32_bf16(Bt[n][k], At[m][k], acc[ai][bj][m][n], 0, 0, 0); __builtin_amdgcn_s_setprio(0); } while (0)
; #define PG8_WAIT_V(n) asm volatile("s_waitcnt vmcnt(" #n ")" ::: "memory")
; #define PG8_WAIT_L(n) asm volatile("s_waitcnt lgkmcnt(" #n ")" ::: "memory")
; #define PG8_BAR __builtin_amdgcn_s_barrier()
; #define PG8_SCHED __builtin_amdgcn_sched_barrier(0)
; template <class Epi, class Sched, bool ALIGN_EPI = false, bool SP2 = false>
; __device__ __forceinline__ void gemm_phase(PG8_LAS unsigned char* lds, const Gemm g, const Sched& S, const Epi& E) {
;     ...
;             PG8_WAIT_V(8); PG8_WAIT_L(0); PG8_BAR; PG8_MMA(1, 0, At, B0); PG8_MMA(1, 1, At, B1); PG8_BAR; PG8_SCHED;
;             PG8_LDB(B0, 1, 0); PG8_LDB(B1, 1, 1); PG8_SCHED; PG8_LDA(At, 1, 0); PG8_STAGE(PG8_SA(0, 1), a2 + hstep, voffA);
;             PG8_WAIT_V(8); PG8_WAIT_L(0); PG8_BAR; PG8_MMA(0, 0, At, B0); PG8_MMA(0, 1, At, B1); PG8_BAR; PG8_SCHED;
	v_mfma_f32_16x16x32_bf16 v[60:63], v[128:131], v[192:195], v[60:63]
	v_mfma_f32_16x16x32_bf16 v[56:59], v[136:139], v[192:195], v[56:59]
	v_mfma_f32_16x16x32_bf16 v[44:47], v[128:131], v[200:203], v[44:47]
	v_mfma_f32_16x16x32_bf16 v[40:43], v[136:139], v[200:203], v[40:43]
	v_mfma_f32_16x16x32_bf16 v[28:31], v[128:131], v[216:219], v[28:31]
	v_mfma_f32_16x16x32_bf16 v[24:27], v[136:139], v[216:219], v[24:27]
	v_mfma_f32_16x16x32_bf16 v[12:15], v[128:131], v[224:227], v[12:15]
	v_mfma_f32_16x16x32_bf16 v[8:11], v[136:139], v[224:227], v[8:11]
	v_mfma_f32_16x16x32_bf16 v[60:63], v[132:135], v[196:199], v[60:63]
	v_mfma_f32_16x16x32_bf16 v[56:59], v[140:143], v[196:199], v[56:59]
	v_mfma_f32_16x16x32_bf16 v[44:47], v[132:135], v[212:215], v[44:47]
	v_mfma_f32_16x16x32_bf16 v[40:43], v[140:143], v[212:215], v[40:43]
	v_mfma_f32_16x16x32_bf16 v[28:31], v[132:135], v[220:223], v[28:31]
	v_mfma_f32_16x16x32_bf16 v[24:27], v[140:143], v[220:223], v[24:27]
	v_mfma_f32_16x16x32_bf16 v[12:15], v[132:135], v[228:231], v[12:15]
	v_mfma_f32_16x16x32_bf16 v[8:11], v[140:143], v[228:231], v[8:11]
	s_setprio 0
	s_setprio 1
	v_mfma_f32_16x16x32_bf16 v[52:55], v[160:163], v[192:195], v[52:55]
	v_mfma_f32_16x16x32_bf16 v[48:51], v[168:171], v[192:195], v[48:51]
	v_mfma_f32_16x16x32_bf16 v[36:39], v[160:163], v[200:203], v[36:39]
	v_mfma_f32_16x16x32_bf16 v[32:35], v[168:171], v[200:203], v[32:35]
	v_mfma_f32_16x16x32_bf16 v[20:23], v[160:163], v[216:219], v[20:23]
	v_mfma_f32_16x16x32_bf16 v[16:19], v[168:171], v[216:219], v[16:19]
	v_mfma_f32_16x16x32_bf16 v[4:7], v[160:163], v[224:227], v[4:7]
	v_mfma_f32_16x16x32_bf16 v[0:3], v[168:171], v[224:227], v[0:3]
	v_mfma_f32_16x16x32_bf16 v[52:55], v[164:167], v[196:199], v[52:55]
	v_mfma_f32_16x16x32_bf16 v[48:51], v[182:185], v[196:199], v[48:51]
	v_mfma_f32_16x16x32_bf16 v[36:39], v[164:167], v[212:215], v[36:39]
	v_mfma_f32_16x16x32_bf16 v[32:35], v[182:185], v[212:215], v[32:35]
	v_mfma_f32_16x16x32_bf16 v[20:23], v[164:167], v[220:223], v[20:23]
	v_mfma_f32_16x16x32_bf16 v[16:19], v[182:185], v[220:223], v[16:19]
	v_mfma_f32_16x16x32_bf16 v[4:7], v[164:167], v[228:231], v[4:7]
	v_mfma_f32_16x16x32_bf16 v[0:3], v[182:185], v[228:231], v[0:3]
	s_barrier
	s_setprio 0
	s_add_i32 s29, 0, 0x18000
	s_add_i32 s31, 0, 0x1c000
	v_add_u32_e32 v140, s29, v189
	v_add_u32_e32 v172, s31, v189
	ds_read_b128 v[128:131], v140
	ds_read_b128 v[132:135], v140 offset:1024
	ds_read_b128 v[136:139], v140 offset:2048
	ds_read_b128 v[140:143], v140 offset:3072
	ds_read_b128 v[160:163], v172
	ds_read_b128 v[164:167], v172 offset:1024
	ds_read_b128 v[168:171], v172 offset:2048
	ds_read_b128 v[182:185], v172 offset:3072
	s_add_u32 s56, s56, 0x80000
	s_addc_u32 s57, s57, 0
	s_mov_b32 m0, s75
	v_lshl_add_u64 v[178:179], s[56:57], 0, v[144:145]
	ds_read_b128 v[192:195], v190 offset:32768
	ds_read_b128 v[196:199], v190 offset:33792
	ds_read_b128 v[200:203], v190 offset:34816
	ds_read_b128 v[212:215], v190 offset:35840
	ds_read_b128 v[216:219], v190 offset:36864
	ds_read_b128 v[220:223], v190 offset:37888
	ds_read_b128 v[224:227], v190 offset:38912
	ds_read_b128 v[228:231], v190 offset:39936
	global_load_lds_dwordx4 v[178:179], off
	v_lshl_add_u64 v[178:179], s[56:57], 0, v[148:149]
	s_mov_b32 m0, s62
	s_nop 0
	global_load_lds_dwordx4 v[178:179], off
	s_waitcnt vmcnt(8)
	s_waitcnt lgkmcnt(0)
	s_setprio 1
	s_barrier
	v_mfma_f32_16x16x32_bf16 v[124:127], v[128:131], v[192:195], v[124:127]
	v_mfma_f32_16x16x32_bf16 v[120:123], v[136:139], v[192:195], v[120:123]
	v_mfma_f32_16x16x32_bf16 v[108:111], v[128:131], v[200:203], v[108:111]
	v_mfma_f32_16x16x32_bf16 v[104:107], v[136:139], v[200:203], v[104:107]
	v_mfma_f32_16x16x32_bf16 v[92:95], v[128:131], v[216:219], v[92:95]
	v_mfma_f32_16x16x32_bf16 v[88:91], v[136:139], v[216:219], v[88:91]
	v_mfma_f32_16x16x32_bf16 v[76:79], v[128:131], v[224:227], v[76:79]
	v_mfma_f32_16x16x32_bf16 v[72:75], v[136:139], v[224:227], v[72:75]
	v_mfma_f32_16x16x32_bf16 v[124:127], v[132:135], v[196:199], v[124:127]
	v_mfma_f32_16x16x32_bf16 v[120:123], v[140:143], v[196:199], v[120:123]
	v_mfma_f32_16x16x32_bf16 v[108:111], v[132:135], v[212:215], v[108:111]
	v_mfma_f32_16x16x32_bf16 v[104:107], v[140:143], v[212:215], v[104:107]
	v_mfma_f32_16x16x32_bf16 v[92:95], v[132:135], v[220:223], v[92:95]
	v_mfma_f32_16x16x32_bf16 v[88:91], v[140:143], v[220:223], v[88:91]
	v_mfma_f32_16x16x32_bf16 v[76:79], v[132:135], v[228:231], v[76:79]
	v_mfma_f32_16x16x32_bf16 v[72:75], v[140:143], v[228:231], v[72:75]
	s_setprio 0
	s_setprio 1
	v_mfma_f32_16x16x32_bf16 v[116:119], v[160:163], v[192:195], v[116:119]
	v_mfma_f32_16x16x32_bf16 v[112:115], v[168:171], v[192:195], v[112:115]
	v_mfma_f32_16x16x32_bf16 v[100:103], v[160:163], v[200:203], v[100:103]
	v_mfma_f32_16x16x32_bf16 v[96:99], v[168:171], v[200:203], v[96:99]
	v_mfma_f32_16x16x32_bf16 v[84:87], v[160:163], v[216:219], v[84:87]
	v_mfma_f32_16x16x32_bf16 v[80:83], v[168:171], v[216:219], v[80:83]
	v_mfma_f32_16x16x32_bf16 v[68:71], v[160:163], v[224:227], v[68:71]
	v_mfma_f32_16x16x32_bf16 v[64:67], v[168:171], v[224:227], v[64:67]
	v_mfma_f32_16x16x32_bf16 v[116:119], v[164:167], v[196:199], v[116:119]
	v_mfma_f32_16x16x32_bf16 v[112:115], v[182:185], v[196:199], v[112:115]
	v_mfma_f32_16x16x32_bf16 v[100:103], v[164:167], v[212:215], v[100:103]
	v_mfma_f32_16x16x32_bf16 v[96:99], v[182:185], v[212:215], v[96:99]
	v_mfma_f32_16x16x32_bf16 v[84:87], v[164:167], v[220:223], v[84:87]
	v_mfma_f32_16x16x32_bf16 v[80:83], v[182:185], v[220:223], v[80:83]
	v_mfma_f32_16x16x32_bf16 v[68:71], v[164:167], v[228:231], v[68:71]
	v_mfma_f32_16x16x32_bf16 v[64:67], v[182:185], v[228:231], v[64:67]
	s_barrier
; #define PG8_STAGE(bufoff, gbase, voff) do { _Pragma("unroll") for (int _i = 0; _i < 2; ++_i) \
;         __builtin_amdgcn_global_load_lds((const unsigned*)((const char*)(gbase) + (voff)[_i]), (PG8_LAS unsigned*)(lds + (bufoff) + ldsw + _i * 8192), 16, 0, 0); } while (0)
; #define PG8_LDA(dst, b, h) do { _Pragma("unroll") for (int m = 0; m < 4; ++m) _Pragma("unroll") for (int k = 0; k < 2; ++k) dst[m][k] = *(const PG8_LAS bf16x8*)(lds + PG8_SA(b, h) + aoff + m * 2048 + k * 1024); } while (0)
; #define PG8_MMA(ai, bj, At, Bt) do { __builtin_amdgcn_s_setprio(1); _Pragma("unroll") for (int m = 0; m < 4; ++m) _Pragma("unroll") for (int n = 0; n < 2; ++n) _Pragma("unroll") for (int k = 0; k < 2; ++k) \
;         acc[ai][bj][m][n] = __builtin_amdgcn_mfma_f32_16x16x32_bf16(Bt[n][k], At[m][k], acc[ai][bj][m][n], 0, 0, 0); __builtin_amdgcn_s_setprio(0); } while (0)
; #define PG8_WAIT_V(n) asm volatile("s_waitcnt vmcnt(" #n ")" ::: "memory")
; #define PG8_WAIT_L(n) asm volatile("s_waitcnt lgkmcnt(" #n ")" ::: "memory")
; #define PG8_BAR __builtin_amdgcn_s_barrier()
; #define PG8_SCHED __builtin_amdgcn_sched_barrier(0)
; template <class Epi, class Sched, bool ALIGN_EPI = false, bool SP2 = false>
; __device__ __forceinline__ void gemm_phase(PG8_LAS unsigned char* lds, const Gemm g, const Sched& S, const Epi& E) {
;     ...
;             PG8_LDA(At, 1, 1); PG8_STAGE(PG8_SB(1, 0), b3, voffB); PG8_STAGE(PG8_SB(1, 1), b3 + hstep, voffB); PG8_STAGE(PG8_SA(1, 0), a3, voffA);
;             PG8_WAIT_V(8); PG8_WAIT_L(0); PG8_BAR; PG8_MMA(1, 0, At, B0); PG8_MMA(1, 1, At, B1); PG8_BAR; PG8_SCHED;
	s_setprio 0
	s_add_u32 s52, s52, s54
	s_addc_u32 s53, s53, s55
	s_add_i32 s29, s29, s72
	v_lshl_add_u64 v[178:179], s[52:53], 0, v[146:147]
	s_mov_b32 m0, s29
	s_nop 0
	global_load_lds_dwordx4 v[178:179], off
	ds_read_b128 v[192:195], v190 offset:49152
	ds_read_b128 v[196:199], v190 offset:50176
	ds_read_b128 v[200:203], v190 offset:51200
	ds_read_b128 v[212:215], v190 offset:52224
	s_add_i32 m0, s29, 0x2000
	v_lshl_add_u64 v[178:179], s[52:53], 0, v[150:151]
	s_add_u32 s52, s52, 0x80000
	s_addc_u32 s53, s53, 0
	s_add_i32 s29, s31, s72
	global_load_lds_dwordx4 v[178:179], off
	ds_read_b128 v[216:219], v190 offset:53248
	ds_read_b128 v[220:223], v190 offset:54272
	ds_read_b128 v[224:227], v190 offset:55296
	ds_read_b128 v[228:231], v190 offset:56320
	v_lshl_add_u64 v[178:179], s[52:53], 0, v[146:147]
	s_mov_b32 m0, s29
	s_nop 0
	global_load_lds_dwordx4 v[178:179], off
	v_lshl_add_u64 v[178:179], s[52:53], 0, v[150:151]
	s_add_i32 m0, s29, 0x2000
	s_nop 0
	global_load_lds_dwordx4 v[178:179], off
	v_lshl_add_u64 v[178:179], s[58:59], 0, v[144:145]
	s_mov_b32 m0, s68
	s_nop 0
	global_load_lds_dwordx4 v[178:179], off
	v_lshl_add_u64 v[178:179], s[58:59], 0, v[148:149]
	s_mov_b32 m0, s69
	s_nop 0
	global_load_lds_dwordx4 v[178:179], off
	s_waitcnt vmcnt(8)
	s_waitcnt lgkmcnt(0)
	s_setprio 1
	s_barrier
	v_mfma_f32_16x16x32_bf16 v[60:63], v[128:131], v[192:195], v[60:63]
	v_mfma_f32_16x16x32_bf16 v[56:59], v[136:139], v[192:195], v[56:59]
	v_mfma_f32_16x16x32_bf16 v[44:47], v[128:131], v[200:203], v[44:47]
	v_mfma_f32_16x16x32_bf16 v[40:43], v[136:139], v[200:203], v[40:43]
	v_mfma_f32_16x16x32_bf16 v[28:31], v[128:131], v[216:219], v[28:31]
	v_mfma_f32_16x16x32_bf16 v[24:27], v[136:139], v[216:219], v[24:27]
	v_mfma_f32_16x16x32_bf16 v[12:15], v[128:131], v[224:227], v[12:15]
	v_mfma_f32_16x16x32_bf16 v[8:11], v[136:139], v[224:227], v[8:11]
	v_mfma_f32_16x16x32_bf16 v[60:63], v[132:135], v[196:199], v[60:63]
	v_mfma_f32_16x16x32_bf16 v[56:59], v[140:143], v[196:199], v[56:59]
	v_mfma_f32_16x16x32_bf16 v[44:47], v[132:135], v[212:215], v[44:47]
	v_mfma_f32_16x16x32_bf16 v[40:43], v[140:143], v[212:215], v[40:43]
	v_mfma_f32_16x16x32_bf16 v[28:31], v[132:135], v[220:223], v[28:31]
	v_mfma_f32_16x16x32_bf16 v[24:27], v[140:143], v[220:223], v[24:27]
	v_mfma_f32_16x16x32_bf16 v[12:15], v[132:135], v[228:231], v[12:15]
	v_mfma_f32_16x16x32_bf16 v[8:11], v[140:143], v[228:231], v[8:11]
	s_setprio 0
	s_setprio 1
	v_mfma_f32_16x16x32_bf16 v[52:55], v[160:163], v[192:195], v[52:55]
	v_mfma_f32_16x16x32_bf16 v[48:51], v[168:171], v[192:195], v[48:51]
	v_mfma_f32_16x16x32_bf16 v[36:39], v[160:163], v[200:203], v[36:39]
	v_mfma_f32_16x16x32_bf16 v[32:35], v[168:171], v[200:203], v[32:35]
	v_mfma_f32_16x16x32_bf16 v[20:23], v[160:163], v[216:219], v[20:23]
	v_mfma_f32_16x16x32_bf16 v[16:19], v[168:171], v[216:219], v[16:19]
	v_mfma_f32_16x16x32_bf16 v[4:7], v[160:163], v[224:227], v[4:7]
	v_mfma_f32_16x16x32_bf16 v[0:3], v[168:171], v[224:227], v[0:3]
	v_mfma_f32_16x16x32_bf16 v[52:55], v[164:167], v[196:199], v[52:55]
	v_mfma_f32_16x16x32_bf16 v[48:51], v[182:185], v[196:199], v[48:51]
	v_mfma_f32_16x16x32_bf16 v[36:39], v[164:167], v[212:215], v[36:39]
	v_mfma_f32_16x16x32_bf16 v[32:35], v[182:185], v[212:215], v[32:35]
	v_mfma_f32_16x16x32_bf16 v[20:23], v[164:167], v[220:223], v[20:23]
	v_mfma_f32_16x16x32_bf16 v[16:19], v[182:185], v[220:223], v[16:19]
	v_mfma_f32_16x16x32_bf16 v[4:7], v[164:167], v[228:231], v[4:7]
	v_mfma_f32_16x16x32_bf16 v[0:3], v[182:185], v[228:231], v[0:3]
	s_barrier
	s_setprio 0
	s_cmp_gt_u32 s1, 29
	s_mov_b32 s1, s5
	s_cbranch_scc1 .LBB0_134

; #define PG8_STAGE(bufoff, gbase, voff) do { _Pragma("unroll") for (int _i = 0; _i < 2; ++_i) \
;         __builtin_amdgcn_global_load_lds((const unsigned*)((const char*)(gbase) + (voff)[_i]), (PG8_LAS unsigned*)(lds + (bufoff) + ldsw + _i * 8192), 16, 0, 0); } while (0)
; #define PG8_LDA(dst, b, h) do { _Pragma("unroll") for (int m = 0; m < 4; ++m) _Pragma("unroll") for (int k = 0; k < 2; ++k) dst[m][k] = *(const PG8_LAS bf16x8*)(lds + PG8_SA(b, h) + aoff + m * 2048 + k * 1024); } while (0)
; #define PG8_LDB(dst, b, h) do { _Pragma("unroll") for (int n = 0; n < 2; ++n) _Pragma("unroll") for (int k = 0; k < 2; ++k) dst[n][k] = *(const PG8_LAS bf16x8*)(lds + PG8_SB(b, h) + boff + n * 2048 + k * 1024); } while (0)
; #define PG8_MMA(ai, bj, At, Bt) do { __builtin_amdgcn_s_setprio(1); _Pragma("unroll") for (int m = 0; m < 4; ++m) _Pragma("unroll") for (int n = 0; n < 2; ++n) _Pragma("unroll") for (int k = 0; k < 2; ++k) \
;         acc[ai][bj][m][n] = __builtin_amdgcn_mfma_f32_16x16x32_bf16(Bt[n][k], At[m][k], acc[ai][bj][m][n], 0, 0, 0); __builtin_amdgcn_s_setprio(0); } while (0)
; #define PG8_WAIT_V(n) asm volatile("s_waitcnt vmcnt(" #n ")" ::: "memory")
; #define PG8_BAR __builtin_amdgcn_s_barrier()
; template <class Epi, class Sched, bool ALIGN_EPI = false, bool SP2 = false>
; __device__ __forceinline__ void gemm_phase(PG8_LAS unsigned char* lds, const Gemm g, const Sched& S, const Epi& E) {
;     ...
;         for (int t = 0; t < nt; t += 2) {
;             const bool last = (t == nt - 2);
;             const char* a1 = cA + (long)(t + 1) * st;
;             const char* a2 = last ? nA : cA + (long)(t + 2) * st; const char* b2 = last ? nB : cB + (long)(t + 2) * st;
;             const long s3 = last ? nst : st; const char* a3 = a2 + s3; const char* b3 = b2 + s3;
;             if (last && has_next) S.a_ready(nxt);
;             if constexpr (SP2) {
;             PG8_LDB(B0, 0, 0); PG8_LDB(B1, 0, 1); PG8_SCHED; PG8_LDA(At, 0, 0); PG8_STAGE(PG8_SA(1, 1), a1 + hstep, voffA);
;             PG8_WAIT_V(8); PG8_WAIT_L(0); PG8_BAR; PG8_MMA(0, 0, At, B0); PG8_MMA(0, 1, At, B1); PG8_BAR; PG8_SCHED;
;             PG8_LDA(At, 0, 1); PG8_STAGE(PG8_SB(0, 0), b2, voffB); PG8_STAGE(PG8_SB(0, 1), b2 + hstep, voffB); PG8_STAGE(PG8_SA(0, 0), a2, voffA);
;             PG8_WAIT_V(8); PG8_WAIT_L(0); PG8_BAR; PG8_MMA(1, 0, At, B0); PG8_MMA(1, 1, At, B1); PG8_BAR; PG8_SCHED;
.LBB0_324:
	s_or_b32 s46, s23, 1
	s_mul_i32 s47, s31, s46
	s_mul_hi_u32 s62, s30, s46
	s_add_i32 s63, s62, s47
	s_mul_i32 s62, s30, s46
	s_add_u32 s46, s44, s42
	s_addc_u32 s47, s45, s43
	s_add_i32 s64, 0, 0x10000
	s_add_i32 s65, 0, 0x14000
	v_add_u32_e32 v150, s64, v139
	v_add_u32_e32 v166, s65, v139
	ds_read_b128 v[134:137], v150
	ds_read_b128 v[142:145], v150 offset:1024
	ds_read_b128 v[146:149], v150 offset:2048
	ds_read_b128 v[150:153], v150 offset:3072
	ds_read_b128 v[154:157], v166
	ds_read_b128 v[158:161], v166 offset:1024
	ds_read_b128 v[162:165], v166 offset:2048
	ds_read_b128 v[166:169], v166 offset:3072
	s_add_u32 s62, s13, s62
	s_addc_u32 s63, s15, s63
	v_lshl_add_u64 v[170:171], s[62:63], 0, v[128:129]
	s_add_i32 m0, s25, 0xc000
	ds_read_b128 v[178:181], v141
	ds_read_b128 v[182:185], v141 offset:1024
	ds_read_b128 v[186:189], v141 offset:2048
	ds_read_b128 v[190:193], v141 offset:3072
	ds_read_b128 v[194:197], v141 offset:4096
	ds_read_b128 v[198:201], v141 offset:5120
	ds_read_b128 v[212:215], v141 offset:6144
	ds_read_b128 v[216:219], v141 offset:7168
	global_load_lds_dwordx4 v[170:171], off
	v_lshl_add_u64 v[170:171], s[62:63], 0, v[130:131]
	s_add_i32 m0, s25, 0xe000
	s_nop 0
	global_load_lds_dwordx4 v[170:171], off
	s_waitcnt vmcnt(8)
	s_waitcnt lgkmcnt(0)
	s_setprio 1
	s_barrier
	v_mfma_f32_16x16x32_bf16 v[124:127], v[134:137], v[178:181], v[124:127]
	v_mfma_f32_16x16x32_bf16 v[120:123], v[146:149], v[178:181], v[120:123]
	v_mfma_f32_16x16x32_bf16 v[108:111], v[134:137], v[186:189], v[108:111]
	v_mfma_f32_16x16x32_bf16 v[104:107], v[146:149], v[186:189], v[104:107]
	v_mfma_f32_16x16x32_bf16 v[92:95], v[134:137], v[194:197], v[92:95]
	v_mfma_f32_16x16x32_bf16 v[88:91], v[146:149], v[194:197], v[88:91]
	v_mfma_f32_16x16x32_bf16 v[76:79], v[134:137], v[212:215], v[76:79]
	v_mfma_f32_16x16x32_bf16 v[72:75], v[146:149], v[212:215], v[72:75]
	v_mfma_f32_16x16x32_bf16 v[124:127], v[142:145], v[182:185], v[124:127]
	v_mfma_f32_16x16x32_bf16 v[120:123], v[150:153], v[182:185], v[120:123]
	v_mfma_f32_16x16x32_bf16 v[108:111], v[142:145], v[190:193], v[108:111]
	v_mfma_f32_16x16x32_bf16 v[104:107], v[150:153], v[190:193], v[104:107]
	v_mfma_f32_16x16x32_bf16 v[92:95], v[142:145], v[198:201], v[92:95]
	v_mfma_f32_16x16x32_bf16 v[88:91], v[150:153], v[198:201], v[88:91]
	v_mfma_f32_16x16x32_bf16 v[76:79], v[142:145], v[216:219], v[76:79]
	v_mfma_f32_16x16x32_bf16 v[72:75], v[150:153], v[216:219], v[72:75]
	s_setprio 0
	s_setprio 1
	v_mfma_f32_16x16x32_bf16 v[116:119], v[154:157], v[178:181], v[116:119]
	v_mfma_f32_16x16x32_bf16 v[112:115], v[162:165], v[178:181], v[112:115]
	v_mfma_f32_16x16x32_bf16 v[100:103], v[154:157], v[186:189], v[100:103]
	v_mfma_f32_16x16x32_bf16 v[96:99], v[162:165], v[186:189], v[96:99]
	v_mfma_f32_16x16x32_bf16 v[84:87], v[154:157], v[194:197], v[84:87]
	v_mfma_f32_16x16x32_bf16 v[80:83], v[162:165], v[194:197], v[80:83]
	v_mfma_f32_16x16x32_bf16 v[68:71], v[154:157], v[212:215], v[68:71]
	v_mfma_f32_16x16x32_bf16 v[64:67], v[162:165], v[212:215], v[64:67]
	v_mfma_f32_16x16x32_bf16 v[116:119], v[158:161], v[182:185], v[116:119]
	v_mfma_f32_16x16x32_bf16 v[112:115], v[166:169], v[182:185], v[112:115]
	v_mfma_f32_16x16x32_bf16 v[100:103], v[158:161], v[190:193], v[100:103]
	v_mfma_f32_16x16x32_bf16 v[96:99], v[166:169], v[190:193], v[96:99]
	v_mfma_f32_16x16x32_bf16 v[84:87], v[158:161], v[198:201], v[84:87]
	v_mfma_f32_16x16x32_bf16 v[80:83], v[166:169], v[198:201], v[80:83]
	v_mfma_f32_16x16x32_bf16 v[68:71], v[158:161], v[216:219], v[68:71]
	v_mfma_f32_16x16x32_bf16 v[64:67], v[166:169], v[216:219], v[64:67]
	s_barrier
	s_setprio 0
	s_add_i32 s62, s64, s53
	v_lshl_add_u64 v[170:171], s[40:41], 0, v[172:173]
	s_mov_b32 m0, s62
	s_nop 0
	global_load_lds_dwordx4 v[170:171], off
	ds_read_b128 v[178:181], v141 offset:16384
	ds_read_b128 v[182:185], v141 offset:17408
	ds_read_b128 v[186:189], v141 offset:18432
	ds_read_b128 v[190:193], v141 offset:19456
	s_add_i32 m0, s62, 0x2000
	s_add_u32 s62, s40, 0x80000
	v_lshl_add_u64 v[170:171], s[40:41], 0, v[132:133]
	s_addc_u32 s63, s41, 0
	s_add_i32 s64, s65, s53
	global_load_lds_dwordx4 v[170:171], off
	ds_read_b128 v[194:197], v141 offset:20480
	ds_read_b128 v[198:201], v141 offset:21504
	ds_read_b128 v[212:215], v141 offset:22528
	ds_read_b128 v[216:219], v141 offset:23552
	v_lshl_add_u64 v[170:171], s[62:63], 0, v[172:173]
	s_mov_b32 m0, s64
	s_nop 0
	global_load_lds_dwordx4 v[170:171], off
	v_lshl_add_u64 v[170:171], s[62:63], 0, v[132:133]
	s_add_i32 m0, s64, 0x2000
	s_nop 0
	global_load_lds_dwordx4 v[170:171], off
	v_lshl_add_u64 v[170:171], s[44:45], 0, v[128:129]
	s_mov_b32 m0, s25
	s_nop 0
	global_load_lds_dwordx4 v[170:171], off
	v_lshl_add_u64 v[170:171], s[44:45], 0, v[130:131]
	s_mov_b32 m0, s54
	s_nop 0
	global_load_lds_dwordx4 v[170:171], off
	s_waitcnt vmcnt(8)
	s_waitcnt lgkmcnt(0)
	s_setprio 1
	s_barrier
; #define PG8_STAGE(bufoff, gbase, voff) do { _Pragma("unroll") for (int _i = 0; _i < 2; ++_i) \
;         __builtin_amdgcn_global_load_lds((const unsigned*)((const char*)(gbase) + (voff)[_i]), (PG8_LAS unsigned*)(lds + (bufoff) + ldsw + _i * 8192), 16, 0, 0); } while (0)
; #define PG8_LDA(dst, b, h) do { _Pragma("unroll") for (int m = 0; m < 4; ++m) _Pragma("unroll") for (int k = 0; k < 2; ++k) dst[m][k] = *(const PG8_LAS bf16x8*)(lds + PG8_SA(b, h) + aoff + m * 2048 + k * 1024); } while (0)
; #define PG8_LDB(dst, b, h) do { _Pragma("unroll") for (int n = 0; n < 2; ++n) _Pragma("unroll") for (int k = 0; k < 2; ++k) dst[n][k] = *(const PG8_LAS bf16x8*)(lds + PG8_SB(b, h) + boff + n * 2048 + k * 1024); } while (0)
; #define PG8_MMA(ai, bj, At, Bt) do { __builtin_amdgcn_s_setprio(1); _Pragma("unroll") for (int m = 0; m < 4; ++m) _Pragma("unroll") for (int n = 0; n < 2; ++n) _Pragma("unroll") for (int k = 0; k < 2; ++k) \
;         acc[ai][bj][m][n] = __builtin_amdgcn_mfma_f32_16x16x32_bf16(Bt[n][k], At[m][k], acc[ai][bj][m][n], 0, 0, 0); __builtin_amdgcn_s_setprio(0); } while (0)
; #define PG8_WAIT_V(n) asm volatile("s_waitcnt vmcnt(" #n ")" ::: "memory")
; #define PG8_WAIT_L(n) asm volatile("s_waitcnt lgkmcnt(" #n ")" ::: "memory")
; #define PG8_BAR __builtin_amdgcn_s_barrier()
; #define PG8_SCHED __builtin_amdgcn_sched_barrier(0)
; template <class Epi, class Sched, bool ALIGN_EPI = false, bool SP2 = false>
; __device__ __forceinline__ void gemm_phase(PG8_LAS unsigned char* lds, const Gemm g, const Sched& S, const Epi& E) {
;     ...
;             PG8_WAIT_V(8); PG8_WAIT_L(0); PG8_BAR; PG8_MMA(1, 0, At, B0); PG8_MMA(1, 1, At, B1); PG8_BAR; PG8_SCHED;
;             PG8_LDB(B0, 1, 0); PG8_LDB(B1, 1, 1); PG8_SCHED; PG8_LDA(At, 1, 0); PG8_STAGE(PG8_SA(0, 1), a2 + hstep, voffA);
;             PG8_WAIT_V(8); PG8_WAIT_L(0); PG8_BAR; PG8_MMA(0, 0, At, B0); PG8_MMA(0, 1, At, B1); PG8_BAR; PG8_SCHED;
	v_mfma_f32_16x16x32_bf16 v[60:63], v[134:137], v[178:181], v[60:63]
	v_mfma_f32_16x16x32_bf16 v[56:59], v[146:149], v[178:181], v[56:59]
	v_mfma_f32_16x16x32_bf16 v[44:47], v[134:137], v[186:189], v[44:47]
	v_mfma_f32_16x16x32_bf16 v[40:43], v[146:149], v[186:189], v[40:43]
	v_mfma_f32_16x16x32_bf16 v[28:31], v[134:137], v[194:197], v[28:31]
	v_mfma_f32_16x16x32_bf16 v[24:27], v[146:149], v[194:197], v[24:27]
	v_mfma_f32_16x16x32_bf16 v[12:15], v[134:137], v[212:215], v[12:15]
	v_mfma_f32_16x16x32_bf16 v[8:11], v[146:149], v[212:215], v[8:11]
	v_mfma_f32_16x16x32_bf16 v[60:63], v[142:145], v[182:185], v[60:63]
	v_mfma_f32_16x16x32_bf16 v[56:59], v[150:153], v[182:185], v[56:59]
	v_mfma_f32_16x16x32_bf16 v[44:47], v[142:145], v[190:193], v[44:47]
	v_mfma_f32_16x16x32_bf16 v[40:43], v[150:153], v[190:193], v[40:43]
	v_mfma_f32_16x16x32_bf16 v[28:31], v[142:145], v[198:201], v[28:31]
	v_mfma_f32_16x16x32_bf16 v[24:27], v[150:153], v[198:201], v[24:27]
	v_mfma_f32_16x16x32_bf16 v[12:15], v[142:145], v[216:219], v[12:15]
	v_mfma_f32_16x16x32_bf16 v[8:11], v[150:153], v[216:219], v[8:11]
	s_setprio 0
	s_setprio 1
	v_mfma_f32_16x16x32_bf16 v[52:55], v[154:157], v[178:181], v[52:55]
	v_mfma_f32_16x16x32_bf16 v[48:51], v[162:165], v[178:181], v[48:51]
	v_mfma_f32_16x16x32_bf16 v[36:39], v[154:157], v[186:189], v[36:39]
	v_mfma_f32_16x16x32_bf16 v[32:35], v[162:165], v[186:189], v[32:35]
	v_mfma_f32_16x16x32_bf16 v[20:23], v[154:157], v[194:197], v[20:23]
	v_mfma_f32_16x16x32_bf16 v[16:19], v[162:165], v[194:197], v[16:19]
	v_mfma_f32_16x16x32_bf16 v[4:7], v[154:157], v[212:215], v[4:7]
	v_mfma_f32_16x16x32_bf16 v[0:3], v[162:165], v[212:215], v[0:3]
	v_mfma_f32_16x16x32_bf16 v[52:55], v[158:161], v[182:185], v[52:55]
	v_mfma_f32_16x16x32_bf16 v[48:51], v[166:169], v[182:185], v[48:51]
	v_mfma_f32_16x16x32_bf16 v[36:39], v[158:161], v[190:193], v[36:39]
	v_mfma_f32_16x16x32_bf16 v[32:35], v[166:169], v[190:193], v[32:35]
	v_mfma_f32_16x16x32_bf16 v[20:23], v[158:161], v[198:201], v[20:23]
	v_mfma_f32_16x16x32_bf16 v[16:19], v[166:169], v[198:201], v[16:19]
	v_mfma_f32_16x16x32_bf16 v[4:7], v[158:161], v[216:219], v[4:7]
	v_mfma_f32_16x16x32_bf16 v[0:3], v[166:169], v[216:219], v[0:3]
	s_barrier
	s_setprio 0
	s_add_i32 s62, 0, 0x18000
	s_add_i32 s63, 0, 0x1c000
	v_add_u32_e32 v150, s62, v139
	v_add_u32_e32 v166, s63, v139
	ds_read_b128 v[134:137], v150
	ds_read_b128 v[142:145], v150 offset:1024
	ds_read_b128 v[146:149], v150 offset:2048
	ds_read_b128 v[150:153], v150 offset:3072
	ds_read_b128 v[154:157], v166
	ds_read_b128 v[158:161], v166 offset:1024
	ds_read_b128 v[162:165], v166 offset:2048
	ds_read_b128 v[166:169], v166 offset:3072
	s_add_u32 s44, s44, 0x80000
	s_addc_u32 s45, s45, 0
	s_mov_b32 m0, s55
	v_lshl_add_u64 v[170:171], s[44:45], 0, v[128:129]
	ds_read_b128 v[178:181], v141 offset:32768
	ds_read_b128 v[182:185], v141 offset:33792
	ds_read_b128 v[186:189], v141 offset:34816
	ds_read_b128 v[190:193], v141 offset:35840
	ds_read_b128 v[194:197], v141 offset:36864
	ds_read_b128 v[198:201], v141 offset:37888
	ds_read_b128 v[212:215], v141 offset:38912
	ds_read_b128 v[216:219], v141 offset:39936
	global_load_lds_dwordx4 v[170:171], off
	v_lshl_add_u64 v[170:171], s[44:45], 0, v[130:131]
	s_mov_b32 m0, s56
	s_nop 0
	global_load_lds_dwordx4 v[170:171], off
	s_waitcnt vmcnt(8)
	s_waitcnt lgkmcnt(0)
	s_setprio 1
	s_barrier
	v_mfma_f32_16x16x32_bf16 v[124:127], v[134:137], v[178:181], v[124:127]
	v_mfma_f32_16x16x32_bf16 v[120:123], v[146:149], v[178:181], v[120:123]
	v_mfma_f32_16x16x32_bf16 v[108:111], v[134:137], v[186:189], v[108:111]
	v_mfma_f32_16x16x32_bf16 v[104:107], v[146:149], v[186:189], v[104:107]
	v_mfma_f32_16x16x32_bf16 v[92:95], v[134:137], v[194:197], v[92:95]
	v_mfma_f32_16x16x32_bf16 v[88:91], v[146:149], v[194:197], v[88:91]
	v_mfma_f32_16x16x32_bf16 v[76:79], v[134:137], v[212:215], v[76:79]
	v_mfma_f32_16x16x32_bf16 v[72:75], v[146:149], v[212:215], v[72:75]
	v_mfma_f32_16x16x32_bf16 v[124:127], v[142:145], v[182:185], v[124:127]
	v_mfma_f32_16x16x32_bf16 v[120:123], v[150:153], v[182:185], v[120:123]
	v_mfma_f32_16x16x32_bf16 v[108:111], v[142:145], v[190:193], v[108:111]
	v_mfma_f32_16x16x32_bf16 v[104:107], v[150:153], v[190:193], v[104:107]
	v_mfma_f32_16x16x32_bf16 v[92:95], v[142:145], v[198:201], v[92:95]
	v_mfma_f32_16x16x32_bf16 v[88:91], v[150:153], v[198:201], v[88:91]
	v_mfma_f32_16x16x32_bf16 v[76:79], v[142:145], v[216:219], v[76:79]
	v_mfma_f32_16x16x32_bf16 v[72:75], v[150:153], v[216:219], v[72:75]
	s_setprio 0
	s_setprio 1
	v_mfma_f32_16x16x32_bf16 v[116:119], v[154:157], v[178:181], v[116:119]
	v_mfma_f32_16x16x32_bf16 v[112:115], v[162:165], v[178:181], v[112:115]
	v_mfma_f32_16x16x32_bf16 v[100:103], v[154:157], v[186:189], v[100:103]
	v_mfma_f32_16x16x32_bf16 v[96:99], v[162:165], v[186:189], v[96:99]
	v_mfma_f32_16x16x32_bf16 v[84:87], v[154:157], v[194:197], v[84:87]
	v_mfma_f32_16x16x32_bf16 v[80:83], v[162:165], v[194:197], v[80:83]
	v_mfma_f32_16x16x32_bf16 v[68:71], v[154:157], v[212:215], v[68:71]
	v_mfma_f32_16x16x32_bf16 v[64:67], v[162:165], v[212:215], v[64:67]
	v_mfma_f32_16x16x32_bf16 v[116:119], v[158:161], v[182:185], v[116:119]
	v_mfma_f32_16x16x32_bf16 v[112:115], v[166:169], v[182:185], v[112:115]
	v_mfma_f32_16x16x32_bf16 v[100:103], v[158:161], v[190:193], v[100:103]
	v_mfma_f32_16x16x32_bf16 v[96:99], v[166:169], v[190:193], v[96:99]
	v_mfma_f32_16x16x32_bf16 v[84:87], v[158:161], v[198:201], v[84:87]
	v_mfma_f32_16x16x32_bf16 v[80:83], v[166:169], v[198:201], v[80:83]
	v_mfma_f32_16x16x32_bf16 v[68:71], v[158:161], v[216:219], v[68:71]
	v_mfma_f32_16x16x32_bf16 v[64:67], v[166:169], v[216:219], v[64:67]
	s_barrier
; #define PG8_STAGE(bufoff, gbase, voff) do { _Pragma("unroll") for (int _i = 0; _i < 2; ++_i) \
;         __builtin_amdgcn_global_load_lds((const unsigned*)((const char*)(gbase) + (voff)[_i]), (PG8_LAS unsigned*)(lds + (bufoff) + ldsw + _i * 8192), 16, 0, 0); } while (0)
; #define PG8_LDA(dst, b, h) do { _Pragma("unroll") for (int m = 0; m < 4; ++m) _Pragma("unroll") for (int k = 0; k < 2; ++k) dst[m][k] = *(const PG8_LAS bf16x8*)(lds + PG8_SA(b, h) + aoff + m * 2048 + k * 1024); } while (0)
; #define PG8_MMA(ai, bj, At, Bt) do { __builtin_amdgcn_s_setprio(1); _Pragma("unroll") for (int m = 0; m < 4; ++m) _Pragma("unroll") for (int n = 0; n < 2; ++n) _Pragma("unroll") for (int k = 0; k < 2; ++k) \
;         acc[ai][bj][m][n] = __builtin_amdgcn_mfma_f32_16x16x32_bf16(Bt[n][k], At[m][k], acc[ai][bj][m][n], 0, 0, 0); __builtin_amdgcn_s_setprio(0); } while (0)
; #define PG8_WAIT_V(n) asm volatile("s_waitcnt vmcnt(" #n ")" ::: "memory")
; #define PG8_WAIT_L(n) asm volatile("s_waitcnt lgkmcnt(" #n ")" ::: "memory")
; #define PG8_BAR __builtin_amdgcn_s_barrier()
; #define PG8_SCHED __builtin_amdgcn_sched_barrier(0)
; template <class Epi, class Sched, bool ALIGN_EPI = false, bool SP2 = false>
; __device__ __forceinline__ void gemm_phase(PG8_LAS unsigned char* lds, const Gemm g, const Sched& S, const Epi& E) {
;     ...
;             PG8_LDA(At, 1, 1); PG8_STAGE(PG8_SB(1, 0), b3, voffB); PG8_STAGE(PG8_SB(1, 1), b3 + hstep, voffB); PG8_STAGE(PG8_SA(1, 0), a3, voffA);
;             PG8_WAIT_V(8); PG8_WAIT_L(0); PG8_BAR; PG8_MMA(1, 0, At, B0); PG8_MMA(1, 1, At, B1); PG8_BAR; PG8_SCHED;
	s_setprio 0
	s_add_u32 s40, s40, s42
	s_addc_u32 s41, s41, s43
	s_add_i32 s42, s62, s53
	v_lshl_add_u64 v[170:171], s[40:41], 0, v[172:173]
	s_mov_b32 m0, s42
	s_nop 0
	global_load_lds_dwordx4 v[170:171], off
	ds_read_b128 v[178:181], v141 offset:49152
	ds_read_b128 v[182:185], v141 offset:50176
	ds_read_b128 v[186:189], v141 offset:51200
	ds_read_b128 v[190:193], v141 offset:52224
	s_add_i32 m0, s42, 0x2000
	v_lshl_add_u64 v[170:171], s[40:41], 0, v[132:133]
	s_add_u32 s40, s40, 0x80000
	s_addc_u32 s41, s41, 0
	s_add_i32 s42, s63, s53
	global_load_lds_dwordx4 v[170:171], off
	ds_read_b128 v[194:197], v141 offset:53248
	ds_read_b128 v[198:201], v141 offset:54272
	ds_read_b128 v[212:215], v141 offset:55296
	ds_read_b128 v[216:219], v141 offset:56320
	v_lshl_add_u64 v[170:171], s[40:41], 0, v[172:173]
	s_mov_b32 m0, s42
	s_nop 0
	global_load_lds_dwordx4 v[170:171], off
	v_lshl_add_u64 v[170:171], s[40:41], 0, v[132:133]
	s_add_i32 m0, s42, 0x2000
	s_nop 0
	global_load_lds_dwordx4 v[170:171], off
	v_lshl_add_u64 v[170:171], s[46:47], 0, v[128:129]
	s_mov_b32 m0, s57
	s_nop 0
	global_load_lds_dwordx4 v[170:171], off
	v_lshl_add_u64 v[170:171], s[46:47], 0, v[130:131]
	s_mov_b32 m0, s58
	s_nop 0
	global_load_lds_dwordx4 v[170:171], off
	s_waitcnt vmcnt(8)
	s_waitcnt lgkmcnt(0)
	s_setprio 1
	s_barrier
	v_mfma_f32_16x16x32_bf16 v[60:63], v[134:137], v[178:181], v[60:63]
	v_mfma_f32_16x16x32_bf16 v[56:59], v[146:149], v[178:181], v[56:59]
	v_mfma_f32_16x16x32_bf16 v[44:47], v[134:137], v[186:189], v[44:47]
	v_mfma_f32_16x16x32_bf16 v[40:43], v[146:149], v[186:189], v[40:43]
	v_mfma_f32_16x16x32_bf16 v[28:31], v[134:137], v[194:197], v[28:31]
	v_mfma_f32_16x16x32_bf16 v[24:27], v[146:149], v[194:197], v[24:27]
	v_mfma_f32_16x16x32_bf16 v[12:15], v[134:137], v[212:215], v[12:15]
	v_mfma_f32_16x16x32_bf16 v[8:11], v[146:149], v[212:215], v[8:11]
	v_mfma_f32_16x16x32_bf16 v[60:63], v[142:145], v[182:185], v[60:63]
	v_mfma_f32_16x16x32_bf16 v[56:59], v[150:153], v[182:185], v[56:59]
	v_mfma_f32_16x16x32_bf16 v[44:47], v[142:145], v[190:193], v[44:47]
	v_mfma_f32_16x16x32_bf16 v[40:43], v[150:153], v[190:193], v[40:43]
	v_mfma_f32_16x16x32_bf16 v[28:31], v[142:145], v[198:201], v[28:31]
	v_mfma_f32_16x16x32_bf16 v[24:27], v[150:153], v[198:201], v[24:27]
	v_mfma_f32_16x16x32_bf16 v[12:15], v[142:145], v[216:219], v[12:15]
	v_mfma_f32_16x16x32_bf16 v[8:11], v[150:153], v[216:219], v[8:11]
	s_setprio 0
	s_setprio 1
	v_mfma_f32_16x16x32_bf16 v[52:55], v[154:157], v[178:181], v[52:55]
	v_mfma_f32_16x16x32_bf16 v[48:51], v[162:165], v[178:181], v[48:51]
	v_mfma_f32_16x16x32_bf16 v[36:39], v[154:157], v[186:189], v[36:39]
	v_mfma_f32_16x16x32_bf16 v[32:35], v[162:165], v[186:189], v[32:35]
	v_mfma_f32_16x16x32_bf16 v[20:23], v[154:157], v[194:197], v[20:23]
	v_mfma_f32_16x16x32_bf16 v[16:19], v[162:165], v[194:197], v[16:19]
	v_mfma_f32_16x16x32_bf16 v[4:7], v[154:157], v[212:215], v[4:7]
	v_mfma_f32_16x16x32_bf16 v[0:3], v[162:165], v[212:215], v[0:3]
	v_mfma_f32_16x16x32_bf16 v[52:55], v[158:161], v[182:185], v[52:55]
	v_mfma_f32_16x16x32_bf16 v[48:51], v[166:169], v[182:185], v[48:51]
	v_mfma_f32_16x16x32_bf16 v[36:39], v[158:161], v[190:193], v[36:39]
	v_mfma_f32_16x16x32_bf16 v[32:35], v[166:169], v[190:193], v[32:35]
	v_mfma_f32_16x16x32_bf16 v[20:23], v[158:161], v[198:201], v[20:23]
	v_mfma_f32_16x16x32_bf16 v[16:19], v[166:169], v[198:201], v[16:19]
	v_mfma_f32_16x16x32_bf16 v[4:7], v[158:161], v[216:219], v[4:7]
	v_mfma_f32_16x16x32_bf16 v[0:3], v[166:169], v[216:219], v[0:3]
	s_barrier
	s_setprio 0
	s_cmp_gt_u32 s23, 29
	s_mov_b32 s23, s61
	s_cbranch_scc1 .LBB0_329

; #define PG8_STAGE(bufoff, gbase, voff) do { _Pragma("unroll") for (int _i = 0; _i < 2; ++_i) \
;         __builtin_amdgcn_global_load_lds((const unsigned*)((const char*)(gbase) + (voff)[_i]), (PG8_LAS unsigned*)(lds + (bufoff) + ldsw + _i * 8192), 16, 0, 0); } while (0)
; #define PG8_LDA(dst, b, h) do { _Pragma("unroll") for (int m = 0; m < 4; ++m) _Pragma("unroll") for (int k = 0; k < 2; ++k) dst[m][k] = *(const PG8_LAS bf16x8*)(lds + PG8_SA(b, h) + aoff + m * 2048 + k * 1024); } while (0)
; #define PG8_LDB(dst, b, h) do { _Pragma("unroll") for (int n = 0; n < 2; ++n) _Pragma("unroll") for (int k = 0; k < 2; ++k) dst[n][k] = *(const PG8_LAS bf16x8*)(lds + PG8_SB(b, h) + boff + n * 2048 + k * 1024); } while (0)
; #define PG8_MMA(ai, bj, At, Bt) do { __builtin_amdgcn_s_setprio(1); _Pragma("unroll") for (int m = 0; m < 4; ++m) _Pragma("unroll") for (int n = 0; n < 2; ++n) _Pragma("unroll") for (int k = 0; k < 2; ++k) \
;         acc[ai][bj][m][n] = __builtin_amdgcn_mfma_f32_16x16x32_bf16(Bt[n][k], At[m][k], acc[ai][bj][m][n], 0, 0, 0); __builtin_amdgcn_s_setprio(0); } while (0)
; #define PG8_WAIT_V(n) asm volatile("s_waitcnt vmcnt(" #n ")" ::: "memory")
; #define PG8_BAR __builtin_amdgcn_s_barrier()
; template <class Epi, class Sched, bool ALIGN_EPI = false, bool SP2 = false>
; __device__ __forceinline__ void gemm_phase(PG8_LAS unsigned char* lds, const Gemm g, const Sched& S, const Epi& E) {
;     ...
;         for (int t = 0; t < nt; t += 2) {
;             const bool last = (t == nt - 2);
;             const char* a1 = cA + (long)(t + 1) * st;
;             const char* a2 = last ? nA : cA + (long)(t + 2) * st; const char* b2 = last ? nB : cB + (long)(t + 2) * st;
;             const long s3 = last ? nst : st; const char* a3 = a2 + s3; const char* b3 = b2 + s3;
;             if (last && has_next) S.a_ready(nxt);
;             if constexpr (SP2) {
;             PG8_LDB(B0, 0, 0); PG8_LDB(B1, 0, 1); PG8_SCHED; PG8_LDA(At, 0, 0); PG8_STAGE(PG8_SA(1, 1), a1 + hstep, voffA);
;             PG8_WAIT_V(8); PG8_WAIT_L(0); PG8_BAR; PG8_MMA(0, 0, At, B0); PG8_MMA(0, 1, At, B1); PG8_BAR; PG8_SCHED;
;             PG8_LDA(At, 0, 1); PG8_STAGE(PG8_SB(0, 0), b2, voffB); PG8_STAGE(PG8_SB(0, 1), b2 + hstep, voffB); PG8_STAGE(PG8_SA(0, 0), a2, voffA);
;             PG8_WAIT_V(8); PG8_WAIT_L(0); PG8_BAR; PG8_MMA(1, 0, At, B0); PG8_MMA(1, 1, At, B1); PG8_BAR; PG8_SCHED;
.LBB0_414:
	s_or_b32 s21, s1, 1
	s_mul_i32 s48, s35, s21
	s_mul_hi_u32 s49, s34, s21
	s_add_i32 s49, s49, s48
	s_mul_i32 s21, s34, s21
	s_add_u32 s21, s30, s21
	s_addc_u32 s65, s31, s49
	s_add_u32 s48, s46, s44
	s_addc_u32 s49, s47, s45
	s_add_i32 s66, 0, 0x10000
	s_add_i32 s67, 0, 0x14000
	v_add_u32_e32 v148, s66, v155
	v_add_u32_e32 v152, s67, v155
	ds_read_b128 v[136:139], v148
	ds_read_b128 v[140:143], v148 offset:1024
	ds_read_b128 v[144:147], v148 offset:2048
	ds_read_b128 v[148:151], v148 offset:3072
	ds_read_b128 v[160:163], v152
	ds_read_b128 v[164:167], v152 offset:1024
	ds_read_b128 v[168:171], v152 offset:2048
	ds_read_b128 v[182:185], v152 offset:3072
	s_add_u32 s64, s21, 0x80000
	s_addc_u32 s65, s65, 0
	v_lshl_add_u64 v[178:179], s[64:65], 0, v[128:129]
	s_add_i32 m0, s56, 0xc000
	ds_read_b128 v[186:189], v158
	ds_read_b128 v[190:193], v158 offset:1024
	ds_read_b128 v[194:197], v158 offset:2048
	ds_read_b128 v[198:201], v158 offset:3072
	ds_read_b128 v[212:215], v158 offset:4096
	ds_read_b128 v[216:219], v158 offset:5120
	ds_read_b128 v[220:223], v158 offset:6144
	ds_read_b128 v[224:227], v158 offset:7168
	global_load_lds_dwordx4 v[178:179], off
	v_lshl_add_u64 v[178:179], s[64:65], 0, v[132:133]
	s_add_i32 m0, s56, 0xe000
	s_nop 0
	global_load_lds_dwordx4 v[178:179], off
	s_waitcnt vmcnt(8)
	s_waitcnt lgkmcnt(0)
	s_setprio 1
	s_barrier
	v_mfma_f32_16x16x32_bf16 v[124:127], v[136:139], v[186:189], v[124:127]
	v_mfma_f32_16x16x32_bf16 v[120:123], v[144:147], v[186:189], v[120:123]
	v_mfma_f32_16x16x32_bf16 v[108:111], v[136:139], v[194:197], v[108:111]
	v_mfma_f32_16x16x32_bf16 v[104:107], v[144:147], v[194:197], v[104:107]
	v_mfma_f32_16x16x32_bf16 v[92:95], v[136:139], v[212:215], v[92:95]
	v_mfma_f32_16x16x32_bf16 v[88:91], v[144:147], v[212:215], v[88:91]
	v_mfma_f32_16x16x32_bf16 v[76:79], v[136:139], v[220:223], v[76:79]
	v_mfma_f32_16x16x32_bf16 v[72:75], v[144:147], v[220:223], v[72:75]
	v_mfma_f32_16x16x32_bf16 v[124:127], v[140:143], v[190:193], v[124:127]
	v_mfma_f32_16x16x32_bf16 v[120:123], v[148:151], v[190:193], v[120:123]
	v_mfma_f32_16x16x32_bf16 v[108:111], v[140:143], v[198:201], v[108:111]
	v_mfma_f32_16x16x32_bf16 v[104:107], v[148:151], v[198:201], v[104:107]
	v_mfma_f32_16x16x32_bf16 v[92:95], v[140:143], v[216:219], v[92:95]
	v_mfma_f32_16x16x32_bf16 v[88:91], v[148:151], v[216:219], v[88:91]
	v_mfma_f32_16x16x32_bf16 v[76:79], v[140:143], v[224:227], v[76:79]
	v_mfma_f32_16x16x32_bf16 v[72:75], v[148:151], v[224:227], v[72:75]
	s_setprio 0
	s_setprio 1
	v_mfma_f32_16x16x32_bf16 v[116:119], v[160:163], v[186:189], v[116:119]
	v_mfma_f32_16x16x32_bf16 v[112:115], v[168:171], v[186:189], v[112:115]
	v_mfma_f32_16x16x32_bf16 v[100:103], v[160:163], v[194:197], v[100:103]
	v_mfma_f32_16x16x32_bf16 v[96:99], v[168:171], v[194:197], v[96:99]
	v_mfma_f32_16x16x32_bf16 v[84:87], v[160:163], v[212:215], v[84:87]
	v_mfma_f32_16x16x32_bf16 v[80:83], v[168:171], v[212:215], v[80:83]
	v_mfma_f32_16x16x32_bf16 v[68:71], v[160:163], v[220:223], v[68:71]
	v_mfma_f32_16x16x32_bf16 v[64:67], v[168:171], v[220:223], v[64:67]
	v_mfma_f32_16x16x32_bf16 v[116:119], v[164:167], v[190:193], v[116:119]
	v_mfma_f32_16x16x32_bf16 v[112:115], v[182:185], v[190:193], v[112:115]
	v_mfma_f32_16x16x32_bf16 v[100:103], v[164:167], v[198:201], v[100:103]
	v_mfma_f32_16x16x32_bf16 v[96:99], v[182:185], v[198:201], v[96:99]
	v_mfma_f32_16x16x32_bf16 v[84:87], v[164:167], v[216:219], v[84:87]
	v_mfma_f32_16x16x32_bf16 v[80:83], v[182:185], v[216:219], v[80:83]
	v_mfma_f32_16x16x32_bf16 v[68:71], v[164:167], v[224:227], v[68:71]
	v_mfma_f32_16x16x32_bf16 v[64:67], v[182:185], v[224:227], v[64:67]
	s_barrier
	s_setprio 0
	s_add_i32 s21, s66, s55
	v_lshl_add_u64 v[178:179], s[42:43], 0, v[130:131]
	s_mov_b32 m0, s21
	s_nop 0
	global_load_lds_dwordx4 v[178:179], off
	ds_read_b128 v[186:189], v158 offset:16384
	ds_read_b128 v[190:193], v158 offset:17408
	ds_read_b128 v[194:197], v158 offset:18432
	ds_read_b128 v[198:201], v158 offset:19456
	s_add_i32 m0, s21, 0x2000
	s_add_u32 s64, s42, 0x80000
	v_lshl_add_u64 v[178:179], s[42:43], 0, v[134:135]
	s_addc_u32 s65, s43, 0
	s_add_i32 s21, s67, s55
	global_load_lds_dwordx4 v[178:179], off
	ds_read_b128 v[212:215], v158 offset:20480
	ds_read_b128 v[216:219], v158 offset:21504
	ds_read_b128 v[220:223], v158 offset:22528
	ds_read_b128 v[224:227], v158 offset:23552
	v_lshl_add_u64 v[178:179], s[64:65], 0, v[130:131]
	s_mov_b32 m0, s21
	s_nop 0
	global_load_lds_dwordx4 v[178:179], off
	v_lshl_add_u64 v[178:179], s[64:65], 0, v[134:135]
	s_add_i32 m0, s21, 0x2000
	s_nop 0
	global_load_lds_dwordx4 v[178:179], off
	v_lshl_add_u64 v[178:179], s[46:47], 0, v[128:129]
	s_mov_b32 m0, s56
	s_nop 0
	global_load_lds_dwordx4 v[178:179], off
	v_lshl_add_u64 v[178:179], s[46:47], 0, v[132:133]
	s_mov_b32 m0, s57
	s_nop 0
	global_load_lds_dwordx4 v[178:179], off
	s_waitcnt vmcnt(8)
	s_waitcnt lgkmcnt(0)
	s_setprio 1
	s_barrier
; #define PG8_STAGE(bufoff, gbase, voff) do { _Pragma("unroll") for (int _i = 0; _i < 2; ++_i) \
;         __builtin_amdgcn_global_load_lds((const unsigned*)((const char*)(gbase) + (voff)[_i]), (PG8_LAS unsigned*)(lds + (bufoff) + ldsw + _i * 8192), 16, 0, 0); } while (0)
; #define PG8_LDA(dst, b, h) do { _Pragma("unroll") for (int m = 0; m < 4; ++m) _Pragma("unroll") for (int k = 0; k < 2; ++k) dst[m][k] = *(const PG8_LAS bf16x8*)(lds + PG8_SA(b, h) + aoff + m * 2048 + k * 1024); } while (0)
; #define PG8_LDB(dst, b, h) do { _Pragma("unroll") for (int n = 0; n < 2; ++n) _Pragma("unroll") for (int k = 0; k < 2; ++k) dst[n][k] = *(const PG8_LAS bf16x8*)(lds + PG8_SB(b, h) + boff + n * 2048 + k * 1024); } while (0)
; #define PG8_MMA(ai, bj, At, Bt) do { __builtin_amdgcn_s_setprio(1); _Pragma("unroll") for (int m = 0; m < 4; ++m) _Pragma("unroll") for (int n = 0; n < 2; ++n) _Pragma("unroll") for (int k = 0; k < 2; ++k) \
;         acc[ai][bj][m][n] = __builtin_amdgcn_mfma_f32_16x16x32_bf16(Bt[n][k], At[m][k], acc[ai][bj][m][n], 0, 0, 0); __builtin_amdgcn_s_setprio(0); } while (0)
; #define PG8_WAIT_V(n) asm volatile("s_waitcnt vmcnt(" #n ")" ::: "memory")
; #define PG8_WAIT_L(n) asm volatile("s_waitcnt lgkmcnt(" #n ")" ::: "memory")
; #define PG8_BAR __builtin_amdgcn_s_barrier()
; #define PG8_SCHED __builtin_amdgcn_sched_barrier(0)
; template <class Epi, class Sched, bool ALIGN_EPI = false, bool SP2 = false>
; __device__ __forceinline__ void gemm_phase(PG8_LAS unsigned char* lds, const Gemm g, const Sched& S, const Epi& E) {
;     ...
;             PG8_WAIT_V(8); PG8_WAIT_L(0); PG8_BAR; PG8_MMA(1, 0, At, B0); PG8_MMA(1, 1, At, B1); PG8_BAR; PG8_SCHED;
;             PG8_LDB(B0, 1, 0); PG8_LDB(B1, 1, 1); PG8_SCHED; PG8_LDA(At, 1, 0); PG8_STAGE(PG8_SA(0, 1), a2 + hstep, voffA);
;             PG8_WAIT_V(8); PG8_WAIT_L(0); PG8_BAR; PG8_MMA(0, 0, At, B0); PG8_MMA(0, 1, At, B1); PG8_BAR; PG8_SCHED;
	v_mfma_f32_16x16x32_bf16 v[60:63], v[136:139], v[186:189], v[60:63]
	v_mfma_f32_16x16x32_bf16 v[56:59], v[144:147], v[186:189], v[56:59]
	v_mfma_f32_16x16x32_bf16 v[44:47], v[136:139], v[194:197], v[44:47]
	v_mfma_f32_16x16x32_bf16 v[40:43], v[144:147], v[194:197], v[40:43]
	v_mfma_f32_16x16x32_bf16 v[28:31], v[136:139], v[212:215], v[28:31]
	v_mfma_f32_16x16x32_bf16 v[24:27], v[144:147], v[212:215], v[24:27]
	v_mfma_f32_16x16x32_bf16 v[12:15], v[136:139], v[220:223], v[12:15]
	v_mfma_f32_16x16x32_bf16 v[4:7], v[144:147], v[220:223], v[4:7]
	v_mfma_f32_16x16x32_bf16 v[60:63], v[140:143], v[190:193], v[60:63]
	v_mfma_f32_16x16x32_bf16 v[56:59], v[148:151], v[190:193], v[56:59]
	v_mfma_f32_16x16x32_bf16 v[44:47], v[140:143], v[198:201], v[44:47]
	v_mfma_f32_16x16x32_bf16 v[40:43], v[148:151], v[198:201], v[40:43]
	v_mfma_f32_16x16x32_bf16 v[28:31], v[140:143], v[216:219], v[28:31]
	v_mfma_f32_16x16x32_bf16 v[24:27], v[148:151], v[216:219], v[24:27]
	v_mfma_f32_16x16x32_bf16 v[12:15], v[140:143], v[224:227], v[12:15]
	v_mfma_f32_16x16x32_bf16 v[4:7], v[148:151], v[224:227], v[4:7]
	s_setprio 0
	s_setprio 1
	v_mfma_f32_16x16x32_bf16 v[52:55], v[160:163], v[186:189], v[52:55]
	v_mfma_f32_16x16x32_bf16 v[48:51], v[168:171], v[186:189], v[48:51]
	v_mfma_f32_16x16x32_bf16 v[36:39], v[160:163], v[194:197], v[36:39]
	v_mfma_f32_16x16x32_bf16 v[32:35], v[168:171], v[194:197], v[32:35]
	v_mfma_f32_16x16x32_bf16 v[20:23], v[160:163], v[212:215], v[20:23]
	v_mfma_f32_16x16x32_bf16 v[16:19], v[168:171], v[212:215], v[16:19]
	v_mfma_f32_16x16x32_bf16 v[8:11], v[160:163], v[220:223], v[8:11]
	v_mfma_f32_16x16x32_bf16 v[0:3], v[168:171], v[220:223], v[0:3]
	v_mfma_f32_16x16x32_bf16 v[52:55], v[164:167], v[190:193], v[52:55]
	v_mfma_f32_16x16x32_bf16 v[48:51], v[182:185], v[190:193], v[48:51]
	v_mfma_f32_16x16x32_bf16 v[36:39], v[164:167], v[198:201], v[36:39]
	v_mfma_f32_16x16x32_bf16 v[32:35], v[182:185], v[198:201], v[32:35]
	v_mfma_f32_16x16x32_bf16 v[20:23], v[164:167], v[216:219], v[20:23]
	v_mfma_f32_16x16x32_bf16 v[16:19], v[182:185], v[216:219], v[16:19]
	v_mfma_f32_16x16x32_bf16 v[8:11], v[164:167], v[224:227], v[8:11]
	v_mfma_f32_16x16x32_bf16 v[0:3], v[182:185], v[224:227], v[0:3]
	s_barrier
	s_setprio 0
	s_add_i32 s21, 0, 0x18000
	s_add_i32 s64, 0, 0x1c000
	v_add_u32_e32 v148, s21, v155
	v_add_u32_e32 v152, s64, v155
	ds_read_b128 v[136:139], v148
	ds_read_b128 v[140:143], v148 offset:1024
	ds_read_b128 v[144:147], v148 offset:2048
	ds_read_b128 v[148:151], v148 offset:3072
	ds_read_b128 v[160:163], v152
	ds_read_b128 v[164:167], v152 offset:1024
	ds_read_b128 v[168:171], v152 offset:2048
	ds_read_b128 v[182:185], v152 offset:3072
	s_add_u32 s46, s46, 0x80000
	s_addc_u32 s47, s47, 0
	s_mov_b32 m0, s58
	v_lshl_add_u64 v[178:179], s[46:47], 0, v[128:129]
	ds_read_b128 v[186:189], v158 offset:32768
	ds_read_b128 v[190:193], v158 offset:33792
	ds_read_b128 v[194:197], v158 offset:34816
	ds_read_b128 v[198:201], v158 offset:35840
	ds_read_b128 v[212:215], v158 offset:36864
	ds_read_b128 v[216:219], v158 offset:37888
	ds_read_b128 v[220:223], v158 offset:38912
	ds_read_b128 v[224:227], v158 offset:39936
	global_load_lds_dwordx4 v[178:179], off
	v_lshl_add_u64 v[178:179], s[46:47], 0, v[132:133]
	s_mov_b32 m0, s59
	s_nop 0
	global_load_lds_dwordx4 v[178:179], off
	s_waitcnt vmcnt(8)
	s_waitcnt lgkmcnt(0)
	s_setprio 1
	s_barrier
	v_mfma_f32_16x16x32_bf16 v[124:127], v[136:139], v[186:189], v[124:127]
	v_mfma_f32_16x16x32_bf16 v[120:123], v[144:147], v[186:189], v[120:123]
	v_mfma_f32_16x16x32_bf16 v[108:111], v[136:139], v[194:197], v[108:111]
	v_mfma_f32_16x16x32_bf16 v[104:107], v[144:147], v[194:197], v[104:107]
	v_mfma_f32_16x16x32_bf16 v[92:95], v[136:139], v[212:215], v[92:95]
	v_mfma_f32_16x16x32_bf16 v[88:91], v[144:147], v[212:215], v[88:91]
	v_mfma_f32_16x16x32_bf16 v[76:79], v[136:139], v[220:223], v[76:79]
	v_mfma_f32_16x16x32_bf16 v[72:75], v[144:147], v[220:223], v[72:75]
	v_mfma_f32_16x16x32_bf16 v[124:127], v[140:143], v[190:193], v[124:127]
	v_mfma_f32_16x16x32_bf16 v[120:123], v[148:151], v[190:193], v[120:123]
	v_mfma_f32_16x16x32_bf16 v[108:111], v[140:143], v[198:201], v[108:111]
	v_mfma_f32_16x16x32_bf16 v[104:107], v[148:151], v[198:201], v[104:107]
	v_mfma_f32_16x16x32_bf16 v[92:95], v[140:143], v[216:219], v[92:95]
	v_mfma_f32_16x16x32_bf16 v[88:91], v[148:151], v[216:219], v[88:91]
	v_mfma_f32_16x16x32_bf16 v[76:79], v[140:143], v[224:227], v[76:79]
	v_mfma_f32_16x16x32_bf16 v[72:75], v[148:151], v[224:227], v[72:75]
	s_setprio 0
	s_setprio 1
	v_mfma_f32_16x16x32_bf16 v[116:119], v[160:163], v[186:189], v[116:119]
	v_mfma_f32_16x16x32_bf16 v[112:115], v[168:171], v[186:189], v[112:115]
	v_mfma_f32_16x16x32_bf16 v[100:103], v[160:163], v[194:197], v[100:103]
	v_mfma_f32_16x16x32_bf16 v[96:99], v[168:171], v[194:197], v[96:99]
	v_mfma_f32_16x16x32_bf16 v[84:87], v[160:163], v[212:215], v[84:87]
	v_mfma_f32_16x16x32_bf16 v[80:83], v[168:171], v[212:215], v[80:83]
	v_mfma_f32_16x16x32_bf16 v[68:71], v[160:163], v[220:223], v[68:71]
	v_mfma_f32_16x16x32_bf16 v[64:67], v[168:171], v[220:223], v[64:67]
	v_mfma_f32_16x16x32_bf16 v[116:119], v[164:167], v[190:193], v[116:119]
	v_mfma_f32_16x16x32_bf16 v[112:115], v[182:185], v[190:193], v[112:115]
	v_mfma_f32_16x16x32_bf16 v[100:103], v[164:167], v[198:201], v[100:103]
	v_mfma_f32_16x16x32_bf16 v[96:99], v[182:185], v[198:201], v[96:99]
	v_mfma_f32_16x16x32_bf16 v[84:87], v[164:167], v[216:219], v[84:87]
	v_mfma_f32_16x16x32_bf16 v[80:83], v[182:185], v[216:219], v[80:83]
	v_mfma_f32_16x16x32_bf16 v[68:71], v[164:167], v[224:227], v[68:71]
	v_mfma_f32_16x16x32_bf16 v[64:67], v[182:185], v[224:227], v[64:67]
	s_barrier
; #define PG8_STAGE(bufoff, gbase, voff) do { _Pragma("unroll") for (int _i = 0; _i < 2; ++_i) \
;         __builtin_amdgcn_global_load_lds((const unsigned*)((const char*)(gbase) + (voff)[_i]), (PG8_LAS unsigned*)(lds + (bufoff) + ldsw + _i * 8192), 16, 0, 0); } while (0)
; #define PG8_LDA(dst, b, h) do { _Pragma("unroll") for (int m = 0; m < 4; ++m) _Pragma("unroll") for (int k = 0; k < 2; ++k) dst[m][k] = *(const PG8_LAS bf16x8*)(lds + PG8_SA(b, h) + aoff + m * 2048 + k * 1024); } while (0)
; #define PG8_MMA(ai, bj, At, Bt) do { __builtin_amdgcn_s_setprio(1); _Pragma("unroll") for (int m = 0; m < 4; ++m) _Pragma("unroll") for (int n = 0; n < 2; ++n) _Pragma("unroll") for (int k = 0; k < 2; ++k) \
;         acc[ai][bj][m][n] = __builtin_amdgcn_mfma_f32_16x16x32_bf16(Bt[n][k], At[m][k], acc[ai][bj][m][n], 0, 0, 0); __builtin_amdgcn_s_setprio(0); } while (0)
; #define PG8_WAIT_V(n) asm volatile("s_waitcnt vmcnt(" #n ")" ::: "memory")
; #define PG8_WAIT_L(n) asm volatile("s_waitcnt lgkmcnt(" #n ")" ::: "memory")
; #define PG8_BAR __builtin_amdgcn_s_barrier()
; #define PG8_SCHED __builtin_amdgcn_sched_barrier(0)
; template <class Epi, class Sched, bool ALIGN_EPI = false, bool SP2 = false>
; __device__ __forceinline__ void gemm_phase(PG8_LAS unsigned char* lds, const Gemm g, const Sched& S, const Epi& E) {
;     ...
;             PG8_LDA(At, 1, 1); PG8_STAGE(PG8_SB(1, 0), b3, voffB); PG8_STAGE(PG8_SB(1, 1), b3 + hstep, voffB); PG8_STAGE(PG8_SA(1, 0), a3, voffA);
;             PG8_WAIT_V(8); PG8_WAIT_L(0); PG8_BAR; PG8_MMA(1, 0, At, B0); PG8_MMA(1, 1, At, B1); PG8_BAR; PG8_SCHED;
	s_setprio 0
	s_add_u32 s42, s42, s44
	s_addc_u32 s43, s43, s45
	s_add_i32 s21, s21, s55
	v_lshl_add_u64 v[178:179], s[42:43], 0, v[130:131]
	s_mov_b32 m0, s21
	s_nop 0
	global_load_lds_dwordx4 v[178:179], off
	ds_read_b128 v[186:189], v158 offset:49152
	ds_read_b128 v[190:193], v158 offset:50176
	ds_read_b128 v[194:197], v158 offset:51200
	ds_read_b128 v[198:201], v158 offset:52224
	s_add_i32 m0, s21, 0x2000
	v_lshl_add_u64 v[178:179], s[42:43], 0, v[134:135]
	s_add_u32 s42, s42, 0x80000
	s_addc_u32 s43, s43, 0
	s_add_i32 s21, s64, s55
	global_load_lds_dwordx4 v[178:179], off
	ds_read_b128 v[212:215], v158 offset:53248
	ds_read_b128 v[216:219], v158 offset:54272
	ds_read_b128 v[220:223], v158 offset:55296
	ds_read_b128 v[224:227], v158 offset:56320
	v_lshl_add_u64 v[178:179], s[42:43], 0, v[130:131]
	s_mov_b32 m0, s21
	s_nop 0
	global_load_lds_dwordx4 v[178:179], off
	v_lshl_add_u64 v[178:179], s[42:43], 0, v[134:135]
	s_add_i32 m0, s21, 0x2000
	s_nop 0
	global_load_lds_dwordx4 v[178:179], off
	v_lshl_add_u64 v[178:179], s[48:49], 0, v[128:129]
	s_mov_b32 m0, s60
	s_nop 0
	global_load_lds_dwordx4 v[178:179], off
	v_lshl_add_u64 v[178:179], s[48:49], 0, v[132:133]
	s_mov_b32 m0, s61
	s_nop 0
	global_load_lds_dwordx4 v[178:179], off
	s_waitcnt vmcnt(8)
	s_waitcnt lgkmcnt(0)
	s_setprio 1
	s_barrier
	v_mfma_f32_16x16x32_bf16 v[60:63], v[136:139], v[186:189], v[60:63]
	v_mfma_f32_16x16x32_bf16 v[56:59], v[144:147], v[186:189], v[56:59]
	v_mfma_f32_16x16x32_bf16 v[44:47], v[136:139], v[194:197], v[44:47]
	v_mfma_f32_16x16x32_bf16 v[40:43], v[144:147], v[194:197], v[40:43]
	v_mfma_f32_16x16x32_bf16 v[28:31], v[136:139], v[212:215], v[28:31]
	v_mfma_f32_16x16x32_bf16 v[24:27], v[144:147], v[212:215], v[24:27]
	v_mfma_f32_16x16x32_bf16 v[12:15], v[136:139], v[220:223], v[12:15]
	v_mfma_f32_16x16x32_bf16 v[4:7], v[144:147], v[220:223], v[4:7]
	v_mfma_f32_16x16x32_bf16 v[60:63], v[140:143], v[190:193], v[60:63]
	v_mfma_f32_16x16x32_bf16 v[56:59], v[148:151], v[190:193], v[56:59]
	v_mfma_f32_16x16x32_bf16 v[44:47], v[140:143], v[198:201], v[44:47]
	v_mfma_f32_16x16x32_bf16 v[40:43], v[148:151], v[198:201], v[40:43]
	v_mfma_f32_16x16x32_bf16 v[28:31], v[140:143], v[216:219], v[28:31]
	v_mfma_f32_16x16x32_bf16 v[24:27], v[148:151], v[216:219], v[24:27]
	v_mfma_f32_16x16x32_bf16 v[12:15], v[140:143], v[224:227], v[12:15]
	v_mfma_f32_16x16x32_bf16 v[4:7], v[148:151], v[224:227], v[4:7]
	s_setprio 0
	s_setprio 1
	v_mfma_f32_16x16x32_bf16 v[52:55], v[160:163], v[186:189], v[52:55]
	v_mfma_f32_16x16x32_bf16 v[48:51], v[168:171], v[186:189], v[48:51]
	v_mfma_f32_16x16x32_bf16 v[36:39], v[160:163], v[194:197], v[36:39]
	v_mfma_f32_16x16x32_bf16 v[32:35], v[168:171], v[194:197], v[32:35]
	v_mfma_f32_16x16x32_bf16 v[20:23], v[160:163], v[212:215], v[20:23]
	v_mfma_f32_16x16x32_bf16 v[16:19], v[168:171], v[212:215], v[16:19]
	v_mfma_f32_16x16x32_bf16 v[8:11], v[160:163], v[220:223], v[8:11]
	v_mfma_f32_16x16x32_bf16 v[0:3], v[168:171], v[220:223], v[0:3]
	v_mfma_f32_16x16x32_bf16 v[52:55], v[164:167], v[190:193], v[52:55]
	v_mfma_f32_16x16x32_bf16 v[48:51], v[182:185], v[190:193], v[48:51]
	v_mfma_f32_16x16x32_bf16 v[36:39], v[164:167], v[198:201], v[36:39]
	v_mfma_f32_16x16x32_bf16 v[32:35], v[182:185], v[198:201], v[32:35]
	v_mfma_f32_16x16x32_bf16 v[20:23], v[164:167], v[216:219], v[20:23]
	v_mfma_f32_16x16x32_bf16 v[16:19], v[182:185], v[216:219], v[16:19]
	v_mfma_f32_16x16x32_bf16 v[8:11], v[164:167], v[224:227], v[8:11]
	v_mfma_f32_16x16x32_bf16 v[0:3], v[182:185], v[224:227], v[0:3]
	s_barrier
	s_setprio 0
	s_cmp_gt_u32 s1, 29
	s_mov_b32 s1, s19
	s_cbranch_scc1 .LBB0_419

; #define PG8_STAGE(bufoff, gbase, voff) do { _Pragma("unroll") for (int _i = 0; _i < 2; ++_i) \
;         __builtin_amdgcn_global_load_lds((const unsigned*)((const char*)(gbase) + (voff)[_i]), (PG8_LAS unsigned*)(lds + (bufoff) + ldsw + _i * 8192), 16, 0, 0); } while (0)
; #define PG8_LDA(dst, b, h) do { _Pragma("unroll") for (int m = 0; m < 4; ++m) _Pragma("unroll") for (int k = 0; k < 2; ++k) dst[m][k] = *(const PG8_LAS bf16x8*)(lds + PG8_SA(b, h) + aoff + m * 2048 + k * 1024); } while (0)
; #define PG8_LDB(dst, b, h) do { _Pragma("unroll") for (int n = 0; n < 2; ++n) _Pragma("unroll") for (int k = 0; k < 2; ++k) dst[n][k] = *(const PG8_LAS bf16x8*)(lds + PG8_SB(b, h) + boff + n * 2048 + k * 1024); } while (0)
; #define PG8_MMA(ai, bj, At, Bt) do { __builtin_amdgcn_s_setprio(1); _Pragma("unroll") for (int m = 0; m < 4; ++m) _Pragma("unroll") for (int n = 0; n < 2; ++n) _Pragma("unroll") for (int k = 0; k < 2; ++k) \
;         acc[ai][bj][m][n] = __builtin_amdgcn_mfma_f32_16x16x32_bf16(Bt[n][k], At[m][k], acc[ai][bj][m][n], 0, 0, 0); __builtin_amdgcn_s_setprio(0); } while (0)
; #define PG8_WAIT_V(n) asm volatile("s_waitcnt vmcnt(" #n ")" ::: "memory")
; #define PG8_BAR __builtin_amdgcn_s_barrier()
; template <class Epi, class Sched, bool ALIGN_EPI = false, bool SP2 = false>
; __device__ __forceinline__ void gemm_phase(PG8_LAS unsigned char* lds, const Gemm g, const Sched& S, const Epi& E) {
;     ...
;         for (int t = 0; t < nt; t += 2) {
;             const bool last = (t == nt - 2);
;             const char* a1 = cA + (long)(t + 1) * st;
;             const char* a2 = last ? nA : cA + (long)(t + 2) * st; const char* b2 = last ? nB : cB + (long)(t + 2) * st;
;             const long s3 = last ? nst : st; const char* a3 = a2 + s3; const char* b3 = b2 + s3;
;             if (last && has_next) S.a_ready(nxt);
;             if constexpr (SP2) {
;             PG8_LDB(B0, 0, 0); PG8_LDB(B1, 0, 1); PG8_SCHED; PG8_LDA(At, 0, 0); PG8_STAGE(PG8_SA(1, 1), a1 + hstep, voffA);
;             PG8_WAIT_V(8); PG8_WAIT_L(0); PG8_BAR; PG8_MMA(0, 0, At, B0); PG8_MMA(0, 1, At, B1); PG8_BAR; PG8_SCHED;
;             PG8_LDA(At, 0, 1); PG8_STAGE(PG8_SB(0, 0), b2, voffB); PG8_STAGE(PG8_SB(0, 1), b2 + hstep, voffB); PG8_STAGE(PG8_SA(0, 0), a2, voffA);
;             PG8_WAIT_V(8); PG8_WAIT_L(0); PG8_BAR; PG8_MMA(1, 0, At, B0); PG8_MMA(1, 1, At, B1); PG8_BAR; PG8_SCHED;
.LBB0_499:
	s_or_b32 s25, s1, 1
	s_mul_i32 s27, s39, s25
	s_mul_hi_u32 s52, s38, s25
	s_add_i32 s52, s52, s27
	s_mul_i32 s25, s38, s25
	s_add_u32 s25, s36, s25
	s_addc_u32 s27, s37, s52
	s_add_u32 s52, s50, s48
	s_addc_u32 s53, s51, s49
	s_add_i32 s72, 0, 0x10000
	s_add_i32 s75, 0, 0x14000
	v_add_u32_e32 v100, s72, v213
	v_add_u32_e32 v156, s75, v213
	ds_read_b128 v[88:91], v100
	ds_read_b128 v[92:95], v100 offset:1024
	ds_read_b128 v[96:99], v100 offset:2048
	ds_read_b128 v[100:103], v100 offset:3072
	ds_read_b128 v[104:107], v156
	ds_read_b128 v[108:111], v156 offset:1024
	ds_read_b128 v[152:155], v156 offset:2048
	ds_read_b128 v[156:159], v156 offset:3072
	s_add_u32 s68, s25, 0x80000
	s_addc_u32 s69, s27, 0
	v_lshl_add_u64 v[178:179], s[68:69], 0, v[182:183]
	s_add_i32 m0, s60, 0xc000
	ds_read_b128 v[160:163], v215
	ds_read_b128 v[164:167], v215 offset:1024
	ds_read_b128 v[168:171], v215 offset:2048
	ds_read_b128 v[188:191], v215 offset:3072
	ds_read_b128 v[192:195], v215 offset:4096
	ds_read_b128 v[196:199], v215 offset:5120
	ds_read_b128 v[200:203], v215 offset:6144
	ds_read_b128 v[216:219], v215 offset:7168
	global_load_lds_dwordx4 v[178:179], off
	v_lshl_add_u64 v[178:179], s[68:69], 0, v[184:185]
	s_add_i32 m0, s60, 0xe000
	s_nop 0
	global_load_lds_dwordx4 v[178:179], off
	s_waitcnt vmcnt(8)
	s_waitcnt lgkmcnt(0)
	s_setprio 1
	s_barrier
	v_mfma_f32_16x16x32_bf16 v[148:151], v[88:91], v[160:163], v[148:151]
	v_mfma_f32_16x16x32_bf16 v[144:147], v[96:99], v[160:163], v[144:147]
	v_mfma_f32_16x16x32_bf16 v[140:143], v[88:91], v[168:171], v[140:143]
	v_mfma_f32_16x16x32_bf16 v[136:139], v[96:99], v[168:171], v[136:139]
	v_mfma_f32_16x16x32_bf16 v[132:135], v[88:91], v[192:195], v[132:135]
	v_mfma_f32_16x16x32_bf16 v[128:131], v[96:99], v[192:195], v[128:131]
	v_mfma_f32_16x16x32_bf16 v[124:127], v[88:91], v[200:203], v[124:127]
	v_mfma_f32_16x16x32_bf16 v[120:123], v[96:99], v[200:203], v[120:123]
	v_mfma_f32_16x16x32_bf16 v[148:151], v[92:95], v[164:167], v[148:151]
	v_mfma_f32_16x16x32_bf16 v[144:147], v[100:103], v[164:167], v[144:147]
	v_mfma_f32_16x16x32_bf16 v[140:143], v[92:95], v[188:191], v[140:143]
	v_mfma_f32_16x16x32_bf16 v[136:139], v[100:103], v[188:191], v[136:139]
	v_mfma_f32_16x16x32_bf16 v[132:135], v[92:95], v[196:199], v[132:135]
	v_mfma_f32_16x16x32_bf16 v[128:131], v[100:103], v[196:199], v[128:131]
	v_mfma_f32_16x16x32_bf16 v[124:127], v[92:95], v[216:219], v[124:127]
	v_mfma_f32_16x16x32_bf16 v[120:123], v[100:103], v[216:219], v[120:123]
	s_setprio 0
	s_setprio 1
	v_mfma_f32_16x16x32_bf16 v[60:63], v[104:107], v[160:163], v[60:63]
	v_mfma_f32_16x16x32_bf16 v[56:59], v[152:155], v[160:163], v[56:59]
	v_mfma_f32_16x16x32_bf16 v[52:55], v[104:107], v[168:171], v[52:55]
	v_mfma_f32_16x16x32_bf16 v[48:51], v[152:155], v[168:171], v[48:51]
	v_mfma_f32_16x16x32_bf16 v[44:47], v[104:107], v[192:195], v[44:47]
	v_mfma_f32_16x16x32_bf16 v[40:43], v[152:155], v[192:195], v[40:43]
	v_mfma_f32_16x16x32_bf16 v[36:39], v[104:107], v[200:203], v[36:39]
	v_mfma_f32_16x16x32_bf16 v[32:35], v[152:155], v[200:203], v[32:35]
	v_mfma_f32_16x16x32_bf16 v[60:63], v[108:111], v[164:167], v[60:63]
	v_mfma_f32_16x16x32_bf16 v[56:59], v[156:159], v[164:167], v[56:59]
	v_mfma_f32_16x16x32_bf16 v[52:55], v[108:111], v[188:191], v[52:55]
	v_mfma_f32_16x16x32_bf16 v[48:51], v[156:159], v[188:191], v[48:51]
	v_mfma_f32_16x16x32_bf16 v[44:47], v[108:111], v[196:199], v[44:47]
	v_mfma_f32_16x16x32_bf16 v[40:43], v[156:159], v[196:199], v[40:43]
	v_mfma_f32_16x16x32_bf16 v[36:39], v[108:111], v[216:219], v[36:39]
	v_mfma_f32_16x16x32_bf16 v[32:35], v[156:159], v[216:219], v[32:35]
	s_barrier
	s_setprio 0
	s_add_i32 s25, s72, s59
	v_lshl_add_u64 v[178:179], s[46:47], 0, v[172:173]
	s_mov_b32 m0, s25
	s_nop 0
	global_load_lds_dwordx4 v[178:179], off
	ds_read_b128 v[160:163], v215 offset:16384
	ds_read_b128 v[164:167], v215 offset:17408
	ds_read_b128 v[168:171], v215 offset:18432
	ds_read_b128 v[188:191], v215 offset:19456
	s_add_i32 m0, s25, 0x2000
	s_add_u32 s68, s46, 0x80000
	v_lshl_add_u64 v[178:179], s[46:47], 0, v[186:187]
	s_addc_u32 s69, s47, 0
	s_add_i32 s25, s75, s59
	global_load_lds_dwordx4 v[178:179], off
	ds_read_b128 v[192:195], v215 offset:20480
	ds_read_b128 v[196:199], v215 offset:21504
	ds_read_b128 v[200:203], v215 offset:22528
	ds_read_b128 v[216:219], v215 offset:23552
	v_lshl_add_u64 v[178:179], s[68:69], 0, v[172:173]
	s_mov_b32 m0, s25
	s_nop 0
	global_load_lds_dwordx4 v[178:179], off
	v_lshl_add_u64 v[178:179], s[68:69], 0, v[186:187]
	s_add_i32 m0, s25, 0x2000
	s_nop 0
	global_load_lds_dwordx4 v[178:179], off
	v_lshl_add_u64 v[178:179], s[50:51], 0, v[182:183]
	s_mov_b32 m0, s60
	s_nop 0
	global_load_lds_dwordx4 v[178:179], off
	v_lshl_add_u64 v[178:179], s[50:51], 0, v[184:185]
	s_mov_b32 m0, s61
	s_nop 0
	global_load_lds_dwordx4 v[178:179], off
	s_waitcnt vmcnt(8)
	s_waitcnt lgkmcnt(0)
	s_setprio 1
	s_barrier
; #define PG8_STAGE(bufoff, gbase, voff) do { _Pragma("unroll") for (int _i = 0; _i < 2; ++_i) \
;         __builtin_amdgcn_global_load_lds((const unsigned*)((const char*)(gbase) + (voff)[_i]), (PG8_LAS unsigned*)(lds + (bufoff) + ldsw + _i * 8192), 16, 0, 0); } while (0)
; #define PG8_LDA(dst, b, h) do { _Pragma("unroll") for (int m = 0; m < 4; ++m) _Pragma("unroll") for (int k = 0; k < 2; ++k) dst[m][k] = *(const PG8_LAS bf16x8*)(lds + PG8_SA(b, h) + aoff + m * 2048 + k * 1024); } while (0)
; #define PG8_LDB(dst, b, h) do { _Pragma("unroll") for (int n = 0; n < 2; ++n) _Pragma("unroll") for (int k = 0; k < 2; ++k) dst[n][k] = *(const PG8_LAS bf16x8*)(lds + PG8_SB(b, h) + boff + n * 2048 + k * 1024); } while (0)
; #define PG8_MMA(ai, bj, At, Bt) do { __builtin_amdgcn_s_setprio(1); _Pragma("unroll") for (int m = 0; m < 4; ++m) _Pragma("unroll") for (int n = 0; n < 2; ++n) _Pragma("unroll") for (int k = 0; k < 2; ++k) \
;         acc[ai][bj][m][n] = __builtin_amdgcn_mfma_f32_16x16x32_bf16(Bt[n][k], At[m][k], acc[ai][bj][m][n], 0, 0, 0); __builtin_amdgcn_s_setprio(0); } while (0)
; #define PG8_WAIT_V(n) asm volatile("s_waitcnt vmcnt(" #n ")" ::: "memory")
; #define PG8_WAIT_L(n) asm volatile("s_waitcnt lgkmcnt(" #n ")" ::: "memory")
; #define PG8_BAR __builtin_amdgcn_s_barrier()
; #define PG8_SCHED __builtin_amdgcn_sched_barrier(0)
; template <class Epi, class Sched, bool ALIGN_EPI = false, bool SP2 = false>
; __device__ __forceinline__ void gemm_phase(PG8_LAS unsigned char* lds, const Gemm g, const Sched& S, const Epi& E) {
;     ...
;             PG8_WAIT_V(8); PG8_WAIT_L(0); PG8_BAR; PG8_MMA(1, 0, At, B0); PG8_MMA(1, 1, At, B1); PG8_BAR; PG8_SCHED;
;             PG8_LDB(B0, 1, 0); PG8_LDB(B1, 1, 1); PG8_SCHED; PG8_LDA(At, 1, 0); PG8_STAGE(PG8_SA(0, 1), a2 + hstep, voffA);
;             PG8_WAIT_V(8); PG8_WAIT_L(0); PG8_BAR; PG8_MMA(0, 0, At, B0); PG8_MMA(0, 1, At, B1); PG8_BAR; PG8_SCHED;
	v_mfma_f32_16x16x32_bf16 v[116:119], v[88:91], v[160:163], v[116:119]
	v_mfma_f32_16x16x32_bf16 v[112:115], v[96:99], v[160:163], v[112:115]
	v_mfma_f32_16x16x32_bf16 v[84:87], v[88:91], v[168:171], v[84:87]
	v_mfma_f32_16x16x32_bf16 v[80:83], v[96:99], v[168:171], v[80:83]
	v_mfma_f32_16x16x32_bf16 v[76:79], v[88:91], v[192:195], v[76:79]
	v_mfma_f32_16x16x32_bf16 v[72:75], v[96:99], v[192:195], v[72:75]
	v_mfma_f32_16x16x32_bf16 v[68:71], v[88:91], v[200:203], v[68:71]
	v_mfma_f32_16x16x32_bf16 v[64:67], v[96:99], v[200:203], v[64:67]
	v_mfma_f32_16x16x32_bf16 v[116:119], v[92:95], v[164:167], v[116:119]
	v_mfma_f32_16x16x32_bf16 v[112:115], v[100:103], v[164:167], v[112:115]
	v_mfma_f32_16x16x32_bf16 v[84:87], v[92:95], v[188:191], v[84:87]
	v_mfma_f32_16x16x32_bf16 v[80:83], v[100:103], v[188:191], v[80:83]
	v_mfma_f32_16x16x32_bf16 v[76:79], v[92:95], v[196:199], v[76:79]
	v_mfma_f32_16x16x32_bf16 v[72:75], v[100:103], v[196:199], v[72:75]
	v_mfma_f32_16x16x32_bf16 v[68:71], v[92:95], v[216:219], v[68:71]
	v_mfma_f32_16x16x32_bf16 v[64:67], v[100:103], v[216:219], v[64:67]
	s_setprio 0
	s_setprio 1
	v_mfma_f32_16x16x32_bf16 v[28:31], v[104:107], v[160:163], v[28:31]
	v_mfma_f32_16x16x32_bf16 v[24:27], v[152:155], v[160:163], v[24:27]
	v_mfma_f32_16x16x32_bf16 v[20:23], v[104:107], v[168:171], v[20:23]
	v_mfma_f32_16x16x32_bf16 v[16:19], v[152:155], v[168:171], v[16:19]
	v_mfma_f32_16x16x32_bf16 v[12:15], v[104:107], v[192:195], v[12:15]
	v_mfma_f32_16x16x32_bf16 v[8:11], v[152:155], v[192:195], v[8:11]
	v_mfma_f32_16x16x32_bf16 v[4:7], v[104:107], v[200:203], v[4:7]
	v_mfma_f32_16x16x32_bf16 v[0:3], v[152:155], v[200:203], v[0:3]
	v_mfma_f32_16x16x32_bf16 v[28:31], v[108:111], v[164:167], v[28:31]
	v_mfma_f32_16x16x32_bf16 v[24:27], v[156:159], v[164:167], v[24:27]
	v_mfma_f32_16x16x32_bf16 v[20:23], v[108:111], v[188:191], v[20:23]
	v_mfma_f32_16x16x32_bf16 v[16:19], v[156:159], v[188:191], v[16:19]
	v_mfma_f32_16x16x32_bf16 v[12:15], v[108:111], v[196:199], v[12:15]
	v_mfma_f32_16x16x32_bf16 v[8:11], v[156:159], v[196:199], v[8:11]
	v_mfma_f32_16x16x32_bf16 v[4:7], v[108:111], v[216:219], v[4:7]
	v_mfma_f32_16x16x32_bf16 v[0:3], v[156:159], v[216:219], v[0:3]
	s_barrier
	s_setprio 0
	s_add_i32 s25, 0, 0x18000
	s_add_i32 s27, 0, 0x1c000
	v_add_u32_e32 v100, s25, v213
	v_add_u32_e32 v156, s27, v213
	ds_read_b128 v[88:91], v100
	ds_read_b128 v[92:95], v100 offset:1024
	ds_read_b128 v[96:99], v100 offset:2048
	ds_read_b128 v[100:103], v100 offset:3072
	ds_read_b128 v[104:107], v156
	ds_read_b128 v[108:111], v156 offset:1024
	ds_read_b128 v[152:155], v156 offset:2048
	ds_read_b128 v[156:159], v156 offset:3072
	s_add_u32 s50, s50, 0x80000
	s_addc_u32 s51, s51, 0
	s_mov_b32 m0, s62
	v_lshl_add_u64 v[178:179], s[50:51], 0, v[182:183]
	ds_read_b128 v[160:163], v215 offset:32768
	ds_read_b128 v[164:167], v215 offset:33792
	ds_read_b128 v[168:171], v215 offset:34816
	ds_read_b128 v[188:191], v215 offset:35840
	ds_read_b128 v[192:195], v215 offset:36864
	ds_read_b128 v[196:199], v215 offset:37888
	ds_read_b128 v[200:203], v215 offset:38912
	ds_read_b128 v[216:219], v215 offset:39936
	global_load_lds_dwordx4 v[178:179], off
	v_lshl_add_u64 v[178:179], s[50:51], 0, v[184:185]
	s_mov_b32 m0, s63
	s_nop 0
	global_load_lds_dwordx4 v[178:179], off
	s_waitcnt vmcnt(8)
	s_waitcnt lgkmcnt(0)
	s_setprio 1
	s_barrier
	v_mfma_f32_16x16x32_bf16 v[148:151], v[88:91], v[160:163], v[148:151]
	v_mfma_f32_16x16x32_bf16 v[144:147], v[96:99], v[160:163], v[144:147]
	v_mfma_f32_16x16x32_bf16 v[140:143], v[88:91], v[168:171], v[140:143]
	v_mfma_f32_16x16x32_bf16 v[136:139], v[96:99], v[168:171], v[136:139]
	v_mfma_f32_16x16x32_bf16 v[132:135], v[88:91], v[192:195], v[132:135]
	v_mfma_f32_16x16x32_bf16 v[128:131], v[96:99], v[192:195], v[128:131]
	v_mfma_f32_16x16x32_bf16 v[124:127], v[88:91], v[200:203], v[124:127]
	v_mfma_f32_16x16x32_bf16 v[120:123], v[96:99], v[200:203], v[120:123]
	v_mfma_f32_16x16x32_bf16 v[148:151], v[92:95], v[164:167], v[148:151]
	v_mfma_f32_16x16x32_bf16 v[144:147], v[100:103], v[164:167], v[144:147]
	v_mfma_f32_16x16x32_bf16 v[140:143], v[92:95], v[188:191], v[140:143]
	v_mfma_f32_16x16x32_bf16 v[136:139], v[100:103], v[188:191], v[136:139]
	v_mfma_f32_16x16x32_bf16 v[132:135], v[92:95], v[196:199], v[132:135]
	v_mfma_f32_16x16x32_bf16 v[128:131], v[100:103], v[196:199], v[128:131]
	v_mfma_f32_16x16x32_bf16 v[124:127], v[92:95], v[216:219], v[124:127]
	v_mfma_f32_16x16x32_bf16 v[120:123], v[100:103], v[216:219], v[120:123]
	s_setprio 0
	s_setprio 1
	v_mfma_f32_16x16x32_bf16 v[60:63], v[104:107], v[160:163], v[60:63]
	v_mfma_f32_16x16x32_bf16 v[56:59], v[152:155], v[160:163], v[56:59]
	v_mfma_f32_16x16x32_bf16 v[52:55], v[104:107], v[168:171], v[52:55]
	v_mfma_f32_16x16x32_bf16 v[48:51], v[152:155], v[168:171], v[48:51]
	v_mfma_f32_16x16x32_bf16 v[44:47], v[104:107], v[192:195], v[44:47]
	v_mfma_f32_16x16x32_bf16 v[40:43], v[152:155], v[192:195], v[40:43]
	v_mfma_f32_16x16x32_bf16 v[36:39], v[104:107], v[200:203], v[36:39]
	v_mfma_f32_16x16x32_bf16 v[32:35], v[152:155], v[200:203], v[32:35]
	v_mfma_f32_16x16x32_bf16 v[60:63], v[108:111], v[164:167], v[60:63]
	v_mfma_f32_16x16x32_bf16 v[56:59], v[156:159], v[164:167], v[56:59]
	v_mfma_f32_16x16x32_bf16 v[52:55], v[108:111], v[188:191], v[52:55]
	v_mfma_f32_16x16x32_bf16 v[48:51], v[156:159], v[188:191], v[48:51]
	v_mfma_f32_16x16x32_bf16 v[44:47], v[108:111], v[196:199], v[44:47]
	v_mfma_f32_16x16x32_bf16 v[40:43], v[156:159], v[196:199], v[40:43]
	v_mfma_f32_16x16x32_bf16 v[36:39], v[108:111], v[216:219], v[36:39]
	v_mfma_f32_16x16x32_bf16 v[32:35], v[156:159], v[216:219], v[32:35]
	s_barrier
; #define PG8_STAGE(bufoff, gbase, voff) do { _Pragma("unroll") for (int _i = 0; _i < 2; ++_i) \
;         __builtin_amdgcn_global_load_lds((const unsigned*)((const char*)(gbase) + (voff)[_i]), (PG8_LAS unsigned*)(lds + (bufoff) + ldsw + _i * 8192), 16, 0, 0); } while (0)
; #define PG8_LDA(dst, b, h) do { _Pragma("unroll") for (int m = 0; m < 4; ++m) _Pragma("unroll") for (int k = 0; k < 2; ++k) dst[m][k] = *(const PG8_LAS bf16x8*)(lds + PG8_SA(b, h) + aoff + m * 2048 + k * 1024); } while (0)
; #define PG8_MMA(ai, bj, At, Bt) do { __builtin_amdgcn_s_setprio(1); _Pragma("unroll") for (int m = 0; m < 4; ++m) _Pragma("unroll") for (int n = 0; n < 2; ++n) _Pragma("unroll") for (int k = 0; k < 2; ++k) \
;         acc[ai][bj][m][n] = __builtin_amdgcn_mfma_f32_16x16x32_bf16(Bt[n][k], At[m][k], acc[ai][bj][m][n], 0, 0, 0); __builtin_amdgcn_s_setprio(0); } while (0)
; #define PG8_WAIT_V(n) asm volatile("s_waitcnt vmcnt(" #n ")" ::: "memory")
; #define PG8_WAIT_L(n) asm volatile("s_waitcnt lgkmcnt(" #n ")" ::: "memory")
; #define PG8_BAR __builtin_amdgcn_s_barrier()
; #define PG8_SCHED __builtin_amdgcn_sched_barrier(0)
; template <class Epi, class Sched, bool ALIGN_EPI = false, bool SP2 = false>
; __device__ __forceinline__ void gemm_phase(PG8_LAS unsigned char* lds, const Gemm g, const Sched& S, const Epi& E) {
;     ...
;             PG8_LDA(At, 1, 1); PG8_STAGE(PG8_SB(1, 0), b3, voffB); PG8_STAGE(PG8_SB(1, 1), b3 + hstep, voffB); PG8_STAGE(PG8_SA(1, 0), a3, voffA);
;             PG8_WAIT_V(8); PG8_WAIT_L(0); PG8_BAR; PG8_MMA(1, 0, At, B0); PG8_MMA(1, 1, At, B1); PG8_BAR; PG8_SCHED;
	s_setprio 0
	s_add_u32 s46, s46, s48
	s_addc_u32 s47, s47, s49
	s_add_i32 s25, s25, s59
	v_lshl_add_u64 v[178:179], s[46:47], 0, v[172:173]
	s_mov_b32 m0, s25
	s_nop 0
	global_load_lds_dwordx4 v[178:179], off
	ds_read_b128 v[160:163], v215 offset:49152
	ds_read_b128 v[164:167], v215 offset:50176
	ds_read_b128 v[168:171], v215 offset:51200
	ds_read_b128 v[188:191], v215 offset:52224
	s_add_i32 m0, s25, 0x2000
	v_lshl_add_u64 v[178:179], s[46:47], 0, v[186:187]
	s_add_u32 s46, s46, 0x80000
	s_addc_u32 s47, s47, 0
	s_add_i32 s25, s27, s59
	global_load_lds_dwordx4 v[178:179], off
	ds_read_b128 v[192:195], v215 offset:53248
	ds_read_b128 v[196:199], v215 offset:54272
	ds_read_b128 v[200:203], v215 offset:55296
	ds_read_b128 v[216:219], v215 offset:56320
	v_lshl_add_u64 v[178:179], s[46:47], 0, v[172:173]
	s_mov_b32 m0, s25
	s_nop 0
	global_load_lds_dwordx4 v[178:179], off
	v_lshl_add_u64 v[178:179], s[46:47], 0, v[186:187]
	s_add_i32 m0, s25, 0x2000
	s_nop 0
	global_load_lds_dwordx4 v[178:179], off
	v_lshl_add_u64 v[178:179], s[52:53], 0, v[182:183]
	s_mov_b32 m0, s64
	s_nop 0
	global_load_lds_dwordx4 v[178:179], off
	v_lshl_add_u64 v[178:179], s[52:53], 0, v[184:185]
	s_mov_b32 m0, s65
	s_nop 0
	global_load_lds_dwordx4 v[178:179], off
	s_waitcnt vmcnt(8)
	s_waitcnt lgkmcnt(0)
	s_setprio 1
	s_barrier
	v_mfma_f32_16x16x32_bf16 v[116:119], v[88:91], v[160:163], v[116:119]
	v_mfma_f32_16x16x32_bf16 v[112:115], v[96:99], v[160:163], v[112:115]
	v_mfma_f32_16x16x32_bf16 v[84:87], v[88:91], v[168:171], v[84:87]
	v_mfma_f32_16x16x32_bf16 v[80:83], v[96:99], v[168:171], v[80:83]
	v_mfma_f32_16x16x32_bf16 v[76:79], v[88:91], v[192:195], v[76:79]
	v_mfma_f32_16x16x32_bf16 v[72:75], v[96:99], v[192:195], v[72:75]
	v_mfma_f32_16x16x32_bf16 v[68:71], v[88:91], v[200:203], v[68:71]
	v_mfma_f32_16x16x32_bf16 v[64:67], v[96:99], v[200:203], v[64:67]
	v_mfma_f32_16x16x32_bf16 v[116:119], v[92:95], v[164:167], v[116:119]
	v_mfma_f32_16x16x32_bf16 v[112:115], v[100:103], v[164:167], v[112:115]
	v_mfma_f32_16x16x32_bf16 v[84:87], v[92:95], v[188:191], v[84:87]
	v_mfma_f32_16x16x32_bf16 v[80:83], v[100:103], v[188:191], v[80:83]
	v_mfma_f32_16x16x32_bf16 v[76:79], v[92:95], v[196:199], v[76:79]
	v_mfma_f32_16x16x32_bf16 v[72:75], v[100:103], v[196:199], v[72:75]
	v_mfma_f32_16x16x32_bf16 v[68:71], v[92:95], v[216:219], v[68:71]
	v_mfma_f32_16x16x32_bf16 v[64:67], v[100:103], v[216:219], v[64:67]
	s_setprio 0
	s_setprio 1
	v_mfma_f32_16x16x32_bf16 v[28:31], v[104:107], v[160:163], v[28:31]
	v_mfma_f32_16x16x32_bf16 v[24:27], v[152:155], v[160:163], v[24:27]
	v_mfma_f32_16x16x32_bf16 v[20:23], v[104:107], v[168:171], v[20:23]
	v_mfma_f32_16x16x32_bf16 v[16:19], v[152:155], v[168:171], v[16:19]
	v_mfma_f32_16x16x32_bf16 v[12:15], v[104:107], v[192:195], v[12:15]
	v_mfma_f32_16x16x32_bf16 v[8:11], v[152:155], v[192:195], v[8:11]
	v_mfma_f32_16x16x32_bf16 v[4:7], v[104:107], v[200:203], v[4:7]
	v_mfma_f32_16x16x32_bf16 v[0:3], v[152:155], v[200:203], v[0:3]
	v_mfma_f32_16x16x32_bf16 v[28:31], v[108:111], v[164:167], v[28:31]
	v_mfma_f32_16x16x32_bf16 v[24:27], v[156:159], v[164:167], v[24:27]
	v_mfma_f32_16x16x32_bf16 v[20:23], v[108:111], v[188:191], v[20:23]
	v_mfma_f32_16x16x32_bf16 v[16:19], v[156:159], v[188:191], v[16:19]
	v_mfma_f32_16x16x32_bf16 v[12:15], v[108:111], v[196:199], v[12:15]
	v_mfma_f32_16x16x32_bf16 v[8:11], v[156:159], v[196:199], v[8:11]
	v_mfma_f32_16x16x32_bf16 v[4:7], v[108:111], v[216:219], v[4:7]
	v_mfma_f32_16x16x32_bf16 v[0:3], v[156:159], v[216:219], v[0:3]
	s_barrier
	s_setprio 0
	s_cmp_gt_u32 s1, 29
	s_mov_b32 s1, s5
	s_cbranch_scc1 .LBB0_504

; #define PG8_STAGE(bufoff, gbase, voff) do { _Pragma("unroll") for (int _i = 0; _i < 2; ++_i) \
;         __builtin_amdgcn_global_load_lds((const unsigned*)((const char*)(gbase) + (voff)[_i]), (PG8_LAS unsigned*)(lds + (bufoff) + ldsw + _i * 8192), 16, 0, 0); } while (0)
; #define PG8_LDA(dst, b, h) do { _Pragma("unroll") for (int m = 0; m < 4; ++m) _Pragma("unroll") for (int k = 0; k < 2; ++k) dst[m][k] = *(const PG8_LAS bf16x8*)(lds + PG8_SA(b, h) + aoff + m * 2048 + k * 1024); } while (0)
; #define PG8_LDB(dst, b, h) do { _Pragma("unroll") for (int n = 0; n < 2; ++n) _Pragma("unroll") for (int k = 0; k < 2; ++k) dst[n][k] = *(const PG8_LAS bf16x8*)(lds + PG8_SB(b, h) + boff + n * 2048 + k * 1024); } while (0)
; #define PG8_MMA(ai, bj, At, Bt) do { __builtin_amdgcn_s_setprio(1); _Pragma("unroll") for (int m = 0; m < 4; ++m) _Pragma("unroll") for (int n = 0; n < 2; ++n) _Pragma("unroll") for (int k = 0; k < 2; ++k) \
;         acc[ai][bj][m][n] = __builtin_amdgcn_mfma_f32_16x16x32_bf16(Bt[n][k], At[m][k], acc[ai][bj][m][n], 0, 0, 0); __builtin_amdgcn_s_setprio(0); } while (0)
; #define PG8_WAIT_V(n) asm volatile("s_waitcnt vmcnt(" #n ")" ::: "memory")
; #define PG8_BAR __builtin_amdgcn_s_barrier()
; template <class Epi, class Sched, bool ALIGN_EPI = false, bool SP2 = false>
; __device__ __forceinline__ void gemm_phase(PG8_LAS unsigned char* lds, const Gemm g, const Sched& S, const Epi& E) {
;     ...
;         for (int t = 0; t < nt; t += 2) {
;             const bool last = (t == nt - 2);
;             const char* a1 = cA + (long)(t + 1) * st;
;             const char* a2 = last ? nA : cA + (long)(t + 2) * st; const char* b2 = last ? nB : cB + (long)(t + 2) * st;
;             const long s3 = last ? nst : st; const char* a3 = a2 + s3; const char* b3 = b2 + s3;
;             if (last && has_next) S.a_ready(nxt);
;             if constexpr (SP2) {
;             PG8_LDB(B0, 0, 0); PG8_LDB(B1, 0, 1); PG8_SCHED; PG8_LDA(At, 0, 0); PG8_STAGE(PG8_SA(1, 1), a1 + hstep, voffA);
;             PG8_WAIT_V(8); PG8_WAIT_L(0); PG8_BAR; PG8_MMA(0, 0, At, B0); PG8_MMA(0, 1, At, B1); PG8_BAR; PG8_SCHED;
;             PG8_LDA(At, 0, 1); PG8_STAGE(PG8_SB(0, 0), b2, voffB); PG8_STAGE(PG8_SB(0, 1), b2 + hstep, voffB); PG8_STAGE(PG8_SA(0, 0), a2, voffA);
;             PG8_WAIT_V(8); PG8_WAIT_L(0); PG8_BAR; PG8_MMA(1, 0, At, B0); PG8_MMA(1, 1, At, B1); PG8_BAR; PG8_SCHED;
.LBB0_613:
	s_or_b32 s50, s27, 1
	s_mul_i32 s51, s37, s50
	s_mul_hi_u32 s65, s36, s50
	s_add_i32 s65, s65, s51
	s_mul_i32 s66, s36, s50
	s_add_u32 s50, s48, s46
	s_addc_u32 s51, s49, s47
	s_add_i32 s68, 0, 0x10000
	v_add_u32_e32 v143, s68, v140
	s_add_i32 s69, 0, 0x14000
	ds_read_b128 v[134:137], v143
	ds_read_b128 v[144:147], v143 offset:1024
	ds_read_b128 v[148:151], v143 offset:2048
	ds_read_b128 v[152:155], v143 offset:3072
	v_add_u32_e32 v143, s69, v140
	ds_read_b128 v[156:159], v143
	ds_read_b128 v[160:163], v143 offset:1024
	ds_read_b128 v[164:167], v143 offset:2048
	ds_read_b128 v[168:171], v143 offset:3072
	s_add_u32 s66, s17, s66
	s_addc_u32 s67, s19, s65
	v_lshl_add_u64 v[178:179], s[66:67], 0, v[128:129]
	s_add_i32 m0, s29, 0xc000
	ds_read_b128 v[182:185], v142
	ds_read_b128 v[186:189], v142 offset:1024
	ds_read_b128 v[190:193], v142 offset:2048
	ds_read_b128 v[194:197], v142 offset:3072
	ds_read_b128 v[198:201], v142 offset:4096
	ds_read_b128 v[212:215], v142 offset:5120
	ds_read_b128 v[216:219], v142 offset:6144
	ds_read_b128 v[220:223], v142 offset:7168
	global_load_lds_dwordx4 v[178:179], off
	v_lshl_add_u64 v[178:179], s[66:67], 0, v[130:131]
	s_add_i32 m0, s29, 0xe000
	s_nop 0
	global_load_lds_dwordx4 v[178:179], off
	s_waitcnt vmcnt(8)
	s_waitcnt lgkmcnt(0)
	s_setprio 1
	s_barrier
	v_mfma_f32_16x16x32_bf16 v[124:127], v[134:137], v[182:185], v[124:127]
	v_mfma_f32_16x16x32_bf16 v[120:123], v[148:151], v[182:185], v[120:123]
	v_mfma_f32_16x16x32_bf16 v[108:111], v[134:137], v[190:193], v[108:111]
	v_mfma_f32_16x16x32_bf16 v[104:107], v[148:151], v[190:193], v[104:107]
	v_mfma_f32_16x16x32_bf16 v[92:95], v[134:137], v[198:201], v[92:95]
	v_mfma_f32_16x16x32_bf16 v[88:91], v[148:151], v[198:201], v[88:91]
	v_mfma_f32_16x16x32_bf16 v[76:79], v[134:137], v[216:219], v[76:79]
	v_mfma_f32_16x16x32_bf16 v[72:75], v[148:151], v[216:219], v[72:75]
	v_mfma_f32_16x16x32_bf16 v[124:127], v[144:147], v[186:189], v[124:127]
	v_mfma_f32_16x16x32_bf16 v[120:123], v[152:155], v[186:189], v[120:123]
	v_mfma_f32_16x16x32_bf16 v[108:111], v[144:147], v[194:197], v[108:111]
	v_mfma_f32_16x16x32_bf16 v[104:107], v[152:155], v[194:197], v[104:107]
	v_mfma_f32_16x16x32_bf16 v[92:95], v[144:147], v[212:215], v[92:95]
	v_mfma_f32_16x16x32_bf16 v[88:91], v[152:155], v[212:215], v[88:91]
	v_mfma_f32_16x16x32_bf16 v[76:79], v[144:147], v[220:223], v[76:79]
	v_mfma_f32_16x16x32_bf16 v[72:75], v[152:155], v[220:223], v[72:75]
	s_setprio 0
	s_setprio 1
	v_mfma_f32_16x16x32_bf16 v[116:119], v[156:159], v[182:185], v[116:119]
	v_mfma_f32_16x16x32_bf16 v[112:115], v[164:167], v[182:185], v[112:115]
	v_mfma_f32_16x16x32_bf16 v[100:103], v[156:159], v[190:193], v[100:103]
	v_mfma_f32_16x16x32_bf16 v[96:99], v[164:167], v[190:193], v[96:99]
	v_mfma_f32_16x16x32_bf16 v[84:87], v[156:159], v[198:201], v[84:87]
	v_mfma_f32_16x16x32_bf16 v[80:83], v[164:167], v[198:201], v[80:83]
	v_mfma_f32_16x16x32_bf16 v[68:71], v[156:159], v[216:219], v[68:71]
	v_mfma_f32_16x16x32_bf16 v[64:67], v[164:167], v[216:219], v[64:67]
	v_mfma_f32_16x16x32_bf16 v[116:119], v[160:163], v[186:189], v[116:119]
	v_mfma_f32_16x16x32_bf16 v[112:115], v[168:171], v[186:189], v[112:115]
	v_mfma_f32_16x16x32_bf16 v[100:103], v[160:163], v[194:197], v[100:103]
	v_mfma_f32_16x16x32_bf16 v[96:99], v[168:171], v[194:197], v[96:99]
	v_mfma_f32_16x16x32_bf16 v[84:87], v[160:163], v[212:215], v[84:87]
	v_mfma_f32_16x16x32_bf16 v[80:83], v[168:171], v[212:215], v[80:83]
	v_mfma_f32_16x16x32_bf16 v[68:71], v[160:163], v[220:223], v[68:71]
	v_mfma_f32_16x16x32_bf16 v[64:67], v[168:171], v[220:223], v[64:67]
	s_barrier
	s_setprio 0
	s_add_i32 s65, s68, s56
	v_lshl_add_u64 v[178:179], s[44:45], 0, v[172:173]
	s_mov_b32 m0, s65
	s_nop 0
	global_load_lds_dwordx4 v[178:179], off
	ds_read_b128 v[182:185], v142 offset:16384
	ds_read_b128 v[186:189], v142 offset:17408
	ds_read_b128 v[190:193], v142 offset:18432
	ds_read_b128 v[194:197], v142 offset:19456
	s_add_i32 m0, s65, 0x2000
	s_add_u32 s66, s44, 0x80000
	v_lshl_add_u64 v[178:179], s[44:45], 0, v[132:133]
	s_addc_u32 s67, s45, 0
	s_add_i32 s65, s69, s56
	global_load_lds_dwordx4 v[178:179], off
	ds_read_b128 v[198:201], v142 offset:20480
	ds_read_b128 v[212:215], v142 offset:21504
	ds_read_b128 v[216:219], v142 offset:22528
	ds_read_b128 v[220:223], v142 offset:23552
	v_lshl_add_u64 v[178:179], s[66:67], 0, v[172:173]
	s_mov_b32 m0, s65
	s_nop 0
	global_load_lds_dwordx4 v[178:179], off
	v_lshl_add_u64 v[178:179], s[66:67], 0, v[132:133]
	s_add_i32 m0, s65, 0x2000
	s_nop 0
	global_load_lds_dwordx4 v[178:179], off
	v_lshl_add_u64 v[178:179], s[48:49], 0, v[128:129]
	s_mov_b32 m0, s29
	s_nop 0
	global_load_lds_dwordx4 v[178:179], off
	v_lshl_add_u64 v[178:179], s[48:49], 0, v[130:131]
	s_mov_b32 m0, s57
	s_nop 0
	global_load_lds_dwordx4 v[178:179], off
	s_waitcnt vmcnt(8)
	s_waitcnt lgkmcnt(0)
	s_setprio 1
	s_barrier
; #define PG8_STAGE(bufoff, gbase, voff) do { _Pragma("unroll") for (int _i = 0; _i < 2; ++_i) \
;         __builtin_amdgcn_global_load_lds((const unsigned*)((const char*)(gbase) + (voff)[_i]), (PG8_LAS unsigned*)(lds + (bufoff) + ldsw + _i * 8192), 16, 0, 0); } while (0)
; #define PG8_LDA(dst, b, h) do { _Pragma("unroll") for (int m = 0; m < 4; ++m) _Pragma("unroll") for (int k = 0; k < 2; ++k) dst[m][k] = *(const PG8_LAS bf16x8*)(lds + PG8_SA(b, h) + aoff + m * 2048 + k * 1024); } while (0)
; #define PG8_LDB(dst, b, h) do { _Pragma("unroll") for (int n = 0; n < 2; ++n) _Pragma("unroll") for (int k = 0; k < 2; ++k) dst[n][k] = *(const PG8_LAS bf16x8*)(lds + PG8_SB(b, h) + boff + n * 2048 + k * 1024); } while (0)
; #define PG8_MMA(ai, bj, At, Bt) do { __builtin_amdgcn_s_setprio(1); _Pragma("unroll") for (int m = 0; m < 4; ++m) _Pragma("unroll") for (int n = 0; n < 2; ++n) _Pragma("unroll") for (int k = 0; k < 2; ++k) \
;         acc[ai][bj][m][n] = __builtin_amdgcn_mfma_f32_16x16x32_bf16(Bt[n][k], At[m][k], acc[ai][bj][m][n], 0, 0, 0); __builtin_amdgcn_s_setprio(0); } while (0)
; #define PG8_WAIT_V(n) asm volatile("s_waitcnt vmcnt(" #n ")" ::: "memory")
; #define PG8_WAIT_L(n) asm volatile("s_waitcnt lgkmcnt(" #n ")" ::: "memory")
; #define PG8_BAR __builtin_amdgcn_s_barrier()
; #define PG8_SCHED __builtin_amdgcn_sched_barrier(0)
; template <class Epi, class Sched, bool ALIGN_EPI = false, bool SP2 = false>
; __device__ __forceinline__ void gemm_phase(PG8_LAS unsigned char* lds, const Gemm g, const Sched& S, const Epi& E) {
;     ...
;             PG8_WAIT_V(8); PG8_WAIT_L(0); PG8_BAR; PG8_MMA(1, 0, At, B0); PG8_MMA(1, 1, At, B1); PG8_BAR; PG8_SCHED;
;             PG8_LDB(B0, 1, 0); PG8_LDB(B1, 1, 1); PG8_SCHED; PG8_LDA(At, 1, 0); PG8_STAGE(PG8_SA(0, 1), a2 + hstep, voffA);
;             PG8_WAIT_V(8); PG8_WAIT_L(0); PG8_BAR; PG8_MMA(0, 0, At, B0); PG8_MMA(0, 1, At, B1); PG8_BAR; PG8_SCHED;
	v_mfma_f32_16x16x32_bf16 v[60:63], v[134:137], v[182:185], v[60:63]
	v_mfma_f32_16x16x32_bf16 v[56:59], v[148:151], v[182:185], v[56:59]
	v_mfma_f32_16x16x32_bf16 v[44:47], v[134:137], v[190:193], v[44:47]
	v_mfma_f32_16x16x32_bf16 v[40:43], v[148:151], v[190:193], v[40:43]
	v_mfma_f32_16x16x32_bf16 v[28:31], v[134:137], v[198:201], v[28:31]
	v_mfma_f32_16x16x32_bf16 v[24:27], v[148:151], v[198:201], v[24:27]
	v_mfma_f32_16x16x32_bf16 v[12:15], v[134:137], v[216:219], v[12:15]
	v_mfma_f32_16x16x32_bf16 v[8:11], v[148:151], v[216:219], v[8:11]
	v_mfma_f32_16x16x32_bf16 v[60:63], v[144:147], v[186:189], v[60:63]
	v_mfma_f32_16x16x32_bf16 v[56:59], v[152:155], v[186:189], v[56:59]
	v_mfma_f32_16x16x32_bf16 v[44:47], v[144:147], v[194:197], v[44:47]
	v_mfma_f32_16x16x32_bf16 v[40:43], v[152:155], v[194:197], v[40:43]
	v_mfma_f32_16x16x32_bf16 v[28:31], v[144:147], v[212:215], v[28:31]
	v_mfma_f32_16x16x32_bf16 v[24:27], v[152:155], v[212:215], v[24:27]
	v_mfma_f32_16x16x32_bf16 v[12:15], v[144:147], v[220:223], v[12:15]
	v_mfma_f32_16x16x32_bf16 v[8:11], v[152:155], v[220:223], v[8:11]
	s_setprio 0
	s_setprio 1
	v_mfma_f32_16x16x32_bf16 v[52:55], v[156:159], v[182:185], v[52:55]
	v_mfma_f32_16x16x32_bf16 v[48:51], v[164:167], v[182:185], v[48:51]
	v_mfma_f32_16x16x32_bf16 v[36:39], v[156:159], v[190:193], v[36:39]
	v_mfma_f32_16x16x32_bf16 v[32:35], v[164:167], v[190:193], v[32:35]
	v_mfma_f32_16x16x32_bf16 v[20:23], v[156:159], v[198:201], v[20:23]
	v_mfma_f32_16x16x32_bf16 v[16:19], v[164:167], v[198:201], v[16:19]
	v_mfma_f32_16x16x32_bf16 v[4:7], v[156:159], v[216:219], v[4:7]
	v_mfma_f32_16x16x32_bf16 v[0:3], v[164:167], v[216:219], v[0:3]
	v_mfma_f32_16x16x32_bf16 v[52:55], v[160:163], v[186:189], v[52:55]
	v_mfma_f32_16x16x32_bf16 v[48:51], v[168:171], v[186:189], v[48:51]
	v_mfma_f32_16x16x32_bf16 v[36:39], v[160:163], v[194:197], v[36:39]
	v_mfma_f32_16x16x32_bf16 v[32:35], v[168:171], v[194:197], v[32:35]
	v_mfma_f32_16x16x32_bf16 v[20:23], v[160:163], v[212:215], v[20:23]
	v_mfma_f32_16x16x32_bf16 v[16:19], v[168:171], v[212:215], v[16:19]
	v_mfma_f32_16x16x32_bf16 v[4:7], v[160:163], v[220:223], v[4:7]
	v_mfma_f32_16x16x32_bf16 v[0:3], v[168:171], v[220:223], v[0:3]
	s_barrier
	s_setprio 0
	s_add_i32 s65, 0, 0x18000
	v_add_u32_e32 v143, s65, v140
	s_add_i32 s66, 0, 0x1c000
	ds_read_b128 v[134:137], v143
	ds_read_b128 v[144:147], v143 offset:1024
	ds_read_b128 v[148:151], v143 offset:2048
	ds_read_b128 v[152:155], v143 offset:3072
	v_add_u32_e32 v143, s66, v140
	ds_read_b128 v[156:159], v143
	ds_read_b128 v[160:163], v143 offset:1024
	ds_read_b128 v[164:167], v143 offset:2048
	ds_read_b128 v[168:171], v143 offset:3072
	s_add_u32 s48, s48, 0x80000
	s_addc_u32 s49, s49, 0
	s_mov_b32 m0, s58
	v_lshl_add_u64 v[178:179], s[48:49], 0, v[128:129]
	ds_read_b128 v[182:185], v142 offset:32768
	ds_read_b128 v[186:189], v142 offset:33792
	ds_read_b128 v[190:193], v142 offset:34816
	ds_read_b128 v[194:197], v142 offset:35840
	ds_read_b128 v[198:201], v142 offset:36864
	ds_read_b128 v[212:215], v142 offset:37888
	ds_read_b128 v[216:219], v142 offset:38912
	ds_read_b128 v[220:223], v142 offset:39936
	global_load_lds_dwordx4 v[178:179], off
	v_lshl_add_u64 v[178:179], s[48:49], 0, v[130:131]
	s_mov_b32 m0, s59
	s_nop 0
	global_load_lds_dwordx4 v[178:179], off
	s_waitcnt vmcnt(8)
	s_waitcnt lgkmcnt(0)
	s_setprio 1
	s_barrier
	v_mfma_f32_16x16x32_bf16 v[124:127], v[134:137], v[182:185], v[124:127]
	v_mfma_f32_16x16x32_bf16 v[120:123], v[148:151], v[182:185], v[120:123]
	v_mfma_f32_16x16x32_bf16 v[108:111], v[134:137], v[190:193], v[108:111]
	v_mfma_f32_16x16x32_bf16 v[104:107], v[148:151], v[190:193], v[104:107]
	v_mfma_f32_16x16x32_bf16 v[92:95], v[134:137], v[198:201], v[92:95]
	v_mfma_f32_16x16x32_bf16 v[88:91], v[148:151], v[198:201], v[88:91]
	v_mfma_f32_16x16x32_bf16 v[76:79], v[134:137], v[216:219], v[76:79]
	v_mfma_f32_16x16x32_bf16 v[72:75], v[148:151], v[216:219], v[72:75]
	v_mfma_f32_16x16x32_bf16 v[124:127], v[144:147], v[186:189], v[124:127]
	v_mfma_f32_16x16x32_bf16 v[120:123], v[152:155], v[186:189], v[120:123]
	v_mfma_f32_16x16x32_bf16 v[108:111], v[144:147], v[194:197], v[108:111]
	v_mfma_f32_16x16x32_bf16 v[104:107], v[152:155], v[194:197], v[104:107]
	v_mfma_f32_16x16x32_bf16 v[92:95], v[144:147], v[212:215], v[92:95]
	v_mfma_f32_16x16x32_bf16 v[88:91], v[152:155], v[212:215], v[88:91]
	v_mfma_f32_16x16x32_bf16 v[76:79], v[144:147], v[220:223], v[76:79]
	v_mfma_f32_16x16x32_bf16 v[72:75], v[152:155], v[220:223], v[72:75]
	s_setprio 0
	s_setprio 1
	v_mfma_f32_16x16x32_bf16 v[116:119], v[156:159], v[182:185], v[116:119]
	v_mfma_f32_16x16x32_bf16 v[112:115], v[164:167], v[182:185], v[112:115]
	v_mfma_f32_16x16x32_bf16 v[100:103], v[156:159], v[190:193], v[100:103]
	v_mfma_f32_16x16x32_bf16 v[96:99], v[164:167], v[190:193], v[96:99]
	v_mfma_f32_16x16x32_bf16 v[84:87], v[156:159], v[198:201], v[84:87]
	v_mfma_f32_16x16x32_bf16 v[80:83], v[164:167], v[198:201], v[80:83]
	v_mfma_f32_16x16x32_bf16 v[68:71], v[156:159], v[216:219], v[68:71]
	v_mfma_f32_16x16x32_bf16 v[64:67], v[164:167], v[216:219], v[64:67]
	v_mfma_f32_16x16x32_bf16 v[116:119], v[160:163], v[186:189], v[116:119]
	v_mfma_f32_16x16x32_bf16 v[112:115], v[168:171], v[186:189], v[112:115]
	v_mfma_f32_16x16x32_bf16 v[100:103], v[160:163], v[194:197], v[100:103]
	v_mfma_f32_16x16x32_bf16 v[96:99], v[168:171], v[194:197], v[96:99]
	v_mfma_f32_16x16x32_bf16 v[84:87], v[160:163], v[212:215], v[84:87]
	v_mfma_f32_16x16x32_bf16 v[80:83], v[168:171], v[212:215], v[80:83]
	v_mfma_f32_16x16x32_bf16 v[68:71], v[160:163], v[220:223], v[68:71]
	v_mfma_f32_16x16x32_bf16 v[64:67], v[168:171], v[220:223], v[64:67]
	s_barrier
; #define PG8_STAGE(bufoff, gbase, voff) do { _Pragma("unroll") for (int _i = 0; _i < 2; ++_i) \
;         __builtin_amdgcn_global_load_lds((const unsigned*)((const char*)(gbase) + (voff)[_i]), (PG8_LAS unsigned*)(lds + (bufoff) + ldsw + _i * 8192), 16, 0, 0); } while (0)
; #define PG8_LDA(dst, b, h) do { _Pragma("unroll") for (int m = 0; m < 4; ++m) _Pragma("unroll") for (int k = 0; k < 2; ++k) dst[m][k] = *(const PG8_LAS bf16x8*)(lds + PG8_SA(b, h) + aoff + m * 2048 + k * 1024); } while (0)
; #define PG8_MMA(ai, bj, At, Bt) do { __builtin_amdgcn_s_setprio(1); _Pragma("unroll") for (int m = 0; m < 4; ++m) _Pragma("unroll") for (int n = 0; n < 2; ++n) _Pragma("unroll") for (int k = 0; k < 2; ++k) \
;         acc[ai][bj][m][n] = __builtin_amdgcn_mfma_f32_16x16x32_bf16(Bt[n][k], At[m][k], acc[ai][bj][m][n], 0, 0, 0); __builtin_amdgcn_s_setprio(0); } while (0)
; #define PG8_WAIT_V(n) asm volatile("s_waitcnt vmcnt(" #n ")" ::: "memory")
; #define PG8_WAIT_L(n) asm volatile("s_waitcnt lgkmcnt(" #n ")" ::: "memory")
; #define PG8_BAR __builtin_amdgcn_s_barrier()
; #define PG8_SCHED __builtin_amdgcn_sched_barrier(0)
; template <class Epi, class Sched, bool ALIGN_EPI = false, bool SP2 = false>
; __device__ __forceinline__ void gemm_phase(PG8_LAS unsigned char* lds, const Gemm g, const Sched& S, const Epi& E) {
;     ...
;             PG8_LDA(At, 1, 1); PG8_STAGE(PG8_SB(1, 0), b3, voffB); PG8_STAGE(PG8_SB(1, 1), b3 + hstep, voffB); PG8_STAGE(PG8_SA(1, 0), a3, voffA);
;             PG8_WAIT_V(8); PG8_WAIT_L(0); PG8_BAR; PG8_MMA(1, 0, At, B0); PG8_MMA(1, 1, At, B1); PG8_BAR; PG8_SCHED;
	s_setprio 0
	s_add_u32 s44, s44, s46
	s_addc_u32 s45, s45, s47
	s_add_i32 s46, s65, s56
	v_lshl_add_u64 v[178:179], s[44:45], 0, v[172:173]
	s_mov_b32 m0, s46
	s_nop 0
	global_load_lds_dwordx4 v[178:179], off
	ds_read_b128 v[182:185], v142 offset:49152
	ds_read_b128 v[186:189], v142 offset:50176
	ds_read_b128 v[190:193], v142 offset:51200
	ds_read_b128 v[194:197], v142 offset:52224
	s_add_i32 m0, s46, 0x2000
	v_lshl_add_u64 v[178:179], s[44:45], 0, v[132:133]
	s_add_u32 s44, s44, 0x80000
	s_addc_u32 s45, s45, 0
	s_add_i32 s46, s66, s56
	global_load_lds_dwordx4 v[178:179], off
	ds_read_b128 v[198:201], v142 offset:53248
	ds_read_b128 v[212:215], v142 offset:54272
	ds_read_b128 v[216:219], v142 offset:55296
	ds_read_b128 v[220:223], v142 offset:56320
	v_lshl_add_u64 v[178:179], s[44:45], 0, v[172:173]
	s_mov_b32 m0, s46
	s_nop 0
	global_load_lds_dwordx4 v[178:179], off
	v_lshl_add_u64 v[178:179], s[44:45], 0, v[132:133]
	s_add_i32 m0, s46, 0x2000
	s_nop 0
	global_load_lds_dwordx4 v[178:179], off
	v_lshl_add_u64 v[178:179], s[50:51], 0, v[128:129]
	s_mov_b32 m0, s60
	s_nop 0
	global_load_lds_dwordx4 v[178:179], off
	v_lshl_add_u64 v[178:179], s[50:51], 0, v[130:131]
	s_mov_b32 m0, s61
	s_nop 0
	global_load_lds_dwordx4 v[178:179], off
	s_waitcnt vmcnt(8)
	s_waitcnt lgkmcnt(0)
	s_setprio 1
	s_barrier
	v_mfma_f32_16x16x32_bf16 v[60:63], v[134:137], v[182:185], v[60:63]
	v_mfma_f32_16x16x32_bf16 v[56:59], v[148:151], v[182:185], v[56:59]
	v_mfma_f32_16x16x32_bf16 v[44:47], v[134:137], v[190:193], v[44:47]
	v_mfma_f32_16x16x32_bf16 v[40:43], v[148:151], v[190:193], v[40:43]
	v_mfma_f32_16x16x32_bf16 v[28:31], v[134:137], v[198:201], v[28:31]
	v_mfma_f32_16x16x32_bf16 v[24:27], v[148:151], v[198:201], v[24:27]
	v_mfma_f32_16x16x32_bf16 v[12:15], v[134:137], v[216:219], v[12:15]
	v_mfma_f32_16x16x32_bf16 v[8:11], v[148:151], v[216:219], v[8:11]
	v_mfma_f32_16x16x32_bf16 v[60:63], v[144:147], v[186:189], v[60:63]
	v_mfma_f32_16x16x32_bf16 v[56:59], v[152:155], v[186:189], v[56:59]
	v_mfma_f32_16x16x32_bf16 v[44:47], v[144:147], v[194:197], v[44:47]
	v_mfma_f32_16x16x32_bf16 v[40:43], v[152:155], v[194:197], v[40:43]
	v_mfma_f32_16x16x32_bf16 v[28:31], v[144:147], v[212:215], v[28:31]
	v_mfma_f32_16x16x32_bf16 v[24:27], v[152:155], v[212:215], v[24:27]
	v_mfma_f32_16x16x32_bf16 v[12:15], v[144:147], v[220:223], v[12:15]
	v_mfma_f32_16x16x32_bf16 v[8:11], v[152:155], v[220:223], v[8:11]
	s_setprio 0
	s_setprio 1
	v_mfma_f32_16x16x32_bf16 v[52:55], v[156:159], v[182:185], v[52:55]
	v_mfma_f32_16x16x32_bf16 v[48:51], v[164:167], v[182:185], v[48:51]
	v_mfma_f32_16x16x32_bf16 v[36:39], v[156:159], v[190:193], v[36:39]
	v_mfma_f32_16x16x32_bf16 v[32:35], v[164:167], v[190:193], v[32:35]
	v_mfma_f32_16x16x32_bf16 v[20:23], v[156:159], v[198:201], v[20:23]
	v_mfma_f32_16x16x32_bf16 v[16:19], v[164:167], v[198:201], v[16:19]
	v_mfma_f32_16x16x32_bf16 v[4:7], v[156:159], v[216:219], v[4:7]
	v_mfma_f32_16x16x32_bf16 v[0:3], v[164:167], v[216:219], v[0:3]
	v_mfma_f32_16x16x32_bf16 v[52:55], v[160:163], v[186:189], v[52:55]
	v_mfma_f32_16x16x32_bf16 v[48:51], v[168:171], v[186:189], v[48:51]
	v_mfma_f32_16x16x32_bf16 v[36:39], v[160:163], v[194:197], v[36:39]
	v_mfma_f32_16x16x32_bf16 v[32:35], v[168:171], v[194:197], v[32:35]
	v_mfma_f32_16x16x32_bf16 v[20:23], v[160:163], v[212:215], v[20:23]
	v_mfma_f32_16x16x32_bf16 v[16:19], v[168:171], v[212:215], v[16:19]
	v_mfma_f32_16x16x32_bf16 v[4:7], v[160:163], v[220:223], v[4:7]
	v_mfma_f32_16x16x32_bf16 v[0:3], v[168:171], v[220:223], v[0:3]
	s_barrier
	s_setprio 0
	s_cmp_gt_u32 s27, 29
	s_mov_b32 s27, s64
	s_cbranch_scc1 .LBB0_618

; #define PG8_STAGE(bufoff, gbase, voff) do { _Pragma("unroll") for (int _i = 0; _i < 2; ++_i) \
;         __builtin_amdgcn_global_load_lds((const unsigned*)((const char*)(gbase) + (voff)[_i]), (PG8_LAS unsigned*)(lds + (bufoff) + ldsw + _i * 8192), 16, 0, 0); } while (0)
; #define PG8_LDA(dst, b, h) do { _Pragma("unroll") for (int m = 0; m < 4; ++m) _Pragma("unroll") for (int k = 0; k < 2; ++k) dst[m][k] = *(const PG8_LAS bf16x8*)(lds + PG8_SA(b, h) + aoff + m * 2048 + k * 1024); } while (0)
; #define PG8_LDB(dst, b, h) do { _Pragma("unroll") for (int n = 0; n < 2; ++n) _Pragma("unroll") for (int k = 0; k < 2; ++k) dst[n][k] = *(const PG8_LAS bf16x8*)(lds + PG8_SB(b, h) + boff + n * 2048 + k * 1024); } while (0)
; #define PG8_MMA(ai, bj, At, Bt) do { __builtin_amdgcn_s_setprio(1); _Pragma("unroll") for (int m = 0; m < 4; ++m) _Pragma("unroll") for (int n = 0; n < 2; ++n) _Pragma("unroll") for (int k = 0; k < 2; ++k) \
;         acc[ai][bj][m][n] = __builtin_amdgcn_mfma_f32_16x16x32_bf16(Bt[n][k], At[m][k], acc[ai][bj][m][n], 0, 0, 0); __builtin_amdgcn_s_setprio(0); } while (0)
; #define PG8_WAIT_V(n) asm volatile("s_waitcnt vmcnt(" #n ")" ::: "memory")
; #define PG8_BAR __builtin_amdgcn_s_barrier()
; template <class Epi, class Sched, bool ALIGN_EPI = false, bool SP2 = false>
; __device__ __forceinline__ void gemm_phase(PG8_LAS unsigned char* lds, const Gemm g, const Sched& S, const Epi& E) {
;     ...
;         for (int t = 0; t < nt; t += 2) {
;             const bool last = (t == nt - 2);
;             const char* a1 = cA + (long)(t + 1) * st;
;             const char* a2 = last ? nA : cA + (long)(t + 2) * st; const char* b2 = last ? nB : cB + (long)(t + 2) * st;
;             const long s3 = last ? nst : st; const char* a3 = a2 + s3; const char* b3 = b2 + s3;
;             if (last && has_next) S.a_ready(nxt);
;             if constexpr (SP2) {
;             PG8_LDB(B0, 0, 0); PG8_LDB(B1, 0, 1); PG8_SCHED; PG8_LDA(At, 0, 0); PG8_STAGE(PG8_SA(1, 1), a1 + hstep, voffA);
;             PG8_WAIT_V(8); PG8_WAIT_L(0); PG8_BAR; PG8_MMA(0, 0, At, B0); PG8_MMA(0, 1, At, B1); PG8_BAR; PG8_SCHED;
;             PG8_LDA(At, 0, 1); PG8_STAGE(PG8_SB(0, 0), b2, voffB); PG8_STAGE(PG8_SB(0, 1), b2 + hstep, voffB); PG8_STAGE(PG8_SA(0, 0), a2, voffA);
;             PG8_WAIT_V(8); PG8_WAIT_L(0); PG8_BAR; PG8_MMA(1, 0, At, B0); PG8_MMA(1, 1, At, B1); PG8_BAR; PG8_SCHED;
.LBB0_710:
	s_or_b32 s19, s66, 1
	s_mul_i32 s46, s31, s19
	s_mul_hi_u32 s47, s30, s19
	s_add_i32 s47, s47, s46
	s_mul_i32 s19, s30, s19
	s_add_u32 s19, s28, s19
	s_addc_u32 s67, s29, s47
	s_add_u32 s46, s44, s42
	s_addc_u32 s47, s45, s43
	s_add_i32 s72, 0, 0x10000
	v_add_u32_e32 v138, s72, v143
	s_add_i32 s75, 0, 0x14000
	ds_read_b128 v[134:137], v138
	ds_read_b128 v[148:151], v138 offset:1024
	ds_read_b128 v[152:155], v138 offset:2048
	ds_read_b128 v[156:159], v138 offset:3072
	v_add_u32_e32 v138, s75, v143
	ds_read_b128 v[160:163], v138
	ds_read_b128 v[164:167], v138 offset:1024
	ds_read_b128 v[168:171], v138 offset:2048
	ds_read_b128 v[178:181], v138 offset:3072
	s_add_u32 s68, s19, 0x80000
	s_addc_u32 s69, s67, 0
	v_lshl_add_u64 v[138:139], s[68:69], 0, v[128:129]
	s_add_i32 m0, s58, 0xc000
	ds_read_b128 v[182:185], v146
	ds_read_b128 v[186:189], v146 offset:1024
	ds_read_b128 v[190:193], v146 offset:2048
	ds_read_b128 v[194:197], v146 offset:3072
	ds_read_b128 v[198:201], v146 offset:4096
	ds_read_b128 v[212:215], v146 offset:5120
	ds_read_b128 v[216:219], v146 offset:6144
	ds_read_b128 v[220:223], v146 offset:7168
	global_load_lds_dwordx4 v[138:139], off
	v_lshl_add_u64 v[138:139], s[68:69], 0, v[130:131]
	s_add_i32 m0, s58, 0xe000
	s_nop 0
	global_load_lds_dwordx4 v[138:139], off
	s_waitcnt vmcnt(8)
	s_waitcnt lgkmcnt(0)
	s_setprio 1
	s_barrier
	v_mfma_f32_16x16x32_bf16 v[124:127], v[134:137], v[182:185], v[124:127]
	v_mfma_f32_16x16x32_bf16 v[120:123], v[152:155], v[182:185], v[120:123]
	v_mfma_f32_16x16x32_bf16 v[108:111], v[134:137], v[190:193], v[108:111]
	v_mfma_f32_16x16x32_bf16 v[104:107], v[152:155], v[190:193], v[104:107]
	v_mfma_f32_16x16x32_bf16 v[92:95], v[134:137], v[198:201], v[92:95]
	v_mfma_f32_16x16x32_bf16 v[88:91], v[152:155], v[198:201], v[88:91]
	v_mfma_f32_16x16x32_bf16 v[76:79], v[134:137], v[216:219], v[76:79]
	v_mfma_f32_16x16x32_bf16 v[72:75], v[152:155], v[216:219], v[72:75]
	v_mfma_f32_16x16x32_bf16 v[124:127], v[148:151], v[186:189], v[124:127]
	v_mfma_f32_16x16x32_bf16 v[120:123], v[156:159], v[186:189], v[120:123]
	v_mfma_f32_16x16x32_bf16 v[108:111], v[148:151], v[194:197], v[108:111]
	v_mfma_f32_16x16x32_bf16 v[104:107], v[156:159], v[194:197], v[104:107]
	v_mfma_f32_16x16x32_bf16 v[92:95], v[148:151], v[212:215], v[92:95]
	v_mfma_f32_16x16x32_bf16 v[88:91], v[156:159], v[212:215], v[88:91]
	v_mfma_f32_16x16x32_bf16 v[76:79], v[148:151], v[220:223], v[76:79]
	v_mfma_f32_16x16x32_bf16 v[72:75], v[156:159], v[220:223], v[72:75]
	s_setprio 0
	s_setprio 1
	v_mfma_f32_16x16x32_bf16 v[116:119], v[160:163], v[182:185], v[116:119]
	v_mfma_f32_16x16x32_bf16 v[112:115], v[168:171], v[182:185], v[112:115]
	v_mfma_f32_16x16x32_bf16 v[100:103], v[160:163], v[190:193], v[100:103]
	v_mfma_f32_16x16x32_bf16 v[96:99], v[168:171], v[190:193], v[96:99]
	v_mfma_f32_16x16x32_bf16 v[84:87], v[160:163], v[198:201], v[84:87]
	v_mfma_f32_16x16x32_bf16 v[80:83], v[168:171], v[198:201], v[80:83]
	v_mfma_f32_16x16x32_bf16 v[68:71], v[160:163], v[216:219], v[68:71]
	v_mfma_f32_16x16x32_bf16 v[64:67], v[168:171], v[216:219], v[64:67]
	v_mfma_f32_16x16x32_bf16 v[116:119], v[164:167], v[186:189], v[116:119]
	v_mfma_f32_16x16x32_bf16 v[112:115], v[178:181], v[186:189], v[112:115]
	v_mfma_f32_16x16x32_bf16 v[100:103], v[164:167], v[194:197], v[100:103]
	v_mfma_f32_16x16x32_bf16 v[96:99], v[178:181], v[194:197], v[96:99]
	v_mfma_f32_16x16x32_bf16 v[84:87], v[164:167], v[212:215], v[84:87]
	v_mfma_f32_16x16x32_bf16 v[80:83], v[178:181], v[212:215], v[80:83]
	v_mfma_f32_16x16x32_bf16 v[68:71], v[164:167], v[220:223], v[68:71]
	v_mfma_f32_16x16x32_bf16 v[64:67], v[178:181], v[220:223], v[64:67]
	s_barrier
	s_setprio 0
	s_add_i32 s19, s72, s57
	v_lshl_add_u64 v[138:139], s[40:41], 0, v[172:173]
	s_mov_b32 m0, s19
	s_nop 0
	global_load_lds_dwordx4 v[138:139], off
	ds_read_b128 v[182:185], v146 offset:16384
	ds_read_b128 v[186:189], v146 offset:17408
	ds_read_b128 v[190:193], v146 offset:18432
	ds_read_b128 v[194:197], v146 offset:19456
	s_add_i32 m0, s19, 0x2000
	s_add_u32 s68, s40, 0x80000
	v_lshl_add_u64 v[138:139], s[40:41], 0, v[132:133]
	s_addc_u32 s69, s41, 0
	s_add_i32 s19, s75, s57
	global_load_lds_dwordx4 v[138:139], off
	ds_read_b128 v[198:201], v146 offset:20480
	ds_read_b128 v[212:215], v146 offset:21504
	ds_read_b128 v[216:219], v146 offset:22528
	ds_read_b128 v[220:223], v146 offset:23552
	v_lshl_add_u64 v[138:139], s[68:69], 0, v[172:173]
	s_mov_b32 m0, s19
	s_nop 0
	global_load_lds_dwordx4 v[138:139], off
	v_lshl_add_u64 v[138:139], s[68:69], 0, v[132:133]
	s_add_i32 m0, s19, 0x2000
	s_nop 0
	global_load_lds_dwordx4 v[138:139], off
	v_lshl_add_u64 v[138:139], s[44:45], 0, v[128:129]
	s_mov_b32 m0, s58
	s_nop 0
	global_load_lds_dwordx4 v[138:139], off
	v_lshl_add_u64 v[138:139], s[44:45], 0, v[130:131]
	s_mov_b32 m0, s59
	s_nop 0
	global_load_lds_dwordx4 v[138:139], off
	s_waitcnt vmcnt(8)
	s_waitcnt lgkmcnt(0)
	s_setprio 1
	s_barrier
; #define PG8_STAGE(bufoff, gbase, voff) do { _Pragma("unroll") for (int _i = 0; _i < 2; ++_i) \
;         __builtin_amdgcn_global_load_lds((const unsigned*)((const char*)(gbase) + (voff)[_i]), (PG8_LAS unsigned*)(lds + (bufoff) + ldsw + _i * 8192), 16, 0, 0); } while (0)
; #define PG8_LDA(dst, b, h) do { _Pragma("unroll") for (int m = 0; m < 4; ++m) _Pragma("unroll") for (int k = 0; k < 2; ++k) dst[m][k] = *(const PG8_LAS bf16x8*)(lds + PG8_SA(b, h) + aoff + m * 2048 + k * 1024); } while (0)
; #define PG8_LDB(dst, b, h) do { _Pragma("unroll") for (int n = 0; n < 2; ++n) _Pragma("unroll") for (int k = 0; k < 2; ++k) dst[n][k] = *(const PG8_LAS bf16x8*)(lds + PG8_SB(b, h) + boff + n * 2048 + k * 1024); } while (0)
; #define PG8_MMA(ai, bj, At, Bt) do { __builtin_amdgcn_s_setprio(1); _Pragma("unroll") for (int m = 0; m < 4; ++m) _Pragma("unroll") for (int n = 0; n < 2; ++n) _Pragma("unroll") for (int k = 0; k < 2; ++k) \
;         acc[ai][bj][m][n] = __builtin_amdgcn_mfma_f32_16x16x32_bf16(Bt[n][k], At[m][k], acc[ai][bj][m][n], 0, 0, 0); __builtin_amdgcn_s_setprio(0); } while (0)
; #define PG8_WAIT_V(n) asm volatile("s_waitcnt vmcnt(" #n ")" ::: "memory")
; #define PG8_WAIT_L(n) asm volatile("s_waitcnt lgkmcnt(" #n ")" ::: "memory")
; #define PG8_BAR __builtin_amdgcn_s_barrier()
; #define PG8_SCHED __builtin_amdgcn_sched_barrier(0)
; template <class Epi, class Sched, bool ALIGN_EPI = false, bool SP2 = false>
; __device__ __forceinline__ void gemm_phase(PG8_LAS unsigned char* lds, const Gemm g, const Sched& S, const Epi& E) {
;     ...
;             PG8_WAIT_V(8); PG8_WAIT_L(0); PG8_BAR; PG8_MMA(1, 0, At, B0); PG8_MMA(1, 1, At, B1); PG8_BAR; PG8_SCHED;
;             PG8_LDB(B0, 1, 0); PG8_LDB(B1, 1, 1); PG8_SCHED; PG8_LDA(At, 1, 0); PG8_STAGE(PG8_SA(0, 1), a2 + hstep, voffA);
;             PG8_WAIT_V(8); PG8_WAIT_L(0); PG8_BAR; PG8_MMA(0, 0, At, B0); PG8_MMA(0, 1, At, B1); PG8_BAR; PG8_SCHED;
	v_mfma_f32_16x16x32_bf16 v[60:63], v[134:137], v[182:185], v[60:63]
	v_mfma_f32_16x16x32_bf16 v[56:59], v[152:155], v[182:185], v[56:59]
	v_mfma_f32_16x16x32_bf16 v[44:47], v[134:137], v[190:193], v[44:47]
	v_mfma_f32_16x16x32_bf16 v[40:43], v[152:155], v[190:193], v[40:43]
	v_mfma_f32_16x16x32_bf16 v[28:31], v[134:137], v[198:201], v[28:31]
	v_mfma_f32_16x16x32_bf16 v[24:27], v[152:155], v[198:201], v[24:27]
	v_mfma_f32_16x16x32_bf16 v[12:15], v[134:137], v[216:219], v[12:15]
	v_mfma_f32_16x16x32_bf16 v[8:11], v[152:155], v[216:219], v[8:11]
	v_mfma_f32_16x16x32_bf16 v[60:63], v[148:151], v[186:189], v[60:63]
	v_mfma_f32_16x16x32_bf16 v[56:59], v[156:159], v[186:189], v[56:59]
	v_mfma_f32_16x16x32_bf16 v[44:47], v[148:151], v[194:197], v[44:47]
	v_mfma_f32_16x16x32_bf16 v[40:43], v[156:159], v[194:197], v[40:43]
	v_mfma_f32_16x16x32_bf16 v[28:31], v[148:151], v[212:215], v[28:31]
	v_mfma_f32_16x16x32_bf16 v[24:27], v[156:159], v[212:215], v[24:27]
	v_mfma_f32_16x16x32_bf16 v[12:15], v[148:151], v[220:223], v[12:15]
	v_mfma_f32_16x16x32_bf16 v[8:11], v[156:159], v[220:223], v[8:11]
	s_setprio 0
	s_setprio 1
	v_mfma_f32_16x16x32_bf16 v[52:55], v[160:163], v[182:185], v[52:55]
	v_mfma_f32_16x16x32_bf16 v[48:51], v[168:171], v[182:185], v[48:51]
	v_mfma_f32_16x16x32_bf16 v[36:39], v[160:163], v[190:193], v[36:39]
	v_mfma_f32_16x16x32_bf16 v[32:35], v[168:171], v[190:193], v[32:35]
	v_mfma_f32_16x16x32_bf16 v[20:23], v[160:163], v[198:201], v[20:23]
	v_mfma_f32_16x16x32_bf16 v[16:19], v[168:171], v[198:201], v[16:19]
	v_mfma_f32_16x16x32_bf16 v[4:7], v[160:163], v[216:219], v[4:7]
	v_mfma_f32_16x16x32_bf16 v[0:3], v[168:171], v[216:219], v[0:3]
	v_mfma_f32_16x16x32_bf16 v[52:55], v[164:167], v[186:189], v[52:55]
	v_mfma_f32_16x16x32_bf16 v[48:51], v[178:181], v[186:189], v[48:51]
	v_mfma_f32_16x16x32_bf16 v[36:39], v[164:167], v[194:197], v[36:39]
	v_mfma_f32_16x16x32_bf16 v[32:35], v[178:181], v[194:197], v[32:35]
	v_mfma_f32_16x16x32_bf16 v[20:23], v[164:167], v[212:215], v[20:23]
	v_mfma_f32_16x16x32_bf16 v[16:19], v[178:181], v[212:215], v[16:19]
	v_mfma_f32_16x16x32_bf16 v[4:7], v[164:167], v[220:223], v[4:7]
	v_mfma_f32_16x16x32_bf16 v[0:3], v[178:181], v[220:223], v[0:3]
	s_barrier
	s_setprio 0
	s_add_i32 s19, 0, 0x18000
	v_add_u32_e32 v138, s19, v143
	s_add_i32 s67, 0, 0x1c000
	ds_read_b128 v[134:137], v138
	ds_read_b128 v[148:151], v138 offset:1024
	ds_read_b128 v[152:155], v138 offset:2048
	ds_read_b128 v[156:159], v138 offset:3072
	v_add_u32_e32 v138, s67, v143
	ds_read_b128 v[160:163], v138
	ds_read_b128 v[164:167], v138 offset:1024
	ds_read_b128 v[168:171], v138 offset:2048
	ds_read_b128 v[178:181], v138 offset:3072
	s_add_u32 s44, s44, 0x80000
	s_addc_u32 s45, s45, 0
	s_mov_b32 m0, s60
	v_lshl_add_u64 v[138:139], s[44:45], 0, v[128:129]
	ds_read_b128 v[182:185], v146 offset:32768
	ds_read_b128 v[186:189], v146 offset:33792
	ds_read_b128 v[190:193], v146 offset:34816
	ds_read_b128 v[194:197], v146 offset:35840
	ds_read_b128 v[198:201], v146 offset:36864
	ds_read_b128 v[212:215], v146 offset:37888
	ds_read_b128 v[216:219], v146 offset:38912
	ds_read_b128 v[220:223], v146 offset:39936
	global_load_lds_dwordx4 v[138:139], off
	v_lshl_add_u64 v[138:139], s[44:45], 0, v[130:131]
	s_mov_b32 m0, s61
	s_nop 0
	global_load_lds_dwordx4 v[138:139], off
	s_waitcnt vmcnt(8)
	s_waitcnt lgkmcnt(0)
	s_setprio 1
	s_barrier
	v_mfma_f32_16x16x32_bf16 v[124:127], v[134:137], v[182:185], v[124:127]
	v_mfma_f32_16x16x32_bf16 v[120:123], v[152:155], v[182:185], v[120:123]
	v_mfma_f32_16x16x32_bf16 v[108:111], v[134:137], v[190:193], v[108:111]
	v_mfma_f32_16x16x32_bf16 v[104:107], v[152:155], v[190:193], v[104:107]
	v_mfma_f32_16x16x32_bf16 v[92:95], v[134:137], v[198:201], v[92:95]
	v_mfma_f32_16x16x32_bf16 v[88:91], v[152:155], v[198:201], v[88:91]
	v_mfma_f32_16x16x32_bf16 v[76:79], v[134:137], v[216:219], v[76:79]
	v_mfma_f32_16x16x32_bf16 v[72:75], v[152:155], v[216:219], v[72:75]
	v_mfma_f32_16x16x32_bf16 v[124:127], v[148:151], v[186:189], v[124:127]
	v_mfma_f32_16x16x32_bf16 v[120:123], v[156:159], v[186:189], v[120:123]
	v_mfma_f32_16x16x32_bf16 v[108:111], v[148:151], v[194:197], v[108:111]
	v_mfma_f32_16x16x32_bf16 v[104:107], v[156:159], v[194:197], v[104:107]
	v_mfma_f32_16x16x32_bf16 v[92:95], v[148:151], v[212:215], v[92:95]
	v_mfma_f32_16x16x32_bf16 v[88:91], v[156:159], v[212:215], v[88:91]
	v_mfma_f32_16x16x32_bf16 v[76:79], v[148:151], v[220:223], v[76:79]
	v_mfma_f32_16x16x32_bf16 v[72:75], v[156:159], v[220:223], v[72:75]
	s_setprio 0
	s_setprio 1
	v_mfma_f32_16x16x32_bf16 v[116:119], v[160:163], v[182:185], v[116:119]
	v_mfma_f32_16x16x32_bf16 v[112:115], v[168:171], v[182:185], v[112:115]
	v_mfma_f32_16x16x32_bf16 v[100:103], v[160:163], v[190:193], v[100:103]
	v_mfma_f32_16x16x32_bf16 v[96:99], v[168:171], v[190:193], v[96:99]
	v_mfma_f32_16x16x32_bf16 v[84:87], v[160:163], v[198:201], v[84:87]
	v_mfma_f32_16x16x32_bf16 v[80:83], v[168:171], v[198:201], v[80:83]
	v_mfma_f32_16x16x32_bf16 v[68:71], v[160:163], v[216:219], v[68:71]
	v_mfma_f32_16x16x32_bf16 v[64:67], v[168:171], v[216:219], v[64:67]
	v_mfma_f32_16x16x32_bf16 v[116:119], v[164:167], v[186:189], v[116:119]
	v_mfma_f32_16x16x32_bf16 v[112:115], v[178:181], v[186:189], v[112:115]
	v_mfma_f32_16x16x32_bf16 v[100:103], v[164:167], v[194:197], v[100:103]
	v_mfma_f32_16x16x32_bf16 v[96:99], v[178:181], v[194:197], v[96:99]
	v_mfma_f32_16x16x32_bf16 v[84:87], v[164:167], v[212:215], v[84:87]
	v_mfma_f32_16x16x32_bf16 v[80:83], v[178:181], v[212:215], v[80:83]
	v_mfma_f32_16x16x32_bf16 v[68:71], v[164:167], v[220:223], v[68:71]
	v_mfma_f32_16x16x32_bf16 v[64:67], v[178:181], v[220:223], v[64:67]
	s_barrier
; #define PG8_STAGE(bufoff, gbase, voff) do { _Pragma("unroll") for (int _i = 0; _i < 2; ++_i) \
;         __builtin_amdgcn_global_load_lds((const unsigned*)((const char*)(gbase) + (voff)[_i]), (PG8_LAS unsigned*)(lds + (bufoff) + ldsw + _i * 8192), 16, 0, 0); } while (0)
; #define PG8_LDA(dst, b, h) do { _Pragma("unroll") for (int m = 0; m < 4; ++m) _Pragma("unroll") for (int k = 0; k < 2; ++k) dst[m][k] = *(const PG8_LAS bf16x8*)(lds + PG8_SA(b, h) + aoff + m * 2048 + k * 1024); } while (0)
; #define PG8_MMA(ai, bj, At, Bt) do { __builtin_amdgcn_s_setprio(1); _Pragma("unroll") for (int m = 0; m < 4; ++m) _Pragma("unroll") for (int n = 0; n < 2; ++n) _Pragma("unroll") for (int k = 0; k < 2; ++k) \
;         acc[ai][bj][m][n] = __builtin_amdgcn_mfma_f32_16x16x32_bf16(Bt[n][k], At[m][k], acc[ai][bj][m][n], 0, 0, 0); __builtin_amdgcn_s_setprio(0); } while (0)
; #define PG8_WAIT_V(n) asm volatile("s_waitcnt vmcnt(" #n ")" ::: "memory")
; #define PG8_WAIT_L(n) asm volatile("s_waitcnt lgkmcnt(" #n ")" ::: "memory")
; #define PG8_BAR __builtin_amdgcn_s_barrier()
; #define PG8_SCHED __builtin_amdgcn_sched_barrier(0)
; template <class Epi, class Sched, bool ALIGN_EPI = false, bool SP2 = false>
; __device__ __forceinline__ void gemm_phase(PG8_LAS unsigned char* lds, const Gemm g, const Sched& S, const Epi& E) {
;     ...
;             PG8_LDA(At, 1, 1); PG8_STAGE(PG8_SB(1, 0), b3, voffB); PG8_STAGE(PG8_SB(1, 1), b3 + hstep, voffB); PG8_STAGE(PG8_SA(1, 0), a3, voffA);
;             PG8_WAIT_V(8); PG8_WAIT_L(0); PG8_BAR; PG8_MMA(1, 0, At, B0); PG8_MMA(1, 1, At, B1); PG8_BAR; PG8_SCHED;
	s_setprio 0
	s_add_u32 s40, s40, s42
	s_addc_u32 s41, s41, s43
	s_add_i32 s19, s19, s57
	v_lshl_add_u64 v[138:139], s[40:41], 0, v[172:173]
	s_mov_b32 m0, s19
	s_nop 0
	global_load_lds_dwordx4 v[138:139], off
	ds_read_b128 v[182:185], v146 offset:49152
	ds_read_b128 v[186:189], v146 offset:50176
	ds_read_b128 v[190:193], v146 offset:51200
	ds_read_b128 v[194:197], v146 offset:52224
	s_add_i32 m0, s19, 0x2000
	v_lshl_add_u64 v[138:139], s[40:41], 0, v[132:133]
	s_add_u32 s40, s40, 0x80000
	s_addc_u32 s41, s41, 0
	s_add_i32 s19, s67, s57
	global_load_lds_dwordx4 v[138:139], off
	ds_read_b128 v[198:201], v146 offset:53248
	ds_read_b128 v[212:215], v146 offset:54272
	ds_read_b128 v[216:219], v146 offset:55296
	ds_read_b128 v[220:223], v146 offset:56320
	v_lshl_add_u64 v[138:139], s[40:41], 0, v[172:173]
	s_mov_b32 m0, s19
	s_nop 0
	global_load_lds_dwordx4 v[138:139], off
	v_lshl_add_u64 v[138:139], s[40:41], 0, v[132:133]
	s_add_i32 m0, s19, 0x2000
	s_nop 0
	global_load_lds_dwordx4 v[138:139], off
	v_lshl_add_u64 v[138:139], s[46:47], 0, v[128:129]
	s_mov_b32 m0, s63
	s_nop 0
	global_load_lds_dwordx4 v[138:139], off
	v_lshl_add_u64 v[138:139], s[46:47], 0, v[130:131]
	s_mov_b32 m0, s64
	s_nop 0
	global_load_lds_dwordx4 v[138:139], off
	s_waitcnt vmcnt(8)
	s_waitcnt lgkmcnt(0)
	s_setprio 1
	s_barrier
	v_mfma_f32_16x16x32_bf16 v[60:63], v[134:137], v[182:185], v[60:63]
	v_mfma_f32_16x16x32_bf16 v[56:59], v[152:155], v[182:185], v[56:59]
	v_mfma_f32_16x16x32_bf16 v[44:47], v[134:137], v[190:193], v[44:47]
	v_mfma_f32_16x16x32_bf16 v[40:43], v[152:155], v[190:193], v[40:43]
	v_mfma_f32_16x16x32_bf16 v[28:31], v[134:137], v[198:201], v[28:31]
	v_mfma_f32_16x16x32_bf16 v[24:27], v[152:155], v[198:201], v[24:27]
	v_mfma_f32_16x16x32_bf16 v[12:15], v[134:137], v[216:219], v[12:15]
	v_mfma_f32_16x16x32_bf16 v[8:11], v[152:155], v[216:219], v[8:11]
	v_mfma_f32_16x16x32_bf16 v[60:63], v[148:151], v[186:189], v[60:63]
	v_mfma_f32_16x16x32_bf16 v[56:59], v[156:159], v[186:189], v[56:59]
	v_mfma_f32_16x16x32_bf16 v[44:47], v[148:151], v[194:197], v[44:47]
	v_mfma_f32_16x16x32_bf16 v[40:43], v[156:159], v[194:197], v[40:43]
	v_mfma_f32_16x16x32_bf16 v[28:31], v[148:151], v[212:215], v[28:31]
	v_mfma_f32_16x16x32_bf16 v[24:27], v[156:159], v[212:215], v[24:27]
	v_mfma_f32_16x16x32_bf16 v[12:15], v[148:151], v[220:223], v[12:15]
	v_mfma_f32_16x16x32_bf16 v[8:11], v[156:159], v[220:223], v[8:11]
	s_setprio 0
	s_setprio 1
	v_mfma_f32_16x16x32_bf16 v[52:55], v[160:163], v[182:185], v[52:55]
	v_mfma_f32_16x16x32_bf16 v[48:51], v[168:171], v[182:185], v[48:51]
	v_mfma_f32_16x16x32_bf16 v[36:39], v[160:163], v[190:193], v[36:39]
	v_mfma_f32_16x16x32_bf16 v[32:35], v[168:171], v[190:193], v[32:35]
	v_mfma_f32_16x16x32_bf16 v[20:23], v[160:163], v[198:201], v[20:23]
	v_mfma_f32_16x16x32_bf16 v[16:19], v[168:171], v[198:201], v[16:19]
	v_mfma_f32_16x16x32_bf16 v[4:7], v[160:163], v[216:219], v[4:7]
	v_mfma_f32_16x16x32_bf16 v[0:3], v[168:171], v[216:219], v[0:3]
	v_mfma_f32_16x16x32_bf16 v[52:55], v[164:167], v[186:189], v[52:55]
	v_mfma_f32_16x16x32_bf16 v[48:51], v[178:181], v[186:189], v[48:51]
	v_mfma_f32_16x16x32_bf16 v[36:39], v[164:167], v[194:197], v[36:39]
	v_mfma_f32_16x16x32_bf16 v[32:35], v[178:181], v[194:197], v[32:35]
	v_mfma_f32_16x16x32_bf16 v[20:23], v[164:167], v[212:215], v[20:23]
	v_mfma_f32_16x16x32_bf16 v[16:19], v[178:181], v[212:215], v[16:19]
	v_mfma_f32_16x16x32_bf16 v[4:7], v[164:167], v[220:223], v[4:7]
	v_mfma_f32_16x16x32_bf16 v[0:3], v[178:181], v[220:223], v[0:3]
	s_barrier
	s_setprio 0
	s_cmp_gt_u32 s66, 29
	s_mov_b32 s66, s17
	s_cbranch_scc1 .LBB0_715

; #define PG8_STAGE(bufoff, gbase, voff) do { _Pragma("unroll") for (int _i = 0; _i < 2; ++_i) \
;         __builtin_amdgcn_global_load_lds((const unsigned*)((const char*)(gbase) + (voff)[_i]), (PG8_LAS unsigned*)(lds + (bufoff) + ldsw + _i * 8192), 16, 0, 0); } while (0)
; #define PG8_LDA(dst, b, h) do { _Pragma("unroll") for (int m = 0; m < 4; ++m) _Pragma("unroll") for (int k = 0; k < 2; ++k) dst[m][k] = *(const PG8_LAS bf16x8*)(lds + PG8_SA(b, h) + aoff + m * 2048 + k * 1024); } while (0)
; #define PG8_LDB(dst, b, h) do { _Pragma("unroll") for (int n = 0; n < 2; ++n) _Pragma("unroll") for (int k = 0; k < 2; ++k) dst[n][k] = *(const PG8_LAS bf16x8*)(lds + PG8_SB(b, h) + boff + n * 2048 + k * 1024); } while (0)
; #define PG8_MMA(ai, bj, At, Bt) do { __builtin_amdgcn_s_setprio(1); _Pragma("unroll") for (int m = 0; m < 4; ++m) _Pragma("unroll") for (int n = 0; n < 2; ++n) _Pragma("unroll") for (int k = 0; k < 2; ++k) \
;         acc[ai][bj][m][n] = __builtin_amdgcn_mfma_f32_16x16x32_bf16(Bt[n][k], At[m][k], acc[ai][bj][m][n], 0, 0, 0); __builtin_amdgcn_s_setprio(0); } while (0)
; #define PG8_WAIT_V(n) asm volatile("s_waitcnt vmcnt(" #n ")" ::: "memory")
; #define PG8_BAR __builtin_amdgcn_s_barrier()
; template <class Epi, class Sched, bool ALIGN_EPI = false, bool SP2 = false>
; __device__ __forceinline__ void gemm_phase(PG8_LAS unsigned char* lds, const Gemm g, const Sched& S, const Epi& E) {
;     ...
;         for (int t = 0; t < nt; t += 2) {
;             const bool last = (t == nt - 2);
;             const char* a1 = cA + (long)(t + 1) * st;
;             const char* a2 = last ? nA : cA + (long)(t + 2) * st; const char* b2 = last ? nB : cB + (long)(t + 2) * st;
;             const long s3 = last ? nst : st; const char* a3 = a2 + s3; const char* b3 = b2 + s3;
;             if (last && has_next) S.a_ready(nxt);
;             if constexpr (SP2) {
;             PG8_LDB(B0, 0, 0); PG8_LDB(B1, 0, 1); PG8_SCHED; PG8_LDA(At, 0, 0); PG8_STAGE(PG8_SA(1, 1), a1 + hstep, voffA);
;             PG8_WAIT_V(8); PG8_WAIT_L(0); PG8_BAR; PG8_MMA(0, 0, At, B0); PG8_MMA(0, 1, At, B1); PG8_BAR; PG8_SCHED;
;             PG8_LDA(At, 0, 1); PG8_STAGE(PG8_SB(0, 0), b2, voffB); PG8_STAGE(PG8_SB(0, 1), b2 + hstep, voffB); PG8_STAGE(PG8_SA(0, 0), a2, voffA);
;             PG8_WAIT_V(8); PG8_WAIT_L(0); PG8_BAR; PG8_MMA(1, 0, At, B0); PG8_MMA(1, 1, At, B1); PG8_BAR; PG8_SCHED;
.LBB0_791:
	s_or_b32 s48, s25, 1
	s_mul_i32 s49, s35, s48
	s_mul_hi_u32 s65, s34, s48
	s_add_i32 s65, s65, s49
	s_mul_i32 s66, s34, s48
	s_add_u32 s48, s46, s44
	s_addc_u32 s49, s47, s45
	s_add_i32 s68, 0, 0x10000
	v_add_u32_e32 v138, s68, v142
	s_add_i32 s69, 0, 0x14000
	ds_read_b128 v[134:137], v138
	ds_read_b128 v[146:149], v138 offset:1024
	ds_read_b128 v[150:153], v138 offset:2048
	ds_read_b128 v[154:157], v138 offset:3072
	v_add_u32_e32 v138, s69, v142
	ds_read_b128 v[158:161], v138
	ds_read_b128 v[162:165], v138 offset:1024
	ds_read_b128 v[166:169], v138 offset:2048
	ds_read_b128 v[178:181], v138 offset:3072
	s_add_u32 s66, s15, s66
	s_addc_u32 s67, s17, s65
	v_lshl_add_u64 v[138:139], s[66:67], 0, v[128:129]
	s_add_i32 m0, s27, 0xc000
	ds_read_b128 v[182:185], v144
	ds_read_b128 v[186:189], v144 offset:1024
	ds_read_b128 v[190:193], v144 offset:2048
	ds_read_b128 v[194:197], v144 offset:3072
	ds_read_b128 v[198:201], v144 offset:4096
	ds_read_b128 v[212:215], v144 offset:5120
	ds_read_b128 v[216:219], v144 offset:6144
	ds_read_b128 v[220:223], v144 offset:7168
	global_load_lds_dwordx4 v[138:139], off
	v_lshl_add_u64 v[138:139], s[66:67], 0, v[130:131]
	s_add_i32 m0, s27, 0xe000
	s_nop 0
	global_load_lds_dwordx4 v[138:139], off
	s_waitcnt vmcnt(8)
	s_waitcnt lgkmcnt(0)
	s_setprio 1
	s_barrier
	v_mfma_f32_16x16x32_bf16 v[124:127], v[134:137], v[182:185], v[124:127]
	v_mfma_f32_16x16x32_bf16 v[120:123], v[150:153], v[182:185], v[120:123]
	v_mfma_f32_16x16x32_bf16 v[108:111], v[134:137], v[190:193], v[108:111]
	v_mfma_f32_16x16x32_bf16 v[104:107], v[150:153], v[190:193], v[104:107]
	v_mfma_f32_16x16x32_bf16 v[92:95], v[134:137], v[198:201], v[92:95]
	v_mfma_f32_16x16x32_bf16 v[88:91], v[150:153], v[198:201], v[88:91]
	v_mfma_f32_16x16x32_bf16 v[76:79], v[134:137], v[216:219], v[76:79]
	v_mfma_f32_16x16x32_bf16 v[72:75], v[150:153], v[216:219], v[72:75]
	v_mfma_f32_16x16x32_bf16 v[124:127], v[146:149], v[186:189], v[124:127]
	v_mfma_f32_16x16x32_bf16 v[120:123], v[154:157], v[186:189], v[120:123]
	v_mfma_f32_16x16x32_bf16 v[108:111], v[146:149], v[194:197], v[108:111]
	v_mfma_f32_16x16x32_bf16 v[104:107], v[154:157], v[194:197], v[104:107]
	v_mfma_f32_16x16x32_bf16 v[92:95], v[146:149], v[212:215], v[92:95]
	v_mfma_f32_16x16x32_bf16 v[88:91], v[154:157], v[212:215], v[88:91]
	v_mfma_f32_16x16x32_bf16 v[76:79], v[146:149], v[220:223], v[76:79]
	v_mfma_f32_16x16x32_bf16 v[72:75], v[154:157], v[220:223], v[72:75]
	s_setprio 0
	s_setprio 1
	v_mfma_f32_16x16x32_bf16 v[116:119], v[158:161], v[182:185], v[116:119]
	v_mfma_f32_16x16x32_bf16 v[112:115], v[166:169], v[182:185], v[112:115]
	v_mfma_f32_16x16x32_bf16 v[100:103], v[158:161], v[190:193], v[100:103]
	v_mfma_f32_16x16x32_bf16 v[96:99], v[166:169], v[190:193], v[96:99]
	v_mfma_f32_16x16x32_bf16 v[84:87], v[158:161], v[198:201], v[84:87]
	v_mfma_f32_16x16x32_bf16 v[80:83], v[166:169], v[198:201], v[80:83]
	v_mfma_f32_16x16x32_bf16 v[68:71], v[158:161], v[216:219], v[68:71]
	v_mfma_f32_16x16x32_bf16 v[64:67], v[166:169], v[216:219], v[64:67]
	v_mfma_f32_16x16x32_bf16 v[116:119], v[162:165], v[186:189], v[116:119]
	v_mfma_f32_16x16x32_bf16 v[112:115], v[178:181], v[186:189], v[112:115]
	v_mfma_f32_16x16x32_bf16 v[100:103], v[162:165], v[194:197], v[100:103]
	v_mfma_f32_16x16x32_bf16 v[96:99], v[178:181], v[194:197], v[96:99]
	v_mfma_f32_16x16x32_bf16 v[84:87], v[162:165], v[212:215], v[84:87]
	v_mfma_f32_16x16x32_bf16 v[80:83], v[178:181], v[212:215], v[80:83]
	v_mfma_f32_16x16x32_bf16 v[68:71], v[162:165], v[220:223], v[68:71]
	v_mfma_f32_16x16x32_bf16 v[64:67], v[178:181], v[220:223], v[64:67]
	s_barrier
	s_setprio 0
	s_add_i32 s65, s68, s56
	v_lshl_add_u64 v[138:139], s[42:43], 0, v[172:173]
	s_mov_b32 m0, s65
	s_nop 0
	global_load_lds_dwordx4 v[138:139], off
	ds_read_b128 v[182:185], v144 offset:16384
	ds_read_b128 v[186:189], v144 offset:17408
	ds_read_b128 v[190:193], v144 offset:18432
	ds_read_b128 v[194:197], v144 offset:19456
	s_add_i32 m0, s65, 0x2000
	s_add_u32 s66, s42, 0x200000
	v_lshl_add_u64 v[138:139], s[42:43], 0, v[132:133]
	s_addc_u32 s67, s43, 0
	s_add_i32 s65, s69, s56
	global_load_lds_dwordx4 v[138:139], off
	ds_read_b128 v[198:201], v144 offset:20480
	ds_read_b128 v[212:215], v144 offset:21504
	ds_read_b128 v[216:219], v144 offset:22528
	ds_read_b128 v[220:223], v144 offset:23552
	v_lshl_add_u64 v[138:139], s[66:67], 0, v[172:173]
	s_mov_b32 m0, s65
	s_nop 0
	global_load_lds_dwordx4 v[138:139], off
	v_lshl_add_u64 v[138:139], s[66:67], 0, v[132:133]
	s_add_i32 m0, s65, 0x2000
	s_nop 0
	global_load_lds_dwordx4 v[138:139], off
	v_lshl_add_u64 v[138:139], s[46:47], 0, v[128:129]
	s_mov_b32 m0, s27
	s_nop 0
	global_load_lds_dwordx4 v[138:139], off
	v_lshl_add_u64 v[138:139], s[46:47], 0, v[130:131]
	s_mov_b32 m0, s57
	s_nop 0
	global_load_lds_dwordx4 v[138:139], off
	s_waitcnt vmcnt(8)
	s_waitcnt lgkmcnt(0)
	s_setprio 1
	s_barrier
; #define PG8_STAGE(bufoff, gbase, voff) do { _Pragma("unroll") for (int _i = 0; _i < 2; ++_i) \
;         __builtin_amdgcn_global_load_lds((const unsigned*)((const char*)(gbase) + (voff)[_i]), (PG8_LAS unsigned*)(lds + (bufoff) + ldsw + _i * 8192), 16, 0, 0); } while (0)
; #define PG8_LDA(dst, b, h) do { _Pragma("unroll") for (int m = 0; m < 4; ++m) _Pragma("unroll") for (int k = 0; k < 2; ++k) dst[m][k] = *(const PG8_LAS bf16x8*)(lds + PG8_SA(b, h) + aoff + m * 2048 + k * 1024); } while (0)
; #define PG8_LDB(dst, b, h) do { _Pragma("unroll") for (int n = 0; n < 2; ++n) _Pragma("unroll") for (int k = 0; k < 2; ++k) dst[n][k] = *(const PG8_LAS bf16x8*)(lds + PG8_SB(b, h) + boff + n * 2048 + k * 1024); } while (0)
; #define PG8_MMA(ai, bj, At, Bt) do { __builtin_amdgcn_s_setprio(1); _Pragma("unroll") for (int m = 0; m < 4; ++m) _Pragma("unroll") for (int n = 0; n < 2; ++n) _Pragma("unroll") for (int k = 0; k < 2; ++k) \
;         acc[ai][bj][m][n] = __builtin_amdgcn_mfma_f32_16x16x32_bf16(Bt[n][k], At[m][k], acc[ai][bj][m][n], 0, 0, 0); __builtin_amdgcn_s_setprio(0); } while (0)
; #define PG8_WAIT_V(n) asm volatile("s_waitcnt vmcnt(" #n ")" ::: "memory")
; #define PG8_WAIT_L(n) asm volatile("s_waitcnt lgkmcnt(" #n ")" ::: "memory")
; #define PG8_BAR __builtin_amdgcn_s_barrier()
; #define PG8_SCHED __builtin_amdgcn_sched_barrier(0)
; template <class Epi, class Sched, bool ALIGN_EPI = false, bool SP2 = false>
; __device__ __forceinline__ void gemm_phase(PG8_LAS unsigned char* lds, const Gemm g, const Sched& S, const Epi& E) {
;     ...
;             PG8_WAIT_V(8); PG8_WAIT_L(0); PG8_BAR; PG8_MMA(1, 0, At, B0); PG8_MMA(1, 1, At, B1); PG8_BAR; PG8_SCHED;
;             PG8_LDB(B0, 1, 0); PG8_LDB(B1, 1, 1); PG8_SCHED; PG8_LDA(At, 1, 0); PG8_STAGE(PG8_SA(0, 1), a2 + hstep, voffA);
;             PG8_WAIT_V(8); PG8_WAIT_L(0); PG8_BAR; PG8_MMA(0, 0, At, B0); PG8_MMA(0, 1, At, B1); PG8_BAR; PG8_SCHED;
	v_mfma_f32_16x16x32_bf16 v[60:63], v[134:137], v[182:185], v[60:63]
	v_mfma_f32_16x16x32_bf16 v[56:59], v[150:153], v[182:185], v[56:59]
	v_mfma_f32_16x16x32_bf16 v[44:47], v[134:137], v[190:193], v[44:47]
	v_mfma_f32_16x16x32_bf16 v[40:43], v[150:153], v[190:193], v[40:43]
	v_mfma_f32_16x16x32_bf16 v[28:31], v[134:137], v[198:201], v[28:31]
	v_mfma_f32_16x16x32_bf16 v[24:27], v[150:153], v[198:201], v[24:27]
	v_mfma_f32_16x16x32_bf16 v[12:15], v[134:137], v[216:219], v[12:15]
	v_mfma_f32_16x16x32_bf16 v[8:11], v[150:153], v[216:219], v[8:11]
	v_mfma_f32_16x16x32_bf16 v[60:63], v[146:149], v[186:189], v[60:63]
	v_mfma_f32_16x16x32_bf16 v[56:59], v[154:157], v[186:189], v[56:59]
	v_mfma_f32_16x16x32_bf16 v[44:47], v[146:149], v[194:197], v[44:47]
	v_mfma_f32_16x16x32_bf16 v[40:43], v[154:157], v[194:197], v[40:43]
	v_mfma_f32_16x16x32_bf16 v[28:31], v[146:149], v[212:215], v[28:31]
	v_mfma_f32_16x16x32_bf16 v[24:27], v[154:157], v[212:215], v[24:27]
	v_mfma_f32_16x16x32_bf16 v[12:15], v[146:149], v[220:223], v[12:15]
	v_mfma_f32_16x16x32_bf16 v[8:11], v[154:157], v[220:223], v[8:11]
	s_setprio 0
	s_setprio 1
	v_mfma_f32_16x16x32_bf16 v[52:55], v[158:161], v[182:185], v[52:55]
	v_mfma_f32_16x16x32_bf16 v[48:51], v[166:169], v[182:185], v[48:51]
	v_mfma_f32_16x16x32_bf16 v[36:39], v[158:161], v[190:193], v[36:39]
	v_mfma_f32_16x16x32_bf16 v[32:35], v[166:169], v[190:193], v[32:35]
	v_mfma_f32_16x16x32_bf16 v[20:23], v[158:161], v[198:201], v[20:23]
	v_mfma_f32_16x16x32_bf16 v[16:19], v[166:169], v[198:201], v[16:19]
	v_mfma_f32_16x16x32_bf16 v[4:7], v[158:161], v[216:219], v[4:7]
	v_mfma_f32_16x16x32_bf16 v[0:3], v[166:169], v[216:219], v[0:3]
	v_mfma_f32_16x16x32_bf16 v[52:55], v[162:165], v[186:189], v[52:55]
	v_mfma_f32_16x16x32_bf16 v[48:51], v[178:181], v[186:189], v[48:51]
	v_mfma_f32_16x16x32_bf16 v[36:39], v[162:165], v[194:197], v[36:39]
	v_mfma_f32_16x16x32_bf16 v[32:35], v[178:181], v[194:197], v[32:35]
	v_mfma_f32_16x16x32_bf16 v[20:23], v[162:165], v[212:215], v[20:23]
	v_mfma_f32_16x16x32_bf16 v[16:19], v[178:181], v[212:215], v[16:19]
	v_mfma_f32_16x16x32_bf16 v[4:7], v[162:165], v[220:223], v[4:7]
	v_mfma_f32_16x16x32_bf16 v[0:3], v[178:181], v[220:223], v[0:3]
	s_barrier
	s_setprio 0
	s_add_i32 s65, 0, 0x18000
	v_add_u32_e32 v138, s65, v142
	s_add_i32 s66, 0, 0x1c000
	ds_read_b128 v[134:137], v138
	ds_read_b128 v[146:149], v138 offset:1024
	ds_read_b128 v[150:153], v138 offset:2048
	ds_read_b128 v[154:157], v138 offset:3072
	v_add_u32_e32 v138, s66, v142
	ds_read_b128 v[158:161], v138
	ds_read_b128 v[162:165], v138 offset:1024
	ds_read_b128 v[166:169], v138 offset:2048
	ds_read_b128 v[178:181], v138 offset:3072
	s_add_u32 s46, s46, 0x200000
	s_addc_u32 s47, s47, 0
	s_mov_b32 m0, s58
	v_lshl_add_u64 v[138:139], s[46:47], 0, v[128:129]
	ds_read_b128 v[182:185], v144 offset:32768
	ds_read_b128 v[186:189], v144 offset:33792
	ds_read_b128 v[190:193], v144 offset:34816
	ds_read_b128 v[194:197], v144 offset:35840
	ds_read_b128 v[198:201], v144 offset:36864
	ds_read_b128 v[212:215], v144 offset:37888
	ds_read_b128 v[216:219], v144 offset:38912
	ds_read_b128 v[220:223], v144 offset:39936
	global_load_lds_dwordx4 v[138:139], off
	v_lshl_add_u64 v[138:139], s[46:47], 0, v[130:131]
	s_mov_b32 m0, s59
	s_nop 0
	global_load_lds_dwordx4 v[138:139], off
	s_waitcnt vmcnt(8)
	s_waitcnt lgkmcnt(0)
	s_setprio 1
	s_barrier
	v_mfma_f32_16x16x32_bf16 v[124:127], v[134:137], v[182:185], v[124:127]
	v_mfma_f32_16x16x32_bf16 v[120:123], v[150:153], v[182:185], v[120:123]
	v_mfma_f32_16x16x32_bf16 v[108:111], v[134:137], v[190:193], v[108:111]
	v_mfma_f32_16x16x32_bf16 v[104:107], v[150:153], v[190:193], v[104:107]
	v_mfma_f32_16x16x32_bf16 v[92:95], v[134:137], v[198:201], v[92:95]
	v_mfma_f32_16x16x32_bf16 v[88:91], v[150:153], v[198:201], v[88:91]
	v_mfma_f32_16x16x32_bf16 v[76:79], v[134:137], v[216:219], v[76:79]
	v_mfma_f32_16x16x32_bf16 v[72:75], v[150:153], v[216:219], v[72:75]
	v_mfma_f32_16x16x32_bf16 v[124:127], v[146:149], v[186:189], v[124:127]
	v_mfma_f32_16x16x32_bf16 v[120:123], v[154:157], v[186:189], v[120:123]
	v_mfma_f32_16x16x32_bf16 v[108:111], v[146:149], v[194:197], v[108:111]
	v_mfma_f32_16x16x32_bf16 v[104:107], v[154:157], v[194:197], v[104:107]
	v_mfma_f32_16x16x32_bf16 v[92:95], v[146:149], v[212:215], v[92:95]
	v_mfma_f32_16x16x32_bf16 v[88:91], v[154:157], v[212:215], v[88:91]
	v_mfma_f32_16x16x32_bf16 v[76:79], v[146:149], v[220:223], v[76:79]
	v_mfma_f32_16x16x32_bf16 v[72:75], v[154:157], v[220:223], v[72:75]
	s_setprio 0
	s_setprio 1
	v_mfma_f32_16x16x32_bf16 v[116:119], v[158:161], v[182:185], v[116:119]
	v_mfma_f32_16x16x32_bf16 v[112:115], v[166:169], v[182:185], v[112:115]
	v_mfma_f32_16x16x32_bf16 v[100:103], v[158:161], v[190:193], v[100:103]
	v_mfma_f32_16x16x32_bf16 v[96:99], v[166:169], v[190:193], v[96:99]
	v_mfma_f32_16x16x32_bf16 v[84:87], v[158:161], v[198:201], v[84:87]
	v_mfma_f32_16x16x32_bf16 v[80:83], v[166:169], v[198:201], v[80:83]
	v_mfma_f32_16x16x32_bf16 v[68:71], v[158:161], v[216:219], v[68:71]
	v_mfma_f32_16x16x32_bf16 v[64:67], v[166:169], v[216:219], v[64:67]
	v_mfma_f32_16x16x32_bf16 v[116:119], v[162:165], v[186:189], v[116:119]
	v_mfma_f32_16x16x32_bf16 v[112:115], v[178:181], v[186:189], v[112:115]
	v_mfma_f32_16x16x32_bf16 v[100:103], v[162:165], v[194:197], v[100:103]
	v_mfma_f32_16x16x32_bf16 v[96:99], v[178:181], v[194:197], v[96:99]
	v_mfma_f32_16x16x32_bf16 v[84:87], v[162:165], v[212:215], v[84:87]
	v_mfma_f32_16x16x32_bf16 v[80:83], v[178:181], v[212:215], v[80:83]
	v_mfma_f32_16x16x32_bf16 v[68:71], v[162:165], v[220:223], v[68:71]
	v_mfma_f32_16x16x32_bf16 v[64:67], v[178:181], v[220:223], v[64:67]
	s_barrier
; #define PG8_STAGE(bufoff, gbase, voff) do { _Pragma("unroll") for (int _i = 0; _i < 2; ++_i) \
;         __builtin_amdgcn_global_load_lds((const unsigned*)((const char*)(gbase) + (voff)[_i]), (PG8_LAS unsigned*)(lds + (bufoff) + ldsw + _i * 8192), 16, 0, 0); } while (0)
; #define PG8_LDA(dst, b, h) do { _Pragma("unroll") for (int m = 0; m < 4; ++m) _Pragma("unroll") for (int k = 0; k < 2; ++k) dst[m][k] = *(const PG8_LAS bf16x8*)(lds + PG8_SA(b, h) + aoff + m * 2048 + k * 1024); } while (0)
; #define PG8_MMA(ai, bj, At, Bt) do { __builtin_amdgcn_s_setprio(1); _Pragma("unroll") for (int m = 0; m < 4; ++m) _Pragma("unroll") for (int n = 0; n < 2; ++n) _Pragma("unroll") for (int k = 0; k < 2; ++k) \
;         acc[ai][bj][m][n] = __builtin_amdgcn_mfma_f32_16x16x32_bf16(Bt[n][k], At[m][k], acc[ai][bj][m][n], 0, 0, 0); __builtin_amdgcn_s_setprio(0); } while (0)
; #define PG8_WAIT_V(n) asm volatile("s_waitcnt vmcnt(" #n ")" ::: "memory")
; #define PG8_WAIT_L(n) asm volatile("s_waitcnt lgkmcnt(" #n ")" ::: "memory")
; #define PG8_BAR __builtin_amdgcn_s_barrier()
; #define PG8_SCHED __builtin_amdgcn_sched_barrier(0)
; template <class Epi, class Sched, bool ALIGN_EPI = false, bool SP2 = false>
; __device__ __forceinline__ void gemm_phase(PG8_LAS unsigned char* lds, const Gemm g, const Sched& S, const Epi& E) {
;     ...
;             PG8_LDA(At, 1, 1); PG8_STAGE(PG8_SB(1, 0), b3, voffB); PG8_STAGE(PG8_SB(1, 1), b3 + hstep, voffB); PG8_STAGE(PG8_SA(1, 0), a3, voffA);
;             PG8_WAIT_V(8); PG8_WAIT_L(0); PG8_BAR; PG8_MMA(1, 0, At, B0); PG8_MMA(1, 1, At, B1); PG8_BAR; PG8_SCHED;
	s_setprio 0
	s_add_u32 s42, s42, s44
	s_addc_u32 s43, s43, s45
	s_add_i32 s44, s65, s56
	v_lshl_add_u64 v[138:139], s[42:43], 0, v[172:173]
	s_mov_b32 m0, s44
	s_nop 0
	global_load_lds_dwordx4 v[138:139], off
	ds_read_b128 v[182:185], v144 offset:49152
	ds_read_b128 v[186:189], v144 offset:50176
	ds_read_b128 v[190:193], v144 offset:51200
	ds_read_b128 v[194:197], v144 offset:52224
	s_add_i32 m0, s44, 0x2000
	v_lshl_add_u64 v[138:139], s[42:43], 0, v[132:133]
	s_add_u32 s42, s42, 0x200000
	s_addc_u32 s43, s43, 0
	s_add_i32 s44, s66, s56
	global_load_lds_dwordx4 v[138:139], off
	ds_read_b128 v[198:201], v144 offset:53248
	ds_read_b128 v[212:215], v144 offset:54272
	ds_read_b128 v[216:219], v144 offset:55296
	ds_read_b128 v[220:223], v144 offset:56320
	v_lshl_add_u64 v[138:139], s[42:43], 0, v[172:173]
	s_mov_b32 m0, s44
	s_nop 0
	global_load_lds_dwordx4 v[138:139], off
	v_lshl_add_u64 v[138:139], s[42:43], 0, v[132:133]
	s_add_i32 m0, s44, 0x2000
	s_nop 0
	global_load_lds_dwordx4 v[138:139], off
	v_lshl_add_u64 v[138:139], s[48:49], 0, v[128:129]
	s_mov_b32 m0, s61
	s_nop 0
	global_load_lds_dwordx4 v[138:139], off
	v_lshl_add_u64 v[138:139], s[48:49], 0, v[130:131]
	s_mov_b32 m0, s62
	s_nop 0
	global_load_lds_dwordx4 v[138:139], off
	s_waitcnt vmcnt(8)
	s_waitcnt lgkmcnt(0)
	s_setprio 1
	s_barrier
	v_mfma_f32_16x16x32_bf16 v[60:63], v[134:137], v[182:185], v[60:63]
	v_mfma_f32_16x16x32_bf16 v[56:59], v[150:153], v[182:185], v[56:59]
	v_mfma_f32_16x16x32_bf16 v[44:47], v[134:137], v[190:193], v[44:47]
	v_mfma_f32_16x16x32_bf16 v[40:43], v[150:153], v[190:193], v[40:43]
	v_mfma_f32_16x16x32_bf16 v[28:31], v[134:137], v[198:201], v[28:31]
	v_mfma_f32_16x16x32_bf16 v[24:27], v[150:153], v[198:201], v[24:27]
	v_mfma_f32_16x16x32_bf16 v[12:15], v[134:137], v[216:219], v[12:15]
	v_mfma_f32_16x16x32_bf16 v[8:11], v[150:153], v[216:219], v[8:11]
	v_mfma_f32_16x16x32_bf16 v[60:63], v[146:149], v[186:189], v[60:63]
	v_mfma_f32_16x16x32_bf16 v[56:59], v[154:157], v[186:189], v[56:59]
	v_mfma_f32_16x16x32_bf16 v[44:47], v[146:149], v[194:197], v[44:47]
	v_mfma_f32_16x16x32_bf16 v[40:43], v[154:157], v[194:197], v[40:43]
	v_mfma_f32_16x16x32_bf16 v[28:31], v[146:149], v[212:215], v[28:31]
	v_mfma_f32_16x16x32_bf16 v[24:27], v[154:157], v[212:215], v[24:27]
	v_mfma_f32_16x16x32_bf16 v[12:15], v[146:149], v[220:223], v[12:15]
	v_mfma_f32_16x16x32_bf16 v[8:11], v[154:157], v[220:223], v[8:11]
	s_setprio 0
	s_setprio 1
	v_mfma_f32_16x16x32_bf16 v[52:55], v[158:161], v[182:185], v[52:55]
	v_mfma_f32_16x16x32_bf16 v[48:51], v[166:169], v[182:185], v[48:51]
	v_mfma_f32_16x16x32_bf16 v[36:39], v[158:161], v[190:193], v[36:39]
	v_mfma_f32_16x16x32_bf16 v[32:35], v[166:169], v[190:193], v[32:35]
	v_mfma_f32_16x16x32_bf16 v[20:23], v[158:161], v[198:201], v[20:23]
	v_mfma_f32_16x16x32_bf16 v[16:19], v[166:169], v[198:201], v[16:19]
	v_mfma_f32_16x16x32_bf16 v[4:7], v[158:161], v[216:219], v[4:7]
	v_mfma_f32_16x16x32_bf16 v[0:3], v[166:169], v[216:219], v[0:3]
	v_mfma_f32_16x16x32_bf16 v[52:55], v[162:165], v[186:189], v[52:55]
	v_mfma_f32_16x16x32_bf16 v[48:51], v[178:181], v[186:189], v[48:51]
	v_mfma_f32_16x16x32_bf16 v[36:39], v[162:165], v[194:197], v[36:39]
	v_mfma_f32_16x16x32_bf16 v[32:35], v[178:181], v[194:197], v[32:35]
	v_mfma_f32_16x16x32_bf16 v[20:23], v[162:165], v[212:215], v[20:23]
	v_mfma_f32_16x16x32_bf16 v[16:19], v[178:181], v[212:215], v[16:19]
	v_mfma_f32_16x16x32_bf16 v[4:7], v[162:165], v[220:223], v[4:7]
	v_mfma_f32_16x16x32_bf16 v[0:3], v[178:181], v[220:223], v[0:3]
	s_barrier
	s_setprio 0
	s_cmpk_gt_u32 s25, 0x7d
	s_mov_b32 s25, s64
	s_cbranch_scc1 .LBB0_796
